# conservative vmcnt waits (no load-store order reliance); XB and mem_attn epilogue stores widened to dwordx4 via permlane16_swap
# speedup vs baseline: 1.0065x; 1.0065x over previous
; #define LAS __attribute__((address_space(3)))
; #define MFMA16(a, b, c) __builtin_amdgcn_mfma_f32_16x16x32_bf16((a), (b), (c), 0, 0, 0)
; __device__ __forceinline__ void mem_attn(const Params& P, int l, LAS unsigned char* lds, int item, int tid) {
;     ...
;     for (int trip = 0; trip < 2; ++trip) {
;         const int q0 = (qblk2 + trip) * 256 + w * 32; const size_t tt0 = (size_t)(b * SEQ + q0 + i), tt1 = tt0 + 16;
;         bf16x8 qf0[4], qf1[4];
; #pragma unroll
;         for (int ks = 0; ks < 4; ++ks) { qf0[ks] = *(const bf16x8*)(z + tt0 * ZP + ZC_MQ + h * 128 + ks * 32 + quad * 8); qf1[ks] = *(const bf16x8*)(z + tt1 * ZP + ZC_MQ + h * 128 + ks * 32 + quad * 8); }
;         f32x4 sa[16], sb[16];
; #pragma unroll
;         for (int kt = 0; kt < 16; ++kt) { sa[kt] = (f32x4){0.f, 0.f, 0.f, 0.f}; sb[kt] = (f32x4){0.f, 0.f, 0.f, 0.f};
; #pragma unroll
;             for (int ks = 0; ks < 4; ++ks) { const bf16x8 ka = *(const LAS bf16x8*)(KS + (kt * 16 + i) * 272 + (ks * 32 + quad * 8) * 2); sa[kt] = MFMA16(ka, qf0[ks], sa[kt]); sb[kt] = MFMA16(ka, qf1[ks], sb[kt]); }
.LBB0_415:
	v_add_u32_e32 v174, s7, v191
	v_mov_b64_e32 v[2:3], s[92:93]
	v_mad_i64_i32 v[2:3], s[8:9], v174, s80, v[2:3]
	v_lshl_add_u64 v[176:177], v[2:3], 0, s[76:77]
	v_lshl_add_u64 v[2:3], v[176:177], 0, v[0:1]
	v_add_co_u32_e32 v8, vcc, 0x2000, v2
	s_mov_b64 s[8:9], 0x2800
	s_nop 0
	v_addc_co_u32_e32 v9, vcc, 0, v3, vcc
	global_load_dwordx4 v[164:167], v[8:9], off offset:2048
	v_lshl_add_u64 v[4:5], v[2:3], 0, s[8:9]
	s_mov_b64 s[8:9], 0x62800
	v_lshl_add_u64 v[6:7], v[2:3], 0, s[8:9]
	v_add_co_u32_e32 v2, vcc, 0x62000, v2
	v_ashrrev_i32_e32 v175, 31, v174
	s_nop 0
	v_addc_co_u32_e32 v3, vcc, 0, v3, vcc
	global_load_dwordx4 v[168:171], v[2:3], off offset:2048
	global_load_dwordx4 v[156:159], v[4:5], off offset:64
	global_load_dwordx4 v[160:163], v[6:7], off offset:64
	global_load_dwordx4 v[78:81], v[4:5], off offset:128
	global_load_dwordx4 v[152:155], v[6:7], off offset:128
	global_load_dwordx4 v[74:77], v[4:5], off offset:192
	global_load_dwordx4 v[148:151], v[6:7], off offset:192
	ds_read_b128 v[2:5], v181
	ds_read_b128 v[10:13], v181 offset:64
	s_waitcnt vmcnt(7) lgkmcnt(1)
	v_mfma_f32_16x16x32_bf16 v[6:9], v[2:5], v[164:167], 0
	ds_read_b128 v[18:21], v181 offset:4416
	s_waitcnt vmcnt(6)
	v_mfma_f32_16x16x32_bf16 v[2:5], v[2:5], v[168:171], 0
	s_waitcnt vmcnt(5) lgkmcnt(1)
	v_mfma_f32_16x16x32_bf16 v[6:9], v[10:13], v[156:159], v[6:9]
	s_waitcnt vmcnt(4)
	v_mfma_f32_16x16x32_bf16 v[2:5], v[10:13], v[160:163], v[2:5]
	ds_read_b128 v[10:13], v181 offset:128
	s_waitcnt vmcnt(3) lgkmcnt(0)
	v_mfma_f32_16x16x32_bf16 v[6:9], v[10:13], v[78:81], v[6:9]
	s_waitcnt vmcnt(2)
	v_mfma_f32_16x16x32_bf16 v[2:5], v[10:13], v[152:155], v[2:5]
	ds_read_b128 v[10:13], v181 offset:192
	s_waitcnt vmcnt(1) lgkmcnt(0)
	v_mfma_f32_16x16x32_bf16 v[6:9], v[10:13], v[74:77], v[6:9]
	s_waitcnt vmcnt(0)
	v_mfma_f32_16x16x32_bf16 v[2:5], v[10:13], v[148:151], v[2:5]
	ds_read_b128 v[10:13], v181 offset:4352
	s_waitcnt lgkmcnt(0)
	v_mfma_f32_16x16x32_bf16 v[14:17], v[10:13], v[164:167], 0
	v_mfma_f32_16x16x32_bf16 v[10:13], v[10:13], v[168:171], 0
	v_mfma_f32_16x16x32_bf16 v[14:17], v[18:21], v[156:159], v[14:17]
	v_mfma_f32_16x16x32_bf16 v[10:13], v[18:21], v[160:163], v[10:13]
	ds_read_b128 v[18:21], v181 offset:4480
	s_waitcnt lgkmcnt(0)
	v_mfma_f32_16x16x32_bf16 v[14:17], v[18:21], v[78:81], v[14:17]
	v_mfma_f32_16x16x32_bf16 v[10:13], v[18:21], v[152:155], v[10:13]
	ds_read_b128 v[18:21], v181 offset:4544
	s_waitcnt lgkmcnt(0)
	v_mfma_f32_16x16x32_bf16 v[58:61], v[18:21], v[74:77], v[14:17]
	v_mfma_f32_16x16x32_bf16 v[62:65], v[18:21], v[148:151], v[10:13]
	s_nop 3
	ds_read_b128 v[10:13], v181 offset:8704
	ds_read_b128 v[18:21], v181 offset:8768
	s_waitcnt lgkmcnt(1)
	v_mfma_f32_16x16x32_bf16 v[14:17], v[10:13], v[164:167], 0
	v_mfma_f32_16x16x32_bf16 v[10:13], v[10:13], v[168:171], 0
	s_waitcnt lgkmcnt(0)
	v_mfma_f32_16x16x32_bf16 v[14:17], v[18:21], v[156:159], v[14:17]
	v_mfma_f32_16x16x32_bf16 v[10:13], v[18:21], v[160:163], v[10:13]
	ds_read_b128 v[18:21], v181 offset:8832
	s_waitcnt lgkmcnt(0)
	v_mfma_f32_16x16x32_bf16 v[14:17], v[18:21], v[78:81], v[14:17]
	v_mfma_f32_16x16x32_bf16 v[10:13], v[18:21], v[152:155], v[10:13]
	ds_read_b128 v[18:21], v181 offset:8896
	s_waitcnt lgkmcnt(0)
	v_mfma_f32_16x16x32_bf16 v[50:53], v[18:21], v[148:151], v[10:13]
	s_nop 4
	ds_read_b128 v[10:13], v181 offset:13056
	v_mfma_f32_16x16x32_bf16 v[54:57], v[18:21], v[74:77], v[14:17]
	ds_read_b128 v[18:21], v181 offset:13120
	s_waitcnt lgkmcnt(1)
	v_mfma_f32_16x16x32_bf16 v[14:17], v[10:13], v[164:167], 0
	v_mfma_f32_16x16x32_bf16 v[10:13], v[10:13], v[168:171], 0
	s_waitcnt lgkmcnt(0)
	v_mfma_f32_16x16x32_bf16 v[14:17], v[18:21], v[156:159], v[14:17]
	v_mfma_f32_16x16x32_bf16 v[10:13], v[18:21], v[160:163], v[10:13]
	ds_read_b128 v[18:21], v181 offset:13184
	s_waitcnt lgkmcnt(0)
	v_mfma_f32_16x16x32_bf16 v[14:17], v[18:21], v[78:81], v[14:17]
	v_mfma_f32_16x16x32_bf16 v[10:13], v[18:21], v[152:155], v[10:13]
	ds_read_b128 v[18:21], v181 offset:13248
	s_waitcnt lgkmcnt(0)
	v_mfma_f32_16x16x32_bf16 v[144:147], v[18:21], v[74:77], v[14:17]
	v_mfma_f32_16x16x32_bf16 v[122:125], v[18:21], v[148:151], v[10:13]
	s_nop 3
	ds_read_b128 v[10:13], v181 offset:17408
	ds_read_b128 v[18:21], v181 offset:17472
	s_waitcnt lgkmcnt(1)
	v_mfma_f32_16x16x32_bf16 v[14:17], v[10:13], v[164:167], 0
	v_mfma_f32_16x16x32_bf16 v[10:13], v[10:13], v[168:171], 0
	s_waitcnt lgkmcnt(0)
	v_mfma_f32_16x16x32_bf16 v[14:17], v[18:21], v[156:159], v[14:17]
	v_mfma_f32_16x16x32_bf16 v[10:13], v[18:21], v[160:163], v[10:13]
	ds_read_b128 v[18:21], v181 offset:17536
	s_waitcnt lgkmcnt(0)
	v_mfma_f32_16x16x32_bf16 v[14:17], v[18:21], v[78:81], v[14:17]
	v_mfma_f32_16x16x32_bf16 v[10:13], v[18:21], v[152:155], v[10:13]
	ds_read_b128 v[18:21], v181 offset:17600
	s_waitcnt lgkmcnt(0)
	v_mfma_f32_16x16x32_bf16 v[42:45], v[18:21], v[148:151], v[10:13]
	s_nop 4
	ds_read_b128 v[10:13], v181 offset:21760
	v_mfma_f32_16x16x32_bf16 v[46:49], v[18:21], v[74:77], v[14:17]
	ds_read_b128 v[18:21], v181 offset:21824
	s_waitcnt lgkmcnt(1)
	v_mfma_f32_16x16x32_bf16 v[14:17], v[10:13], v[164:167], 0
	v_mfma_f32_16x16x32_bf16 v[10:13], v[10:13], v[168:171], 0
	s_waitcnt lgkmcnt(0)
	v_mfma_f32_16x16x32_bf16 v[14:17], v[18:21], v[156:159], v[14:17]
	v_mfma_f32_16x16x32_bf16 v[10:13], v[18:21], v[160:163], v[10:13]
	ds_read_b128 v[18:21], v181 offset:21888
	s_waitcnt lgkmcnt(0)
	v_mfma_f32_16x16x32_bf16 v[14:17], v[18:21], v[78:81], v[14:17]
	v_mfma_f32_16x16x32_bf16 v[10:13], v[18:21], v[152:155], v[10:13]
	ds_read_b128 v[18:21], v181 offset:21952
	s_waitcnt lgkmcnt(0)
; #define LAS __attribute__((address_space(3)))
; #define MFMA16(a, b, c) __builtin_amdgcn_mfma_f32_16x16x32_bf16((a), (b), (c), 0, 0, 0)
; __device__ __forceinline__ void mem_attn(const Params& P, int l, LAS unsigned char* lds, int item, int tid) {
;     ...
;         for (int kt = 0; kt < 16; ++kt) { sa[kt] = (f32x4){0.f, 0.f, 0.f, 0.f}; sb[kt] = (f32x4){0.f, 0.f, 0.f, 0.f};
; #pragma unroll
;             for (int ks = 0; ks < 4; ++ks) { const bf16x8 ka = *(const LAS bf16x8*)(KS + (kt * 16 + i) * 272 + (ks * 32 + quad * 8) * 2); sa[kt] = MFMA16(ka, qf0[ks], sa[kt]); sb[kt] = MFMA16(ka, qf1[ks], sb[kt]); }
;             if (kt & 1) __builtin_amdgcn_sched_barrier(0); }
	v_mfma_f32_16x16x32_bf16 v[118:121], v[18:21], v[74:77], v[14:17]
	v_mfma_f32_16x16x32_bf16 v[114:117], v[18:21], v[148:151], v[10:13]
	s_nop 3
	ds_read_b128 v[10:13], v181 offset:26112
	ds_read_b128 v[18:21], v181 offset:26176
	s_waitcnt lgkmcnt(1)
	v_mfma_f32_16x16x32_bf16 v[14:17], v[10:13], v[164:167], 0
	v_mfma_f32_16x16x32_bf16 v[10:13], v[10:13], v[168:171], 0
	s_waitcnt lgkmcnt(0)
	v_mfma_f32_16x16x32_bf16 v[14:17], v[18:21], v[156:159], v[14:17]
	v_mfma_f32_16x16x32_bf16 v[10:13], v[18:21], v[160:163], v[10:13]
	ds_read_b128 v[18:21], v181 offset:26240
	s_waitcnt lgkmcnt(0)
	v_mfma_f32_16x16x32_bf16 v[14:17], v[18:21], v[78:81], v[14:17]
	v_mfma_f32_16x16x32_bf16 v[10:13], v[18:21], v[152:155], v[10:13]
	ds_read_b128 v[18:21], v181 offset:26304
	s_waitcnt lgkmcnt(0)
	v_mfma_f32_16x16x32_bf16 v[34:37], v[18:21], v[148:151], v[10:13]
	s_nop 4
	ds_read_b128 v[10:13], v181 offset:30464
	v_mfma_f32_16x16x32_bf16 v[38:41], v[18:21], v[74:77], v[14:17]
	ds_read_b128 v[18:21], v181 offset:30528
	s_waitcnt lgkmcnt(1)
	v_mfma_f32_16x16x32_bf16 v[14:17], v[10:13], v[164:167], 0
	v_mfma_f32_16x16x32_bf16 v[10:13], v[10:13], v[168:171], 0
	s_waitcnt lgkmcnt(0)
	v_mfma_f32_16x16x32_bf16 v[14:17], v[18:21], v[156:159], v[14:17]
	v_mfma_f32_16x16x32_bf16 v[10:13], v[18:21], v[160:163], v[10:13]
	ds_read_b128 v[18:21], v181 offset:30592
	s_waitcnt lgkmcnt(0)
	v_mfma_f32_16x16x32_bf16 v[14:17], v[18:21], v[78:81], v[14:17]
	v_mfma_f32_16x16x32_bf16 v[10:13], v[18:21], v[152:155], v[10:13]
	ds_read_b128 v[18:21], v181 offset:30656
	s_waitcnt lgkmcnt(0)
	v_mfma_f32_16x16x32_bf16 v[110:113], v[18:21], v[74:77], v[14:17]
	v_mfma_f32_16x16x32_bf16 v[106:109], v[18:21], v[148:151], v[10:13]
	s_nop 3
	ds_read_b128 v[10:13], v181 offset:34816
	ds_read_b128 v[18:21], v181 offset:34880
	s_waitcnt lgkmcnt(1)
	v_mfma_f32_16x16x32_bf16 v[14:17], v[10:13], v[164:167], 0
	v_mfma_f32_16x16x32_bf16 v[10:13], v[10:13], v[168:171], 0
	s_waitcnt lgkmcnt(0)
	v_mfma_f32_16x16x32_bf16 v[14:17], v[18:21], v[156:159], v[14:17]
	v_mfma_f32_16x16x32_bf16 v[10:13], v[18:21], v[160:163], v[10:13]
	ds_read_b128 v[18:21], v181 offset:34944
	s_waitcnt lgkmcnt(0)
	v_mfma_f32_16x16x32_bf16 v[14:17], v[18:21], v[78:81], v[14:17]
	v_mfma_f32_16x16x32_bf16 v[10:13], v[18:21], v[152:155], v[10:13]
	ds_read_b128 v[18:21], v181 offset:35008
	s_waitcnt lgkmcnt(0)
	v_mfma_f32_16x16x32_bf16 v[26:29], v[18:21], v[148:151], v[10:13]
	s_nop 4
	ds_read_b128 v[10:13], v181 offset:39168
	v_mfma_f32_16x16x32_bf16 v[30:33], v[18:21], v[74:77], v[14:17]
	ds_read_b128 v[18:21], v181 offset:39232
	s_waitcnt lgkmcnt(1)
	v_mfma_f32_16x16x32_bf16 v[14:17], v[10:13], v[164:167], 0
	v_mfma_f32_16x16x32_bf16 v[10:13], v[10:13], v[168:171], 0
	s_waitcnt lgkmcnt(0)
	v_mfma_f32_16x16x32_bf16 v[14:17], v[18:21], v[156:159], v[14:17]
	v_mfma_f32_16x16x32_bf16 v[10:13], v[18:21], v[160:163], v[10:13]
	ds_read_b128 v[18:21], v181 offset:39296
	s_waitcnt lgkmcnt(0)
	v_mfma_f32_16x16x32_bf16 v[14:17], v[18:21], v[78:81], v[14:17]
	v_mfma_f32_16x16x32_bf16 v[10:13], v[18:21], v[152:155], v[10:13]
	ds_read_b128 v[18:21], v181 offset:39360
	s_waitcnt lgkmcnt(0)
	v_mfma_f32_16x16x32_bf16 v[102:105], v[18:21], v[74:77], v[14:17]
	v_mfma_f32_16x16x32_bf16 v[98:101], v[18:21], v[148:151], v[10:13]
	s_nop 3
	ds_read_b128 v[10:13], v181 offset:43520
	ds_read_b128 v[18:21], v181 offset:43584
	s_waitcnt lgkmcnt(1)
	v_mfma_f32_16x16x32_bf16 v[14:17], v[10:13], v[164:167], 0
	ds_read_b128 v[66:69], v181 offset:47936
	v_mfma_f32_16x16x32_bf16 v[10:13], v[10:13], v[168:171], 0
	s_waitcnt lgkmcnt(1)
	v_mfma_f32_16x16x32_bf16 v[14:17], v[18:21], v[156:159], v[14:17]
	v_mfma_f32_16x16x32_bf16 v[10:13], v[18:21], v[160:163], v[10:13]
	ds_read_b128 v[18:21], v181 offset:43648
	s_waitcnt lgkmcnt(0)
	v_mfma_f32_16x16x32_bf16 v[14:17], v[18:21], v[78:81], v[14:17]
	v_mfma_f32_16x16x32_bf16 v[10:13], v[18:21], v[152:155], v[10:13]
	ds_read_b128 v[18:21], v181 offset:43712
	s_waitcnt lgkmcnt(0)
	v_mfma_f32_16x16x32_bf16 v[22:25], v[18:21], v[74:77], v[14:17]
	v_mfma_f32_16x16x32_bf16 v[18:21], v[18:21], v[148:151], v[10:13]
	s_nop 3
	ds_read_b128 v[10:13], v181 offset:47872
	s_waitcnt lgkmcnt(0)
	v_mfma_f32_16x16x32_bf16 v[14:17], v[10:13], v[164:167], 0
	v_mfma_f32_16x16x32_bf16 v[10:13], v[10:13], v[168:171], 0
	v_mfma_f32_16x16x32_bf16 v[14:17], v[66:69], v[156:159], v[14:17]
	v_mfma_f32_16x16x32_bf16 v[10:13], v[66:69], v[160:163], v[10:13]
	ds_read_b128 v[66:69], v181 offset:48000
	s_waitcnt lgkmcnt(0)
	v_mfma_f32_16x16x32_bf16 v[14:17], v[66:69], v[78:81], v[14:17]
	v_mfma_f32_16x16x32_bf16 v[10:13], v[66:69], v[152:155], v[10:13]
	ds_read_b128 v[66:69], v181 offset:48064
	s_waitcnt lgkmcnt(0)
	v_mfma_f32_16x16x32_bf16 v[94:97], v[66:69], v[74:77], v[14:17]
	v_mfma_f32_16x16x32_bf16 v[90:93], v[66:69], v[148:151], v[10:13]
	s_nop 3
	ds_read_b128 v[10:13], v181 offset:52224
	ds_read_b128 v[66:69], v181 offset:52288
	s_waitcnt lgkmcnt(1)
	v_mfma_f32_16x16x32_bf16 v[14:17], v[10:13], v[164:167], 0
	ds_read_b128 v[82:85], v181 offset:56640
	v_mfma_f32_16x16x32_bf16 v[10:13], v[10:13], v[168:171], 0
	s_waitcnt lgkmcnt(1)
	v_mfma_f32_16x16x32_bf16 v[14:17], v[66:69], v[156:159], v[14:17]
	v_mfma_f32_16x16x32_bf16 v[10:13], v[66:69], v[160:163], v[10:13]
	ds_read_b128 v[66:69], v181 offset:52352
	s_waitcnt lgkmcnt(0)
	v_mfma_f32_16x16x32_bf16 v[14:17], v[66:69], v[78:81], v[14:17]
	v_mfma_f32_16x16x32_bf16 v[10:13], v[66:69], v[152:155], v[10:13]
	ds_read_b128 v[66:69], v181 offset:52416
	s_waitcnt lgkmcnt(0)
	v_mfma_f32_16x16x32_bf16 v[14:17], v[66:69], v[74:77], v[14:17]
	v_mfma_f32_16x16x32_bf16 v[10:13], v[66:69], v[148:151], v[10:13]
	ds_read_b128 v[66:69], v181 offset:56576
	s_waitcnt lgkmcnt(0)
; #define LAS __attribute__((address_space(3)))
; #define MFMA16(a, b, c) __builtin_amdgcn_mfma_f32_16x16x32_bf16((a), (b), (c), 0, 0, 0)
; __device__ __forceinline__ void mem_attn(const Params& P, int l, LAS unsigned char* lds, int item, int tid) {
;     ...
;         for (int kt = 0; kt < 16; ++kt) { sa[kt] = (f32x4){0.f, 0.f, 0.f, 0.f}; sb[kt] = (f32x4){0.f, 0.f, 0.f, 0.f};
; #pragma unroll
;             for (int ks = 0; ks < 4; ++ks) { const bf16x8 ka = *(const LAS bf16x8*)(KS + (kt * 16 + i) * 272 + (ks * 32 + quad * 8) * 2); sa[kt] = MFMA16(ka, qf0[ks], sa[kt]); sb[kt] = MFMA16(ka, qf1[ks], sb[kt]); }
;             if (kt & 1) __builtin_amdgcn_sched_barrier(0); }
;         float mxa = -INFINITY, mxb = -INFINITY;
; #pragma unroll
;         for (int kt = 0; kt < 16; ++kt) { mxa = fmaxf(fmaxf(fmaxf(sa[kt][0], sa[kt][1]), fmaxf(sa[kt][2], sa[kt][3])), mxa); mxb = fmaxf(fmaxf(fmaxf(sb[kt][0], sb[kt][1]), fmaxf(sb[kt][2], sb[kt][3])), mxb); }
	v_mfma_f32_16x16x32_bf16 v[70:73], v[66:69], v[164:167], 0
	v_mfma_f32_16x16x32_bf16 v[66:69], v[66:69], v[168:171], 0
	v_mfma_f32_16x16x32_bf16 v[70:73], v[82:85], v[156:159], v[70:73]
	v_mfma_f32_16x16x32_bf16 v[66:69], v[82:85], v[160:163], v[66:69]
	ds_read_b128 v[82:85], v181 offset:56704
	s_waitcnt lgkmcnt(0)
	v_mfma_f32_16x16x32_bf16 v[70:73], v[82:85], v[78:81], v[70:73]
	v_mfma_f32_16x16x32_bf16 v[66:69], v[82:85], v[152:155], v[66:69]
	ds_read_b128 v[82:85], v181 offset:56768
	s_waitcnt lgkmcnt(0)
	v_mfma_f32_16x16x32_bf16 v[86:89], v[82:85], v[74:77], v[70:73]
	v_mfma_f32_16x16x32_bf16 v[82:85], v[82:85], v[148:151], v[66:69]
	s_nop 3
	ds_read_b128 v[66:69], v181 offset:60928
	ds_read_b128 v[192:195], v181 offset:60992
	s_waitcnt lgkmcnt(1)
	v_mfma_f32_16x16x32_bf16 v[70:73], v[66:69], v[164:167], 0
	v_mfma_f32_16x16x32_bf16 v[66:69], v[66:69], v[168:171], 0
	s_waitcnt lgkmcnt(0)
	v_mfma_f32_16x16x32_bf16 v[70:73], v[192:195], v[156:159], v[70:73]
	v_mfma_f32_16x16x32_bf16 v[66:69], v[192:195], v[160:163], v[66:69]
	ds_read_b128 v[192:195], v181 offset:61056
	s_waitcnt lgkmcnt(0)
	v_mfma_f32_16x16x32_bf16 v[70:73], v[192:195], v[78:81], v[70:73]
	v_mfma_f32_16x16x32_bf16 v[66:69], v[192:195], v[152:155], v[66:69]
	ds_read_b128 v[192:195], v181 offset:61120
	s_waitcnt lgkmcnt(0)
	v_mfma_f32_16x16x32_bf16 v[70:73], v[192:195], v[74:77], v[70:73]
	v_mfma_f32_16x16x32_bf16 v[66:69], v[192:195], v[148:151], v[66:69]
	ds_read_b128 v[192:195], v181 offset:65280
	s_waitcnt lgkmcnt(0)
	v_mfma_f32_16x16x32_bf16 v[164:167], v[192:195], v[164:167], 0
	v_mfma_f32_16x16x32_bf16 v[168:171], v[192:195], v[168:171], 0
	ds_read_b128 v[192:195], v181 offset:65344
	s_waitcnt lgkmcnt(0)
	v_mfma_f32_16x16x32_bf16 v[156:159], v[192:195], v[156:159], v[164:167]
	s_nop 3
	ds_read_b128 v[164:167], v181 offset:65408
	s_waitcnt lgkmcnt(0)
	v_mfma_f32_16x16x32_bf16 v[78:81], v[164:167], v[78:81], v[156:159]
	s_nop 2
	ds_read_b128 v[156:159], v181 offset:65472
	v_mfma_f32_16x16x32_bf16 v[160:163], v[192:195], v[160:163], v[168:171]
	v_mfma_f32_16x16x32_bf16 v[152:155], v[164:167], v[152:155], v[160:163]
	s_waitcnt lgkmcnt(0)
	v_mfma_f32_16x16x32_bf16 v[78:81], v[156:159], v[74:77], v[78:81]
	v_mfma_f32_16x16x32_bf16 v[74:77], v[156:159], v[148:151], v[152:155]
	v_max_f32_e32 v148, v7, v7
	v_max_f32_e32 v149, v6, v6
	v_max_f32_e32 v148, v149, v148
	v_max_f32_e32 v149, v9, v9
	v_max_f32_e32 v150, v8, v8
	v_max_f32_e32 v149, v150, v149
	v_max3_f32 v148, v148, v149, s12
	v_max_f32_e32 v149, v3, v3
	v_max_f32_e32 v150, v2, v2
	v_max_f32_e32 v149, v150, v149
	v_max_f32_e32 v150, v5, v5
	v_max_f32_e32 v151, v4, v4
	v_max_f32_e32 v150, v151, v150
	v_max3_f32 v149, v149, v150, s12
	v_max_f32_e32 v150, v59, v59
	v_max_f32_e32 v151, v58, v58
	v_max_f32_e32 v150, v151, v150
	v_max_f32_e32 v151, v61, v61
	v_max_f32_e32 v152, v60, v60
	v_max_f32_e32 v151, v152, v151
	v_max3_f32 v148, v150, v151, v148
	v_max_f32_e32 v150, v63, v63
	v_max_f32_e32 v151, v62, v62
	v_max_f32_e32 v150, v151, v150
	v_max_f32_e32 v151, v65, v65
	v_max_f32_e32 v152, v64, v64
	v_max_f32_e32 v151, v152, v151
	v_max3_f32 v149, v150, v151, v149
	v_max_f32_e32 v150, v55, v55
	v_max_f32_e32 v151, v54, v54
	v_max_f32_e32 v150, v151, v150
	v_max_f32_e32 v151, v57, v57
	v_max_f32_e32 v152, v56, v56
	v_max_f32_e32 v151, v152, v151
	v_max3_f32 v148, v150, v151, v148
	v_max_f32_e32 v150, v51, v51
	v_max_f32_e32 v151, v50, v50
	v_max_f32_e32 v150, v151, v150
	v_max_f32_e32 v151, v53, v53
	v_max_f32_e32 v152, v52, v52
	v_max_f32_e32 v151, v152, v151
	v_max3_f32 v149, v150, v151, v149
	v_max_f32_e32 v150, v145, v145
	v_max_f32_e32 v151, v144, v144
	v_max_f32_e32 v150, v151, v150
	v_max_f32_e32 v151, v147, v147
	v_max_f32_e32 v152, v146, v146
	v_max_f32_e32 v151, v152, v151
	v_max3_f32 v148, v150, v151, v148
	v_max_f32_e32 v150, v123, v123
	v_max_f32_e32 v151, v122, v122
	v_max_f32_e32 v150, v151, v150
	v_max_f32_e32 v151, v125, v125
	v_max_f32_e32 v152, v124, v124
	v_max_f32_e32 v151, v152, v151
	v_max3_f32 v149, v150, v151, v149
	v_max_f32_e32 v150, v47, v47
	v_max_f32_e32 v151, v46, v46
	v_max_f32_e32 v150, v151, v150
	v_max_f32_e32 v151, v49, v49
	v_max_f32_e32 v152, v48, v48
	v_max_f32_e32 v151, v152, v151
	v_max3_f32 v148, v150, v151, v148
	v_max_f32_e32 v150, v43, v43
	v_max_f32_e32 v151, v42, v42
	v_max_f32_e32 v150, v151, v150
	v_max_f32_e32 v151, v45, v45
	v_max_f32_e32 v152, v44, v44
	v_max_f32_e32 v151, v152, v151
	v_max3_f32 v149, v150, v151, v149
	v_max_f32_e32 v150, v119, v119
	v_max_f32_e32 v151, v118, v118
	v_max_f32_e32 v150, v151, v150
	v_max_f32_e32 v151, v121, v121
	v_max_f32_e32 v152, v120, v120
	v_max_f32_e32 v151, v152, v151
	v_max3_f32 v148, v150, v151, v148
	v_max_f32_e32 v150, v115, v115
	v_max_f32_e32 v151, v114, v114
	v_max_f32_e32 v150, v151, v150
	v_max_f32_e32 v151, v117, v117
	v_max_f32_e32 v152, v116, v116
	v_max_f32_e32 v151, v152, v151
	v_max3_f32 v149, v150, v151, v149
	v_max_f32_e32 v150, v39, v39
	v_max_f32_e32 v151, v38, v38
	v_max_f32_e32 v150, v151, v150
	v_max_f32_e32 v151, v41, v41
	v_max_f32_e32 v152, v40, v40
	v_max_f32_e32 v151, v152, v151
	v_max3_f32 v148, v150, v151, v148
	v_max_f32_e32 v150, v35, v35
	v_max_f32_e32 v151, v34, v34
	v_max_f32_e32 v150, v151, v150
	v_max_f32_e32 v151, v37, v37
	v_max_f32_e32 v152, v36, v36
	v_max_f32_e32 v151, v152, v151
	v_max3_f32 v149, v150, v151, v149
	v_max_f32_e32 v150, v111, v111
	v_max_f32_e32 v151, v110, v110
	v_max_f32_e32 v150, v151, v150
	v_max_f32_e32 v151, v113, v113
	v_max_f32_e32 v152, v112, v112
	v_max_f32_e32 v151, v152, v151
	v_max3_f32 v148, v150, v151, v148
	v_max_f32_e32 v150, v107, v107
	v_max_f32_e32 v151, v106, v106
; __device__ __forceinline__ void mem_attn(const Params& P, int l, LAS unsigned char* lds, int item, int tid) {
;     ...
;         for (int kt = 0; kt < 16; ++kt) { mxa = fmaxf(fmaxf(fmaxf(sa[kt][0], sa[kt][1]), fmaxf(sa[kt][2], sa[kt][3])), mxa); mxb = fmaxf(fmaxf(fmaxf(sb[kt][0], sb[kt][1]), fmaxf(sb[kt][2], sb[kt][3])), mxb); }
;         mxa = fmaxf(mxa, __shfl_xor(mxa, 16)); mxa = fmaxf(mxa, __shfl_xor(mxa, 32)); mxb = fmaxf(mxb, __shfl_xor(mxb, 16)); mxb = fmaxf(mxb, __shfl_xor(mxb, 32));
;         const float sc = 0.08838834764831845f * 1.4426950408889634f; float lsa = 0.f, lsb = 0.f;
;         bf16x8 pa[8], pbb[8];
; #pragma unroll
;         for (int s = 0; s < 8; ++s) { float p[8], r[8];
; #pragma unroll
;             for (int j = 0; j < 4; ++j) { p[j] = __builtin_amdgcn_exp2f((sa[2 * s][j] - mxa) * sc); p[4 + j] = __builtin_amdgcn_exp2f((sa[2 * s + 1][j] - mxa) * sc); r[j] = __builtin_amdgcn_exp2f((sb[2 * s][j] - mxb) * sc); r[4 + j] = __builtin_amdgcn_exp2f((sb[2 * s + 1][j] - mxb) * sc); }
	v_max_f32_e32 v150, v151, v150
	v_max_f32_e32 v151, v109, v109
	v_max_f32_e32 v152, v108, v108
	v_max_f32_e32 v151, v152, v151
	v_max3_f32 v149, v150, v151, v149
	v_max_f32_e32 v150, v31, v31
	v_max_f32_e32 v151, v30, v30
	v_max_f32_e32 v150, v151, v150
	v_max_f32_e32 v151, v33, v33
	v_max_f32_e32 v152, v32, v32
	v_max_f32_e32 v151, v152, v151
	v_max3_f32 v148, v150, v151, v148
	v_max_f32_e32 v150, v27, v27
	v_max_f32_e32 v151, v26, v26
	v_max_f32_e32 v150, v151, v150
	v_max_f32_e32 v151, v29, v29
	v_max_f32_e32 v152, v28, v28
	v_max_f32_e32 v151, v152, v151
	v_max3_f32 v149, v150, v151, v149
	v_max_f32_e32 v150, v103, v103
	v_max_f32_e32 v151, v102, v102
	v_max_f32_e32 v150, v151, v150
	v_max_f32_e32 v151, v105, v105
	v_max_f32_e32 v152, v104, v104
	v_max_f32_e32 v151, v152, v151
	v_max3_f32 v148, v150, v151, v148
	v_max_f32_e32 v150, v99, v99
	v_max_f32_e32 v151, v98, v98
	v_max_f32_e32 v150, v151, v150
	v_max_f32_e32 v151, v101, v101
	v_max_f32_e32 v152, v100, v100
	v_max_f32_e32 v151, v152, v151
	v_max3_f32 v149, v150, v151, v149
	v_max_f32_e32 v150, v23, v23
	v_max_f32_e32 v151, v22, v22
	v_max_f32_e32 v150, v151, v150
	v_max_f32_e32 v151, v25, v25
	v_max_f32_e32 v152, v24, v24
	v_max_f32_e32 v151, v152, v151
	v_max3_f32 v148, v150, v151, v148
	v_max_f32_e32 v150, v19, v19
	v_max_f32_e32 v151, v18, v18
	v_max_f32_e32 v150, v151, v150
	v_max_f32_e32 v151, v21, v21
	v_max_f32_e32 v152, v20, v20
	v_max_f32_e32 v151, v152, v151
	v_max3_f32 v149, v150, v151, v149
	v_max_f32_e32 v150, v95, v95
	v_max_f32_e32 v151, v94, v94
	v_max_f32_e32 v150, v151, v150
	v_max_f32_e32 v151, v97, v97
	v_max_f32_e32 v152, v96, v96
	v_max_f32_e32 v151, v152, v151
	v_max3_f32 v148, v150, v151, v148
	v_max_f32_e32 v150, v91, v91
	v_max_f32_e32 v151, v90, v90
	v_max_f32_e32 v150, v151, v150
	v_max_f32_e32 v151, v93, v93
	v_max_f32_e32 v152, v92, v92
	v_max_f32_e32 v151, v152, v151
	v_max3_f32 v149, v150, v151, v149
	v_max_f32_e32 v150, v15, v15
	v_max_f32_e32 v151, v14, v14
	v_max_f32_e32 v150, v151, v150
	v_max_f32_e32 v151, v17, v17
	v_max_f32_e32 v152, v16, v16
	v_max_f32_e32 v151, v152, v151
	v_max3_f32 v148, v150, v151, v148
	v_max_f32_e32 v150, v11, v11
	v_max_f32_e32 v151, v10, v10
	v_max_f32_e32 v150, v151, v150
	v_max_f32_e32 v151, v13, v13
	v_max_f32_e32 v152, v12, v12
	v_max_f32_e32 v151, v152, v151
	v_max3_f32 v149, v150, v151, v149
	v_max_f32_e32 v150, v87, v87
	v_max_f32_e32 v151, v86, v86
	v_max_f32_e32 v150, v151, v150
	v_max_f32_e32 v151, v89, v89
	v_max_f32_e32 v152, v88, v88
	v_max_f32_e32 v151, v152, v151
	v_max3_f32 v148, v150, v151, v148
	v_max_f32_e32 v150, v83, v83
	v_max_f32_e32 v151, v82, v82
	v_max_f32_e32 v150, v151, v150
	v_max_f32_e32 v151, v85, v85
	v_max_f32_e32 v152, v84, v84
	v_max_f32_e32 v151, v152, v151
	v_max3_f32 v149, v150, v151, v149
	v_max_f32_e32 v150, v71, v71
	v_max_f32_e32 v151, v70, v70
	v_max_f32_e32 v150, v151, v150
	v_max_f32_e32 v151, v73, v73
	v_max_f32_e32 v152, v72, v72
	v_max_f32_e32 v151, v152, v151
	v_max3_f32 v148, v150, v151, v148
	v_max_f32_e32 v150, v67, v67
	v_max_f32_e32 v151, v66, v66
	v_max_f32_e32 v150, v151, v150
	v_max_f32_e32 v151, v69, v69
	v_max_f32_e32 v152, v68, v68
	v_max_f32_e32 v151, v152, v151
	v_max3_f32 v149, v150, v151, v149
	v_max_f32_e32 v150, v79, v79
	v_max_f32_e32 v151, v78, v78
	v_max_f32_e32 v150, v151, v150
	v_max_f32_e32 v151, v81, v81
	v_max_f32_e32 v152, v80, v80
	v_max_f32_e32 v151, v152, v151
	v_max3_f32 v148, v150, v151, v148
	v_max_f32_e32 v150, v75, v75
	v_max_f32_e32 v151, v74, v74
	v_max_f32_e32 v150, v151, v150
	v_max_f32_e32 v151, v77, v77
	v_max_f32_e32 v152, v76, v76
	v_max_f32_e32 v151, v152, v151
	v_max3_f32 v149, v150, v151, v149
	ds_bpermute_b32 v150, v179, v148
	s_waitcnt lgkmcnt(0)
	v_max_f32_e32 v150, v150, v150
	v_max_f32_e32 v148, v148, v150
	ds_bpermute_b32 v150, v180, v148
	s_waitcnt lgkmcnt(0)
	v_max_f32_e32 v150, v150, v150
	v_max_f32_e32 v148, v148, v150
	ds_bpermute_b32 v150, v179, v149
	v_sub_f32_e32 v6, v6, v148
	v_mul_f32_e32 v6, 0x3e0293ee, v6
	v_sub_f32_e32 v7, v7, v148
	v_exp_f32_e32 v6, v6
	s_waitcnt lgkmcnt(0)
	v_max_f32_e32 v150, v150, v150
	v_max_f32_e32 v149, v149, v150
	ds_bpermute_b32 v150, v180, v149
	v_mul_f32_e32 v7, 0x3e0293ee, v7
	v_sub_f32_e32 v8, v8, v148
	v_exp_f32_e32 v7, v7
	v_mul_f32_e32 v8, 0x3e0293ee, v8
	s_waitcnt lgkmcnt(0)
; __device__ __forceinline__ unsigned pk2(float lo, float hi) { const f32x2c_t v = {lo, hi}; return __builtin_bit_cast(unsigned, __builtin_convertvector(v, bf16x2c_t)); }
; __device__ __forceinline__ void mem_attn(const Params& P, int l, LAS unsigned char* lds, int item, int tid) {
;     ...
;         for (int s = 0; s < 8; ++s) { float p[8], r[8];
; #pragma unroll
;             for (int j = 0; j < 4; ++j) { p[j] = __builtin_amdgcn_exp2f((sa[2 * s][j] - mxa) * sc); p[4 + j] = __builtin_amdgcn_exp2f((sa[2 * s + 1][j] - mxa) * sc); r[j] = __builtin_amdgcn_exp2f((sb[2 * s][j] - mxb) * sc); r[4 + j] = __builtin_amdgcn_exp2f((sb[2 * s + 1][j] - mxb) * sc); }
; #pragma unroll
;             for (int j = 0; j < 8; ++j) { lsa += p[j]; lsb += r[j]; }
;             v4u pw; pw.x = pk2(p[0], p[1]); pw.y = pk2(p[2], p[3]); pw.z = pk2(p[4], p[5]); pw.w = pk2(p[6], p[7]); pa[s] = __builtin_bit_cast(bf16x8, pw);
;             v4u rw; rw.x = pk2(r[0], r[1]); rw.y = pk2(r[2], r[3]); rw.z = pk2(r[4], r[5]); rw.w = pk2(r[6], r[7]); pbb[s] = __builtin_bit_cast(bf16x8, rw); }
;         lsa += __shfl_xor(lsa, 16); lsa += __shfl_xor(lsa, 32); lsb += __shfl_xor(lsb, 16); lsb += __shfl_xor(lsb, 32);
	v_max_f32_e32 v150, v150, v150
	v_max_f32_e32 v149, v149, v150
	v_sub_f32_e32 v62, v62, v149
	v_mul_f32_e32 v62, 0x3e0293ee, v62
	v_sub_f32_e32 v2, v2, v149
	v_exp_f32_e32 v150, v62
	v_sub_f32_e32 v62, v63, v149
	v_mul_f32_e32 v2, 0x3e0293ee, v2
	v_sub_f32_e32 v3, v3, v149
	v_mul_f32_e32 v62, 0x3e0293ee, v62
	v_exp_f32_e32 v2, v2
	v_mul_f32_e32 v3, 0x3e0293ee, v3
	v_exp_f32_e32 v151, v62
	v_sub_f32_e32 v4, v4, v149
	v_sub_f32_e32 v62, v64, v149
	v_exp_f32_e32 v3, v3
	v_mul_f32_e32 v4, 0x3e0293ee, v4
	v_mul_f32_e32 v62, 0x3e0293ee, v62
	v_sub_f32_e32 v9, v9, v148
	v_sub_f32_e32 v5, v5, v149
	v_sub_f32_e32 v58, v58, v148
	v_exp_f32_e32 v8, v8
	v_exp_f32_e32 v4, v4
	v_exp_f32_e32 v152, v62
	v_mul_f32_e32 v9, 0x3e0293ee, v9
	v_mul_f32_e32 v5, 0x3e0293ee, v5
	v_sub_f32_e32 v62, v65, v149
	v_mul_f32_e32 v58, 0x3e0293ee, v58
	v_sub_f32_e32 v59, v59, v148
	v_exp_f32_e32 v9, v9
	v_exp_f32_e32 v5, v5
	v_mul_f32_e32 v62, 0x3e0293ee, v62
	v_exp_f32_e32 v58, v58
	v_mul_f32_e32 v59, 0x3e0293ee, v59
	v_exp_f32_e32 v153, v62
	v_add_f32_e32 v62, 0, v6
	v_add_f32_e32 v63, 0, v2
	v_exp_f32_e32 v59, v59
	v_add_f32_e32 v62, v7, v62
	v_add_f32_e32 v63, v3, v63
	v_add_f32_e32 v62, v8, v62
	v_add_f32_e32 v63, v4, v63
	v_add_f32_e32 v62, v9, v62
	v_add_f32_e32 v63, v5, v63
	v_sub_f32_e32 v60, v60, v148
	v_add_f32_e32 v62, v58, v62
	v_add_f32_e32 v63, v150, v63
	v_mul_f32_e32 v60, 0x3e0293ee, v60
	v_sub_f32_e32 v61, v61, v148
	v_add_f32_e32 v62, v59, v62
	v_add_f32_e32 v63, v151, v63
	v_cvt_pk_bf16_f32 v64, v58, v59
	v_cvt_pk_bf16_f32 v59, v4, v5
	v_sub_f32_e32 v4, v50, v149
	v_sub_f32_e32 v50, v56, v148
	v_exp_f32_e32 v60, v60
	v_mul_f32_e32 v61, 0x3e0293ee, v61
	v_add_f32_e32 v63, v152, v63
	v_mul_f32_e32 v50, 0x3e0293ee, v50
	v_exp_f32_e32 v61, v61
	v_add_f32_e32 v155, v153, v63
	v_cvt_pk_bf16_f32 v63, v8, v9
	v_sub_f32_e32 v8, v51, v149
	v_exp_f32_e32 v51, v50
	v_sub_f32_e32 v50, v146, v148
	v_mul_f32_e32 v50, 0x3e0293ee, v50
	v_cvt_pk_bf16_f32 v58, v2, v3
	v_sub_f32_e32 v2, v54, v148
	v_exp_f32_e32 v54, v50
	v_sub_f32_e32 v50, v52, v149
	v_add_f32_e32 v62, v60, v62
	v_mul_f32_e32 v50, 0x3e0293ee, v50
	v_add_f32_e32 v154, v61, v62
	v_cvt_pk_bf16_f32 v62, v6, v7
	v_sub_f32_e32 v6, v55, v148
	v_exp_f32_e32 v55, v50
	v_sub_f32_e32 v50, v124, v149
	v_mul_f32_e32 v50, 0x3e0293ee, v50
	v_sub_f32_e32 v5, v122, v149
	v_exp_f32_e32 v122, v50
	v_sub_f32_e32 v50, v57, v148
	v_mul_f32_e32 v50, 0x3e0293ee, v50
	v_mul_f32_e32 v4, 0x3e0293ee, v4
	v_exp_f32_e32 v52, v50
	v_sub_f32_e32 v50, v147, v148
	v_mul_f32_e32 v2, 0x3e0293ee, v2
	v_exp_f32_e32 v4, v4
	v_mul_f32_e32 v8, 0x3e0293ee, v8
	v_mul_f32_e32 v50, 0x3e0293ee, v50
	v_exp_f32_e32 v2, v2
	v_mul_f32_e32 v6, 0x3e0293ee, v6
	v_exp_f32_e32 v8, v8
	v_exp_f32_e32 v56, v50
	v_sub_f32_e32 v50, v53, v149
	v_exp_f32_e32 v6, v6
	v_mul_f32_e32 v50, 0x3e0293ee, v50
	v_sub_f32_e32 v3, v144, v148
	v_mul_f32_e32 v5, 0x3e0293ee, v5
	v_sub_f32_e32 v9, v123, v149
	v_exp_f32_e32 v57, v50
	v_sub_f32_e32 v50, v125, v149
	v_mul_f32_e32 v3, 0x3e0293ee, v3
	v_exp_f32_e32 v5, v5
	v_sub_f32_e32 v7, v145, v148
	v_mul_f32_e32 v9, 0x3e0293ee, v9
	v_mul_f32_e32 v50, 0x3e0293ee, v50
	v_add_f32_e32 v53, v4, v155
	v_exp_f32_e32 v3, v3
	v_mul_f32_e32 v7, 0x3e0293ee, v7
	v_exp_f32_e32 v9, v9
	v_exp_f32_e32 v123, v50
	v_add_f32_e32 v50, v2, v154
	v_add_f32_e32 v53, v8, v53
	v_exp_f32_e32 v7, v7
	v_add_f32_e32 v50, v6, v50
	v_add_f32_e32 v53, v55, v53
	v_add_f32_e32 v50, v51, v50
	v_add_f32_e32 v53, v57, v53
	v_add_f32_e32 v50, v52, v50
	v_add_f32_e32 v53, v5, v53
	v_add_f32_e32 v50, v3, v50
	v_add_f32_e32 v53, v9, v53
	v_add_f32_e32 v50, v7, v50
	v_add_f32_e32 v53, v122, v53
	v_add_f32_e32 v50, v54, v50
	v_add_f32_e32 v125, v123, v53
	v_cvt_pk_bf16_f32 v53, v54, v56
	v_cvt_pk_bf16_f32 v54, v4, v8
	v_sub_f32_e32 v4, v42, v149
	v_sub_f32_e32 v42, v48, v148
	v_mul_f32_e32 v42, 0x3e0293ee, v42
	v_sub_f32_e32 v8, v43, v149
	v_exp_f32_e32 v43, v42
	v_sub_f32_e32 v42, v120, v148
	v_mul_f32_e32 v42, 0x3e0293ee, v42
	v_add_f32_e32 v124, v56, v50
	v_cvt_pk_bf16_f32 v50, v2, v6
	v_sub_f32_e32 v2, v46, v148
	v_exp_f32_e32 v46, v42
	v_sub_f32_e32 v42, v44, v149
	v_mul_f32_e32 v42, 0x3e0293ee, v42
	v_sub_f32_e32 v6, v47, v148
	v_exp_f32_e32 v47, v42
	v_sub_f32_e32 v42, v116, v149
	v_mul_f32_e32 v42, 0x3e0293ee, v42
	v_cvt_pk_bf16_f32 v56, v5, v9
	v_sub_f32_e32 v5, v114, v149
	v_exp_f32_e32 v114, v42
	v_sub_f32_e32 v42, v49, v148
	v_mul_f32_e32 v42, 0x3e0293ee, v42
	v_mul_f32_e32 v4, 0x3e0293ee, v4
	v_exp_f32_e32 v44, v42
	v_sub_f32_e32 v42, v121, v148
	v_mul_f32_e32 v2, 0x3e0293ee, v2
	v_exp_f32_e32 v4, v4
	v_mul_f32_e32 v8, 0x3e0293ee, v8
	v_mul_f32_e32 v42, 0x3e0293ee, v42
	v_exp_f32_e32 v2, v2
	v_mul_f32_e32 v6, 0x3e0293ee, v6
	v_exp_f32_e32 v8, v8
	v_exp_f32_e32 v48, v42
	v_sub_f32_e32 v42, v45, v149
	v_exp_f32_e32 v6, v6
	v_mul_f32_e32 v42, 0x3e0293ee, v42
	v_cvt_pk_bf16_f32 v51, v51, v52
	v_cvt_pk_bf16_f32 v52, v3, v7
	v_sub_f32_e32 v3, v118, v148
	v_mul_f32_e32 v5, 0x3e0293ee, v5
	v_sub_f32_e32 v9, v115, v149
	v_exp_f32_e32 v49, v42
	v_sub_f32_e32 v42, v117, v149
	v_mul_f32_e32 v3, 0x3e0293ee, v3
	v_exp_f32_e32 v5, v5
	v_sub_f32_e32 v7, v119, v148
	v_mul_f32_e32 v9, 0x3e0293ee, v9
	v_mul_f32_e32 v42, 0x3e0293ee, v42
	v_add_f32_e32 v45, v4, v125
	v_exp_f32_e32 v3, v3
	v_mul_f32_e32 v7, 0x3e0293ee, v7
	v_exp_f32_e32 v9, v9
	v_exp_f32_e32 v115, v42
	v_add_f32_e32 v42, v2, v124
	v_add_f32_e32 v45, v8, v45
	v_exp_f32_e32 v7, v7
	v_add_f32_e32 v42, v6, v42
	v_add_f32_e32 v45, v47, v45
	v_add_f32_e32 v42, v43, v42
	v_add_f32_e32 v45, v49, v45
	v_add_f32_e32 v42, v44, v42
	v_add_f32_e32 v45, v5, v45
	v_add_f32_e32 v42, v3, v42
	v_add_f32_e32 v45, v9, v45
; __device__ __forceinline__ unsigned pk2(float lo, float hi) { const f32x2c_t v = {lo, hi}; return __builtin_bit_cast(unsigned, __builtin_convertvector(v, bf16x2c_t)); }
; __device__ __forceinline__ void mem_attn(const Params& P, int l, LAS unsigned char* lds, int item, int tid) {
;     ...
;         for (int s = 0; s < 8; ++s) { float p[8], r[8];
; #pragma unroll
;             for (int j = 0; j < 4; ++j) { p[j] = __builtin_amdgcn_exp2f((sa[2 * s][j] - mxa) * sc); p[4 + j] = __builtin_amdgcn_exp2f((sa[2 * s + 1][j] - mxa) * sc); r[j] = __builtin_amdgcn_exp2f((sb[2 * s][j] - mxb) * sc); r[4 + j] = __builtin_amdgcn_exp2f((sb[2 * s + 1][j] - mxb) * sc); }
; #pragma unroll
;             for (int j = 0; j < 8; ++j) { lsa += p[j]; lsb += r[j]; }
;             v4u pw; pw.x = pk2(p[0], p[1]); pw.y = pk2(p[2], p[3]); pw.z = pk2(p[4], p[5]); pw.w = pk2(p[6], p[7]); pa[s] = __builtin_bit_cast(bf16x8, pw);
;             v4u rw; rw.x = pk2(r[0], r[1]); rw.y = pk2(r[2], r[3]); rw.z = pk2(r[4], r[5]); rw.w = pk2(r[6], r[7]); pbb[s] = __builtin_bit_cast(bf16x8, rw); }
	v_add_f32_e32 v42, v7, v42
	v_add_f32_e32 v45, v114, v45
	v_add_f32_e32 v42, v46, v42
	v_add_f32_e32 v117, v115, v45
	v_cvt_pk_bf16_f32 v45, v46, v48
	v_cvt_pk_bf16_f32 v46, v4, v8
	v_sub_f32_e32 v4, v34, v149
	v_sub_f32_e32 v34, v40, v148
	v_mul_f32_e32 v34, 0x3e0293ee, v34
	v_sub_f32_e32 v8, v35, v149
	v_exp_f32_e32 v35, v34
	v_sub_f32_e32 v34, v112, v148
	v_mul_f32_e32 v34, 0x3e0293ee, v34
	v_add_f32_e32 v116, v48, v42
	v_cvt_pk_bf16_f32 v42, v2, v6
	v_sub_f32_e32 v2, v38, v148
	v_exp_f32_e32 v38, v34
	v_sub_f32_e32 v34, v36, v149
	v_mul_f32_e32 v34, 0x3e0293ee, v34
	v_sub_f32_e32 v6, v39, v148
	v_exp_f32_e32 v39, v34
	v_sub_f32_e32 v34, v108, v149
	v_mul_f32_e32 v34, 0x3e0293ee, v34
	v_cvt_pk_bf16_f32 v48, v5, v9
	v_sub_f32_e32 v5, v106, v149
	v_exp_f32_e32 v106, v34
	v_sub_f32_e32 v34, v41, v148
	v_mul_f32_e32 v34, 0x3e0293ee, v34
	v_mul_f32_e32 v4, 0x3e0293ee, v4
	v_exp_f32_e32 v36, v34
	v_sub_f32_e32 v34, v113, v148
	v_mul_f32_e32 v2, 0x3e0293ee, v2
	v_exp_f32_e32 v4, v4
	v_mul_f32_e32 v8, 0x3e0293ee, v8
	v_mul_f32_e32 v34, 0x3e0293ee, v34
	v_exp_f32_e32 v2, v2
	v_mul_f32_e32 v6, 0x3e0293ee, v6
	v_exp_f32_e32 v8, v8
	v_exp_f32_e32 v40, v34
	v_sub_f32_e32 v34, v37, v149
	v_exp_f32_e32 v6, v6
	v_mul_f32_e32 v34, 0x3e0293ee, v34
	v_cvt_pk_bf16_f32 v43, v43, v44
	v_cvt_pk_bf16_f32 v44, v3, v7
	v_sub_f32_e32 v3, v110, v148
	v_mul_f32_e32 v5, 0x3e0293ee, v5
	v_sub_f32_e32 v9, v107, v149
	v_exp_f32_e32 v41, v34
	v_sub_f32_e32 v34, v109, v149
	v_mul_f32_e32 v3, 0x3e0293ee, v3
	v_exp_f32_e32 v5, v5
	v_sub_f32_e32 v7, v111, v148
	v_mul_f32_e32 v9, 0x3e0293ee, v9
	v_mul_f32_e32 v34, 0x3e0293ee, v34
	v_add_f32_e32 v37, v4, v117
	v_exp_f32_e32 v3, v3
	v_mul_f32_e32 v7, 0x3e0293ee, v7
	v_exp_f32_e32 v9, v9
	v_exp_f32_e32 v107, v34
	v_add_f32_e32 v34, v2, v116
	v_add_f32_e32 v37, v8, v37
	v_exp_f32_e32 v7, v7
	v_add_f32_e32 v34, v6, v34
	v_add_f32_e32 v37, v39, v37
	v_add_f32_e32 v34, v35, v34
	v_add_f32_e32 v37, v41, v37
	v_add_f32_e32 v34, v36, v34
	v_add_f32_e32 v37, v5, v37
	v_add_f32_e32 v34, v3, v34
	v_add_f32_e32 v37, v9, v37
	v_add_f32_e32 v34, v7, v34
	v_add_f32_e32 v37, v106, v37
	v_add_f32_e32 v34, v38, v34
	v_add_f32_e32 v109, v107, v37
	v_cvt_pk_bf16_f32 v37, v38, v40
	v_cvt_pk_bf16_f32 v38, v4, v8
	v_sub_f32_e32 v4, v26, v149
	v_sub_f32_e32 v26, v32, v148
	v_mul_f32_e32 v26, 0x3e0293ee, v26
	v_sub_f32_e32 v8, v27, v149
	v_exp_f32_e32 v27, v26
	v_sub_f32_e32 v26, v104, v148
	v_mul_f32_e32 v26, 0x3e0293ee, v26
	v_add_f32_e32 v108, v40, v34
	v_cvt_pk_bf16_f32 v34, v2, v6
	v_sub_f32_e32 v2, v30, v148
	v_exp_f32_e32 v30, v26
	v_sub_f32_e32 v26, v28, v149
	v_mul_f32_e32 v26, 0x3e0293ee, v26
	v_sub_f32_e32 v6, v31, v148
	v_exp_f32_e32 v31, v26
	v_sub_f32_e32 v26, v100, v149
	v_mul_f32_e32 v26, 0x3e0293ee, v26
	v_cvt_pk_bf16_f32 v40, v5, v9
	v_sub_f32_e32 v5, v98, v149
	v_exp_f32_e32 v98, v26
	v_sub_f32_e32 v26, v33, v148
	v_mul_f32_e32 v26, 0x3e0293ee, v26
	v_mul_f32_e32 v4, 0x3e0293ee, v4
	v_exp_f32_e32 v28, v26
	v_sub_f32_e32 v26, v105, v148
	v_mul_f32_e32 v2, 0x3e0293ee, v2
	v_exp_f32_e32 v4, v4
	v_mul_f32_e32 v8, 0x3e0293ee, v8
	v_mul_f32_e32 v26, 0x3e0293ee, v26
	v_exp_f32_e32 v2, v2
	v_mul_f32_e32 v6, 0x3e0293ee, v6
	v_exp_f32_e32 v8, v8
	v_exp_f32_e32 v32, v26
	v_sub_f32_e32 v26, v29, v149
	v_exp_f32_e32 v6, v6
	v_mul_f32_e32 v26, 0x3e0293ee, v26
	v_cvt_pk_bf16_f32 v35, v35, v36
	v_cvt_pk_bf16_f32 v36, v3, v7
	v_sub_f32_e32 v3, v102, v148
	v_mul_f32_e32 v5, 0x3e0293ee, v5
	v_sub_f32_e32 v9, v99, v149
	v_exp_f32_e32 v33, v26
	v_sub_f32_e32 v26, v101, v149
	v_mul_f32_e32 v3, 0x3e0293ee, v3
	v_exp_f32_e32 v5, v5
	v_sub_f32_e32 v7, v103, v148
	v_mul_f32_e32 v9, 0x3e0293ee, v9
	v_mul_f32_e32 v26, 0x3e0293ee, v26
	v_add_f32_e32 v29, v4, v109
	v_exp_f32_e32 v3, v3
	v_mul_f32_e32 v7, 0x3e0293ee, v7
	v_exp_f32_e32 v9, v9
	v_exp_f32_e32 v99, v26
	v_add_f32_e32 v26, v2, v108
	v_add_f32_e32 v29, v8, v29
	v_exp_f32_e32 v7, v7
	v_add_f32_e32 v26, v6, v26
	v_add_f32_e32 v29, v31, v29
	v_add_f32_e32 v26, v27, v26
	v_add_f32_e32 v29, v33, v29
	v_add_f32_e32 v26, v28, v26
	v_add_f32_e32 v29, v5, v29
	v_add_f32_e32 v26, v3, v26
	v_add_f32_e32 v29, v9, v29
	v_add_f32_e32 v26, v7, v26
	v_add_f32_e32 v29, v98, v29
	v_add_f32_e32 v26, v30, v26
	v_add_f32_e32 v101, v99, v29
	v_cvt_pk_bf16_f32 v29, v30, v32
	v_cvt_pk_bf16_f32 v30, v4, v8
	v_sub_f32_e32 v4, v18, v149
	v_sub_f32_e32 v18, v24, v148
	v_mul_f32_e32 v18, 0x3e0293ee, v18
	v_sub_f32_e32 v8, v19, v149
	v_exp_f32_e32 v19, v18
	v_sub_f32_e32 v18, v96, v148
	v_mul_f32_e32 v18, 0x3e0293ee, v18
	v_add_f32_e32 v100, v32, v26
	v_cvt_pk_bf16_f32 v26, v2, v6
	v_sub_f32_e32 v2, v22, v148
	v_exp_f32_e32 v22, v18
	v_sub_f32_e32 v18, v20, v149
	v_mul_f32_e32 v18, 0x3e0293ee, v18
	v_sub_f32_e32 v6, v23, v148
	v_exp_f32_e32 v23, v18
	v_sub_f32_e32 v18, v92, v149
	v_mul_f32_e32 v18, 0x3e0293ee, v18
	v_cvt_pk_bf16_f32 v32, v5, v9
	v_sub_f32_e32 v5, v90, v149
	v_exp_f32_e32 v90, v18
	v_sub_f32_e32 v18, v25, v148
	v_mul_f32_e32 v18, 0x3e0293ee, v18
	v_mul_f32_e32 v4, 0x3e0293ee, v4
	v_exp_f32_e32 v20, v18
	v_sub_f32_e32 v18, v97, v148
	v_mul_f32_e32 v2, 0x3e0293ee, v2
	v_exp_f32_e32 v4, v4
	v_mul_f32_e32 v8, 0x3e0293ee, v8
	v_mul_f32_e32 v18, 0x3e0293ee, v18
	v_exp_f32_e32 v2, v2
	v_mul_f32_e32 v6, 0x3e0293ee, v6
	v_exp_f32_e32 v8, v8
	v_exp_f32_e32 v24, v18
	v_sub_f32_e32 v18, v21, v149
	v_exp_f32_e32 v6, v6
	v_mul_f32_e32 v18, 0x3e0293ee, v18
	v_cvt_pk_bf16_f32 v27, v27, v28
	v_cvt_pk_bf16_f32 v28, v3, v7
	v_sub_f32_e32 v3, v94, v148
	v_mul_f32_e32 v5, 0x3e0293ee, v5
	v_sub_f32_e32 v9, v91, v149
	v_exp_f32_e32 v25, v18
	v_sub_f32_e32 v18, v93, v149
	v_mul_f32_e32 v3, 0x3e0293ee, v3
	v_exp_f32_e32 v5, v5
; #define LAS __attribute__((address_space(3)))
; __device__ __forceinline__ unsigned pk2(float lo, float hi) { const f32x2c_t v = {lo, hi}; return __builtin_bit_cast(unsigned, __builtin_convertvector(v, bf16x2c_t)); }
; #define MFMA16(a, b, c) __builtin_amdgcn_mfma_f32_16x16x32_bf16((a), (b), (c), 0, 0, 0)
; __device__ __forceinline__ s16x4 trread(const LAS unsigned char* p) { return __builtin_bit_cast(s16x4, __builtin_amdgcn_ds_read_tr16_b64_v4i16((LAS s16x4*)p)); }
; __device__ __forceinline__ bf16x8 cat8(s16x4 lo, s16x4 hi) { return (bf16x8){lo[0], lo[1], lo[2], lo[3], hi[0], hi[1], hi[2], hi[3]}; }
; __device__ __forceinline__ void mem_attn(const Params& P, int l, LAS unsigned char* lds, int item, int tid) {
;     ...
;         for (int s = 0; s < 8; ++s) { float p[8], r[8];
; #pragma unroll
;             for (int j = 0; j < 4; ++j) { p[j] = __builtin_amdgcn_exp2f((sa[2 * s][j] - mxa) * sc); p[4 + j] = __builtin_amdgcn_exp2f((sa[2 * s + 1][j] - mxa) * sc); r[j] = __builtin_amdgcn_exp2f((sb[2 * s][j] - mxb) * sc); r[4 + j] = __builtin_amdgcn_exp2f((sb[2 * s + 1][j] - mxb) * sc); }
; #pragma unroll
;             for (int j = 0; j < 8; ++j) { lsa += p[j]; lsb += r[j]; }
;             v4u pw; pw.x = pk2(p[0], p[1]); pw.y = pk2(p[2], p[3]); pw.z = pk2(p[4], p[5]); pw.w = pk2(p[6], p[7]); pa[s] = __builtin_bit_cast(bf16x8, pw);
;             v4u rw; rw.x = pk2(r[0], r[1]); rw.y = pk2(r[2], r[3]); rw.z = pk2(r[4], r[5]); rw.w = pk2(r[6], r[7]); pbb[s] = __builtin_bit_cast(bf16x8, rw); }
;         lsa += __shfl_xor(lsa, 16); lsa += __shfl_xor(lsa, 32); lsb += __shfl_xor(lsb, 16); lsb += __shfl_xor(lsb, 32);
;         f32x4 oa[8], ob[8];
; #pragma unroll
;         for (int et = 0; et < 8; ++et) { oa[et] = (f32x4){0.f, 0.f, 0.f, 0.f}; ob[et] = (f32x4){0.f, 0.f, 0.f, 0.f}; }
; #pragma unroll
;         for (int s = 0; s < 8; ++s) { const LAS unsigned char* vp = VS + (32 * s + quad * 4 + (i >> 2)) * 288 + (4 * (i & 3)) * 2;
; #pragma unroll
;             for (int et = 0; et < 8; ++et) { const bf16x8 va = cat8(trread(vp + et * 32), trread(vp + et * 32 + 16 * 288)); oa[et] = MFMA16(va, pa[s], oa[et]); ob[et] = MFMA16(va, pbb[s], ob[et]); }
	v_sub_f32_e32 v7, v95, v148
	v_mul_f32_e32 v9, 0x3e0293ee, v9
	v_mul_f32_e32 v18, 0x3e0293ee, v18
	v_add_f32_e32 v21, v4, v101
	v_exp_f32_e32 v3, v3
	v_mul_f32_e32 v7, 0x3e0293ee, v7
	v_exp_f32_e32 v9, v9
	v_exp_f32_e32 v91, v18
	v_add_f32_e32 v18, v2, v100
	v_add_f32_e32 v21, v8, v21
	v_exp_f32_e32 v7, v7
	v_add_f32_e32 v18, v6, v18
	v_add_f32_e32 v21, v23, v21
	v_add_f32_e32 v18, v19, v18
	v_add_f32_e32 v21, v25, v21
	v_add_f32_e32 v18, v20, v18
	v_add_f32_e32 v21, v5, v21
	v_add_f32_e32 v18, v3, v18
	v_add_f32_e32 v21, v9, v21
	v_add_f32_e32 v18, v7, v18
	v_add_f32_e32 v21, v90, v21
	v_add_f32_e32 v18, v22, v18
	v_add_f32_e32 v93, v91, v21
	v_cvt_pk_bf16_f32 v21, v22, v24
	v_cvt_pk_bf16_f32 v22, v4, v8
	v_sub_f32_e32 v4, v10, v149
	v_sub_f32_e32 v10, v16, v148
	v_mul_f32_e32 v10, 0x3e0293ee, v10
	v_sub_f32_e32 v8, v11, v149
	v_exp_f32_e32 v11, v10
	v_sub_f32_e32 v10, v88, v148
	v_mul_f32_e32 v10, 0x3e0293ee, v10
	v_add_f32_e32 v92, v24, v18
	v_cvt_pk_bf16_f32 v18, v2, v6
	v_sub_f32_e32 v2, v14, v148
	v_exp_f32_e32 v14, v10
	v_sub_f32_e32 v10, v12, v149
	v_mul_f32_e32 v10, 0x3e0293ee, v10
	v_sub_f32_e32 v6, v15, v148
	v_exp_f32_e32 v15, v10
	v_sub_f32_e32 v10, v84, v149
	v_mul_f32_e32 v10, 0x3e0293ee, v10
	v_cvt_pk_bf16_f32 v24, v5, v9
	v_sub_f32_e32 v5, v82, v149
	v_exp_f32_e32 v82, v10
	v_sub_f32_e32 v10, v17, v148
	v_mul_f32_e32 v10, 0x3e0293ee, v10
	v_mul_f32_e32 v4, 0x3e0293ee, v4
	v_exp_f32_e32 v12, v10
	v_sub_f32_e32 v10, v89, v148
	v_mul_f32_e32 v2, 0x3e0293ee, v2
	v_exp_f32_e32 v4, v4
	v_mul_f32_e32 v8, 0x3e0293ee, v8
	v_mul_f32_e32 v10, 0x3e0293ee, v10
	v_exp_f32_e32 v2, v2
	v_mul_f32_e32 v6, 0x3e0293ee, v6
	v_exp_f32_e32 v8, v8
	v_exp_f32_e32 v16, v10
	v_sub_f32_e32 v10, v13, v149
	v_exp_f32_e32 v6, v6
	v_mul_f32_e32 v10, 0x3e0293ee, v10
	v_cvt_pk_bf16_f32 v19, v19, v20
	v_cvt_pk_bf16_f32 v20, v3, v7
	v_sub_f32_e32 v3, v86, v148
	v_mul_f32_e32 v5, 0x3e0293ee, v5
	v_sub_f32_e32 v7, v87, v148
	v_sub_f32_e32 v9, v83, v149
	v_exp_f32_e32 v17, v10
	v_sub_f32_e32 v10, v85, v149
	v_mul_f32_e32 v3, 0x3e0293ee, v3
	v_exp_f32_e32 v5, v5
	v_mul_f32_e32 v7, 0x3e0293ee, v7
	v_mul_f32_e32 v9, 0x3e0293ee, v9
	v_mul_f32_e32 v10, 0x3e0293ee, v10
	v_add_f32_e32 v13, v4, v93
	v_exp_f32_e32 v3, v3
	v_exp_f32_e32 v7, v7
	v_exp_f32_e32 v9, v9
	v_exp_f32_e32 v83, v10
	v_add_f32_e32 v10, v2, v92
	v_add_f32_e32 v13, v8, v13
	v_add_f32_e32 v10, v6, v10
	v_add_f32_e32 v13, v15, v13
	v_add_f32_e32 v10, v11, v10
	v_add_f32_e32 v13, v17, v13
	v_add_f32_e32 v10, v12, v10
	v_add_f32_e32 v13, v5, v13
	v_add_f32_e32 v10, v3, v10
	v_add_f32_e32 v13, v9, v13
	v_cvt_pk_bf16_f32 v11, v11, v12
	v_cvt_pk_bf16_f32 v12, v3, v7
	v_sub_f32_e32 v3, v78, v148
	v_add_f32_e32 v10, v7, v10
	v_add_f32_e32 v13, v82, v13
	v_mul_f32_e32 v3, 0x3e0293ee, v3
	v_add_f32_e32 v10, v14, v10
	v_add_f32_e32 v85, v83, v13
	v_cvt_pk_bf16_f32 v13, v14, v16
	v_cvt_pk_bf16_f32 v14, v4, v8
	v_exp_f32_e32 v4, v3
	v_sub_f32_e32 v3, v66, v149
	v_mul_f32_e32 v3, 0x3e0293ee, v3
	v_add_f32_e32 v84, v16, v10
	v_cvt_pk_bf16_f32 v10, v2, v6
	v_exp_f32_e32 v6, v3
	v_sub_f32_e32 v3, v74, v149
	v_sub_f32_e32 v2, v70, v148
	v_mul_f32_e32 v3, 0x3e0293ee, v3
	v_mul_f32_e32 v2, 0x3e0293ee, v2
	v_exp_f32_e32 v8, v3
	v_sub_f32_e32 v3, v71, v148
	v_exp_f32_e32 v2, v2
	v_mul_f32_e32 v3, 0x3e0293ee, v3
	v_sub_f32_e32 v66, v72, v148
	v_exp_f32_e32 v3, v3
	v_mul_f32_e32 v66, 0x3e0293ee, v66
	v_sub_f32_e32 v71, v73, v148
	v_sub_f32_e32 v7, v67, v149
	v_exp_f32_e32 v66, v66
	v_mul_f32_e32 v71, 0x3e0293ee, v71
	v_cvt_pk_bf16_f32 v16, v5, v9
	v_sub_f32_e32 v5, v79, v148
	v_mul_f32_e32 v7, 0x3e0293ee, v7
	v_sub_f32_e32 v68, v68, v149
	v_exp_f32_e32 v71, v71
	v_mul_f32_e32 v5, 0x3e0293ee, v5
	v_exp_f32_e32 v7, v7
	v_sub_f32_e32 v67, v80, v148
	v_mul_f32_e32 v68, 0x3e0293ee, v68
	v_sub_f32_e32 v69, v69, v149
	v_add_f32_e32 v74, v2, v84
	v_exp_f32_e32 v5, v5
	v_mul_f32_e32 v67, 0x3e0293ee, v67
	v_exp_f32_e32 v68, v68
	v_sub_f32_e32 v72, v81, v148
	v_mul_f32_e32 v69, 0x3e0293ee, v69
	v_add_f32_e32 v74, v3, v74
	v_sub_f32_e32 v9, v75, v149
	v_exp_f32_e32 v67, v67
	v_mul_f32_e32 v72, 0x3e0293ee, v72
	v_exp_f32_e32 v69, v69
	v_add_f32_e32 v74, v66, v74
	v_mul_f32_e32 v9, 0x3e0293ee, v9
	v_sub_f32_e32 v70, v76, v149
	v_exp_f32_e32 v72, v72
	v_add_f32_e32 v75, v6, v85
	v_add_f32_e32 v74, v71, v74
	v_exp_f32_e32 v9, v9
	v_mul_f32_e32 v70, 0x3e0293ee, v70
	v_sub_f32_e32 v73, v77, v149
	v_add_f32_e32 v75, v7, v75
	v_add_f32_e32 v74, v4, v74
	v_exp_f32_e32 v70, v70
	v_mul_f32_e32 v73, 0x3e0293ee, v73
	v_add_f32_e32 v75, v68, v75
	v_add_f32_e32 v74, v5, v74
	v_exp_f32_e32 v73, v73
	v_add_f32_e32 v75, v69, v75
	v_add_f32_e32 v74, v67, v74
	v_add_f32_e32 v75, v8, v75
	v_add_f32_e32 v74, v72, v74
	v_add_f32_e32 v75, v9, v75
	v_cvt_pk_bf16_f32 v2, v2, v3
	v_cvt_pk_bf16_f32 v3, v66, v71
	ds_bpermute_b32 v66, v179, v74
	v_add_f32_e32 v75, v70, v75
	v_add_f32_e32 v75, v73, v75
	v_cvt_pk_bf16_f32 v4, v4, v5
	v_cvt_pk_bf16_f32 v5, v67, v72
	v_cvt_pk_bf16_f32 v8, v8, v9
	v_cvt_pk_bf16_f32 v9, v70, v73
	ds_read_b64_tr_b16 v[72:73], v182 offset:4608
	ds_read_b64_tr_b16 v[70:71], v182
	ds_read_b64_tr_b16 v[78:79], v182 offset:32
	ds_read_b64_tr_b16 v[80:81], v182 offset:4640
	v_cvt_pk_bf16_f32 v6, v6, v7
	v_cvt_pk_bf16_f32 v7, v68, v69
	s_waitcnt lgkmcnt(4)
; #define LAS __attribute__((address_space(3)))
; #define MFMA16(a, b, c) __builtin_amdgcn_mfma_f32_16x16x32_bf16((a), (b), (c), 0, 0, 0)
; __device__ __forceinline__ s16x4 trread(const LAS unsigned char* p) { return __builtin_bit_cast(s16x4, __builtin_amdgcn_ds_read_tr16_b64_v4i16((LAS s16x4*)p)); }
; __device__ __forceinline__ bf16x8 cat8(s16x4 lo, s16x4 hi) { return (bf16x8){lo[0], lo[1], lo[2], lo[3], hi[0], hi[1], hi[2], hi[3]}; }
; __device__ __forceinline__ void mem_attn(const Params& P, int l, LAS unsigned char* lds, int item, int tid) {
;     ...
;         lsa += __shfl_xor(lsa, 16); lsa += __shfl_xor(lsa, 32); lsb += __shfl_xor(lsb, 16); lsb += __shfl_xor(lsb, 32);
;         f32x4 oa[8], ob[8];
; #pragma unroll
;         for (int et = 0; et < 8; ++et) { oa[et] = (f32x4){0.f, 0.f, 0.f, 0.f}; ob[et] = (f32x4){0.f, 0.f, 0.f, 0.f}; }
; #pragma unroll
;         for (int s = 0; s < 8; ++s) { const LAS unsigned char* vp = VS + (32 * s + quad * 4 + (i >> 2)) * 288 + (4 * (i & 3)) * 2;
; #pragma unroll
;             for (int et = 0; et < 8; ++et) { const bf16x8 va = cat8(trread(vp + et * 32), trread(vp + et * 32 + 16 * 288)); oa[et] = MFMA16(va, pa[s], oa[et]); ob[et] = MFMA16(va, pbb[s], ob[et]); }
;             __builtin_amdgcn_sched_barrier(0); }
	v_add_f32_e32 v66, v74, v66
	ds_bpermute_b32 v68, v179, v75
	ds_bpermute_b32 v67, v180, v66
	ds_read_b64_tr_b16 v[86:87], v182 offset:64
	ds_read_b64_tr_b16 v[88:89], v182 offset:4672
	ds_read_b64_tr_b16 v[94:95], v182 offset:96
	ds_read_b64_tr_b16 v[96:97], v182 offset:4704
	ds_read_b64_tr_b16 v[102:103], v182 offset:128
	ds_read_b64_tr_b16 v[104:105], v182 offset:4736
	ds_read_b64_tr_b16 v[110:111], v182 offset:160
	ds_read_b64_tr_b16 v[112:113], v182 offset:4768
	ds_read_b64_tr_b16 v[118:119], v182 offset:192
	ds_read_b64_tr_b16 v[120:121], v182 offset:4800
	ds_read_b64_tr_b16 v[144:145], v182 offset:224
	ds_read_b64_tr_b16 v[146:147], v182 offset:4832
	v_cvt_pk_bf16_f32 v65, v60, v61
	v_cvt_pk_bf16_f32 v60, v150, v151
	v_cvt_pk_bf16_f32 v61, v152, v153
	v_cvt_pk_bf16_f32 v55, v55, v57
	v_cvt_pk_bf16_f32 v57, v122, v123
	s_waitcnt lgkmcnt(13)
	v_add_f32_e32 v123, v75, v68
	v_cvt_pk_bf16_f32 v47, v47, v49
	v_cvt_pk_bf16_f32 v49, v114, v115
	v_cvt_pk_bf16_f32 v39, v39, v41
	v_cvt_pk_bf16_f32 v41, v106, v107
	v_cvt_pk_bf16_f32 v31, v31, v33
	v_cvt_pk_bf16_f32 v33, v98, v99
	v_cvt_pk_bf16_f32 v23, v23, v25
	v_cvt_pk_bf16_f32 v25, v90, v91
	v_cvt_pk_bf16_f32 v15, v15, v17
	v_cvt_pk_bf16_f32 v17, v82, v83
	ds_bpermute_b32 v124, v180, v123
	s_waitcnt lgkmcnt(13)
	v_add_f32_e32 v122, v66, v67
	v_mfma_f32_16x16x32_bf16 v[66:69], v[70:73], v[62:65], 0
	v_mfma_f32_16x16x32_bf16 v[70:73], v[70:73], v[58:61], 0
	v_mfma_f32_16x16x32_bf16 v[74:77], v[78:81], v[62:65], 0
	v_mfma_f32_16x16x32_bf16 v[78:81], v[78:81], v[58:61], 0
	s_waitcnt lgkmcnt(11)
	v_mfma_f32_16x16x32_bf16 v[82:85], v[86:89], v[62:65], 0
	v_mfma_f32_16x16x32_bf16 v[86:89], v[86:89], v[58:61], 0
	s_waitcnt lgkmcnt(9)
	v_mfma_f32_16x16x32_bf16 v[90:93], v[94:97], v[62:65], 0
	v_mfma_f32_16x16x32_bf16 v[94:97], v[94:97], v[58:61], 0
	s_waitcnt lgkmcnt(7)
	v_mfma_f32_16x16x32_bf16 v[98:101], v[102:105], v[62:65], 0
	v_mfma_f32_16x16x32_bf16 v[102:105], v[102:105], v[58:61], 0
	s_waitcnt lgkmcnt(5)
	v_mfma_f32_16x16x32_bf16 v[106:109], v[110:113], v[62:65], 0
	v_mfma_f32_16x16x32_bf16 v[110:113], v[110:113], v[58:61], 0
	s_waitcnt lgkmcnt(3)
	v_mfma_f32_16x16x32_bf16 v[114:117], v[118:121], v[62:65], 0
	v_mfma_f32_16x16x32_bf16 v[118:121], v[118:121], v[58:61], 0
	s_waitcnt lgkmcnt(1)
	v_mfma_f32_16x16x32_bf16 v[62:65], v[144:147], v[62:65], 0
	v_mfma_f32_16x16x32_bf16 v[58:61], v[144:147], v[58:61], 0
	ds_read_b64_tr_b16 v[146:147], v182 offset:13824
	ds_read_b64_tr_b16 v[144:145], v182 offset:9216
	ds_read_b64_tr_b16 v[148:149], v182 offset:9248
	ds_read_b64_tr_b16 v[150:151], v182 offset:13856
	s_waitcnt lgkmcnt(2)
	v_mfma_f32_16x16x32_bf16 v[66:69], v[144:147], v[50:53], v[66:69]
	v_mfma_f32_16x16x32_bf16 v[70:73], v[144:147], v[54:57], v[70:73]
	ds_read_b64_tr_b16 v[144:145], v182 offset:9280
	ds_read_b64_tr_b16 v[146:147], v182 offset:13888
	s_waitcnt lgkmcnt(0)
	v_mfma_f32_16x16x32_bf16 v[82:85], v[144:147], v[50:53], v[82:85]
	v_mfma_f32_16x16x32_bf16 v[86:89], v[144:147], v[54:57], v[86:89]
	ds_read_b64_tr_b16 v[144:145], v182 offset:9312
	ds_read_b64_tr_b16 v[146:147], v182 offset:13920
	s_waitcnt lgkmcnt(0)
	v_mfma_f32_16x16x32_bf16 v[90:93], v[144:147], v[50:53], v[90:93]
	v_mfma_f32_16x16x32_bf16 v[94:97], v[144:147], v[54:57], v[94:97]
	ds_read_b64_tr_b16 v[144:145], v182 offset:9344
	ds_read_b64_tr_b16 v[146:147], v182 offset:13952
	s_waitcnt lgkmcnt(0)
	v_mfma_f32_16x16x32_bf16 v[98:101], v[144:147], v[50:53], v[98:101]
	v_mfma_f32_16x16x32_bf16 v[102:105], v[144:147], v[54:57], v[102:105]
	ds_read_b64_tr_b16 v[144:145], v182 offset:9376
	ds_read_b64_tr_b16 v[146:147], v182 offset:13984
	s_waitcnt lgkmcnt(0)
	v_mfma_f32_16x16x32_bf16 v[106:109], v[144:147], v[50:53], v[106:109]
	v_mfma_f32_16x16x32_bf16 v[110:113], v[144:147], v[54:57], v[110:113]
	ds_read_b64_tr_b16 v[144:145], v182 offset:9408
	ds_read_b64_tr_b16 v[146:147], v182 offset:14016
	s_waitcnt lgkmcnt(0)
	v_mfma_f32_16x16x32_bf16 v[114:117], v[144:147], v[50:53], v[114:117]
	v_mfma_f32_16x16x32_bf16 v[118:121], v[144:147], v[54:57], v[118:121]
	ds_read_b64_tr_b16 v[144:145], v182 offset:9440
	ds_read_b64_tr_b16 v[146:147], v182 offset:14048
	v_mfma_f32_16x16x32_bf16 v[74:77], v[148:151], v[50:53], v[74:77]
	v_mfma_f32_16x16x32_bf16 v[78:81], v[148:151], v[54:57], v[78:81]
	s_waitcnt lgkmcnt(0)
	v_mfma_f32_16x16x32_bf16 v[50:53], v[144:147], v[50:53], v[62:65]
	v_mfma_f32_16x16x32_bf16 v[54:57], v[144:147], v[54:57], v[58:61]
	s_nop 2
	ds_read_b64_tr_b16 v[60:61], v182 offset:23040
	ds_read_b64_tr_b16 v[58:59], v182 offset:18432
	ds_read_b64_tr_b16 v[62:63], v182 offset:18464
	ds_read_b64_tr_b16 v[64:65], v182 offset:23072
	s_waitcnt lgkmcnt(2)
	v_mfma_f32_16x16x32_bf16 v[66:69], v[58:61], v[42:45], v[66:69]
	v_mfma_f32_16x16x32_bf16 v[58:61], v[58:61], v[46:49], v[70:73]
	s_waitcnt lgkmcnt(0)
	v_mfma_f32_16x16x32_bf16 v[70:73], v[62:65], v[42:45], v[74:77]
	s_nop 2
	ds_read_b64_tr_b16 v[74:75], v182 offset:18496
	ds_read_b64_tr_b16 v[76:77], v182 offset:23104
	v_mfma_f32_16x16x32_bf16 v[62:65], v[62:65], v[46:49], v[78:81]
	s_waitcnt lgkmcnt(0)
	v_mfma_f32_16x16x32_bf16 v[78:81], v[74:77], v[42:45], v[82:85]
	s_nop 2
	ds_read_b64_tr_b16 v[82:83], v182 offset:18528
	ds_read_b64_tr_b16 v[84:85], v182 offset:23136
	v_mfma_f32_16x16x32_bf16 v[74:77], v[74:77], v[46:49], v[86:89]
	s_waitcnt lgkmcnt(0)
	v_mfma_f32_16x16x32_bf16 v[86:89], v[82:85], v[42:45], v[90:93]
	s_nop 2
	ds_read_b64_tr_b16 v[90:91], v182 offset:18560
	ds_read_b64_tr_b16 v[92:93], v182 offset:23168
	v_mfma_f32_16x16x32_bf16 v[82:85], v[82:85], v[46:49], v[94:97]
	s_waitcnt lgkmcnt(0)
; #define LAS __attribute__((address_space(3)))
; #define MFMA16(a, b, c) __builtin_amdgcn_mfma_f32_16x16x32_bf16((a), (b), (c), 0, 0, 0)
; __device__ __forceinline__ s16x4 trread(const LAS unsigned char* p) { return __builtin_bit_cast(s16x4, __builtin_amdgcn_ds_read_tr16_b64_v4i16((LAS s16x4*)p)); }
; __device__ __forceinline__ bf16x8 cat8(s16x4 lo, s16x4 hi) { return (bf16x8){lo[0], lo[1], lo[2], lo[3], hi[0], hi[1], hi[2], hi[3]}; }
; __device__ __forceinline__ void mem_attn(const Params& P, int l, LAS unsigned char* lds, int item, int tid) {
;     ...
;         for (int s = 0; s < 8; ++s) { const LAS unsigned char* vp = VS + (32 * s + quad * 4 + (i >> 2)) * 288 + (4 * (i & 3)) * 2;
; #pragma unroll
;             for (int et = 0; et < 8; ++et) { const bf16x8 va = cat8(trread(vp + et * 32), trread(vp + et * 32 + 16 * 288)); oa[et] = MFMA16(va, pa[s], oa[et]); ob[et] = MFMA16(va, pbb[s], ob[et]); }
;             __builtin_amdgcn_sched_barrier(0); }
	v_mfma_f32_16x16x32_bf16 v[94:97], v[90:93], v[42:45], v[98:101]
	s_nop 2
	ds_read_b64_tr_b16 v[98:99], v182 offset:18592
	ds_read_b64_tr_b16 v[100:101], v182 offset:23200
	v_mfma_f32_16x16x32_bf16 v[90:93], v[90:93], v[46:49], v[102:105]
	s_waitcnt lgkmcnt(0)
	v_mfma_f32_16x16x32_bf16 v[102:105], v[98:101], v[42:45], v[106:109]
	s_nop 2
	ds_read_b64_tr_b16 v[106:107], v182 offset:18624
	ds_read_b64_tr_b16 v[108:109], v182 offset:23232
	v_mfma_f32_16x16x32_bf16 v[98:101], v[98:101], v[46:49], v[110:113]
	s_waitcnt lgkmcnt(0)
	v_mfma_f32_16x16x32_bf16 v[110:113], v[106:109], v[42:45], v[114:117]
	s_nop 2
	ds_read_b64_tr_b16 v[114:115], v182 offset:18656
	ds_read_b64_tr_b16 v[116:117], v182 offset:23264
	v_mfma_f32_16x16x32_bf16 v[106:109], v[106:109], v[46:49], v[118:121]
	s_waitcnt lgkmcnt(0)
	v_mfma_f32_16x16x32_bf16 v[42:45], v[114:117], v[42:45], v[50:53]
	v_mfma_f32_16x16x32_bf16 v[46:49], v[114:117], v[46:49], v[54:57]
	s_nop 1
	ds_read_b64_tr_b16 v[52:53], v182 offset:32256
	ds_read_b64_tr_b16 v[50:51], v182 offset:27648
	ds_read_b64_tr_b16 v[54:55], v182 offset:27680
	ds_read_b64_tr_b16 v[56:57], v182 offset:32288
	s_waitcnt lgkmcnt(2)
	v_mfma_f32_16x16x32_bf16 v[66:69], v[50:53], v[34:37], v[66:69]
	v_mfma_f32_16x16x32_bf16 v[50:53], v[50:53], v[38:41], v[58:61]
	s_waitcnt lgkmcnt(0)
	v_mfma_f32_16x16x32_bf16 v[58:61], v[54:57], v[34:37], v[70:73]
	v_mfma_f32_16x16x32_bf16 v[54:57], v[54:57], v[38:41], v[62:65]
	s_nop 2
	ds_read_b64_tr_b16 v[62:63], v182 offset:27712
	ds_read_b64_tr_b16 v[64:65], v182 offset:32320
	s_waitcnt lgkmcnt(0)
	v_mfma_f32_16x16x32_bf16 v[70:73], v[62:65], v[34:37], v[78:81]
	v_mfma_f32_16x16x32_bf16 v[62:65], v[62:65], v[38:41], v[74:77]
	s_nop 2
	ds_read_b64_tr_b16 v[74:75], v182 offset:27744
	ds_read_b64_tr_b16 v[76:77], v182 offset:32352
	s_waitcnt lgkmcnt(0)
	v_mfma_f32_16x16x32_bf16 v[78:81], v[74:77], v[34:37], v[86:89]
	v_mfma_f32_16x16x32_bf16 v[74:77], v[74:77], v[38:41], v[82:85]
	s_nop 2
	ds_read_b64_tr_b16 v[82:83], v182 offset:27776
	ds_read_b64_tr_b16 v[84:85], v182 offset:32384
	s_waitcnt lgkmcnt(0)
	v_mfma_f32_16x16x32_bf16 v[86:89], v[82:85], v[34:37], v[94:97]
	v_mfma_f32_16x16x32_bf16 v[82:85], v[82:85], v[38:41], v[90:93]
	s_nop 2
	ds_read_b64_tr_b16 v[90:91], v182 offset:27808
	ds_read_b64_tr_b16 v[92:93], v182 offset:32416
	s_waitcnt lgkmcnt(0)
	v_mfma_f32_16x16x32_bf16 v[94:97], v[90:93], v[34:37], v[102:105]
	v_mfma_f32_16x16x32_bf16 v[90:93], v[90:93], v[38:41], v[98:101]
	s_nop 2
	ds_read_b64_tr_b16 v[98:99], v182 offset:27840
	ds_read_b64_tr_b16 v[100:101], v182 offset:32448
	s_waitcnt lgkmcnt(0)
	v_mfma_f32_16x16x32_bf16 v[102:105], v[98:101], v[34:37], v[110:113]
	v_mfma_f32_16x16x32_bf16 v[98:101], v[98:101], v[38:41], v[106:109]
	s_nop 2
	ds_read_b64_tr_b16 v[106:107], v182 offset:27872
	ds_read_b64_tr_b16 v[108:109], v182 offset:32480
	s_waitcnt lgkmcnt(0)
	v_mfma_f32_16x16x32_bf16 v[34:37], v[106:109], v[34:37], v[42:45]
	v_mfma_f32_16x16x32_bf16 v[38:41], v[106:109], v[38:41], v[46:49]
	s_nop 1
	ds_read_b64_tr_b16 v[44:45], v182 offset:41472
	ds_read_b64_tr_b16 v[42:43], v182 offset:36864
	ds_read_b64_tr_b16 v[46:47], v182 offset:36896
	ds_read_b64_tr_b16 v[48:49], v182 offset:41504
	s_waitcnt lgkmcnt(2)
	v_mfma_f32_16x16x32_bf16 v[66:69], v[42:45], v[26:29], v[66:69]
	v_mfma_f32_16x16x32_bf16 v[42:45], v[42:45], v[30:33], v[50:53]
	s_waitcnt lgkmcnt(0)
	v_mfma_f32_16x16x32_bf16 v[50:53], v[46:49], v[26:29], v[58:61]
	v_mfma_f32_16x16x32_bf16 v[46:49], v[46:49], v[30:33], v[54:57]
	s_nop 2
	ds_read_b64_tr_b16 v[54:55], v182 offset:36928
	ds_read_b64_tr_b16 v[56:57], v182 offset:41536
	s_waitcnt lgkmcnt(0)
	v_mfma_f32_16x16x32_bf16 v[58:61], v[54:57], v[26:29], v[70:73]
	v_mfma_f32_16x16x32_bf16 v[54:57], v[54:57], v[30:33], v[62:65]
	s_nop 2
	ds_read_b64_tr_b16 v[62:63], v182 offset:36960
	ds_read_b64_tr_b16 v[64:65], v182 offset:41568
	s_waitcnt lgkmcnt(0)
	v_mfma_f32_16x16x32_bf16 v[70:73], v[62:65], v[26:29], v[78:81]
	v_mfma_f32_16x16x32_bf16 v[62:65], v[62:65], v[30:33], v[74:77]
	s_nop 2
	ds_read_b64_tr_b16 v[74:75], v182 offset:36992
	ds_read_b64_tr_b16 v[76:77], v182 offset:41600
	s_waitcnt lgkmcnt(0)
	v_mfma_f32_16x16x32_bf16 v[78:81], v[74:77], v[26:29], v[86:89]
	v_mfma_f32_16x16x32_bf16 v[74:77], v[74:77], v[30:33], v[82:85]
	s_nop 2
	ds_read_b64_tr_b16 v[82:83], v182 offset:37024
	ds_read_b64_tr_b16 v[84:85], v182 offset:41632
	s_waitcnt lgkmcnt(0)
	v_mfma_f32_16x16x32_bf16 v[86:89], v[82:85], v[26:29], v[94:97]
	v_mfma_f32_16x16x32_bf16 v[82:85], v[82:85], v[30:33], v[90:93]
	s_nop 2
	ds_read_b64_tr_b16 v[90:91], v182 offset:37056
	ds_read_b64_tr_b16 v[92:93], v182 offset:41664
	s_waitcnt lgkmcnt(0)
	v_mfma_f32_16x16x32_bf16 v[94:97], v[90:93], v[26:29], v[102:105]
	v_mfma_f32_16x16x32_bf16 v[90:93], v[90:93], v[30:33], v[98:101]
	s_nop 2
	ds_read_b64_tr_b16 v[98:99], v182 offset:37088
	ds_read_b64_tr_b16 v[100:101], v182 offset:41696
	s_waitcnt lgkmcnt(0)
	v_mfma_f32_16x16x32_bf16 v[26:29], v[98:101], v[26:29], v[34:37]
	v_mfma_f32_16x16x32_bf16 v[30:33], v[98:101], v[30:33], v[38:41]
	s_nop 1
	ds_read_b64_tr_b16 v[36:37], v182 offset:50688
	ds_read_b64_tr_b16 v[34:35], v182 offset:46080
	ds_read_b64_tr_b16 v[38:39], v182 offset:46112
	ds_read_b64_tr_b16 v[40:41], v182 offset:50720
	s_waitcnt lgkmcnt(2)
	v_mfma_f32_16x16x32_bf16 v[66:69], v[34:37], v[18:21], v[66:69]
	v_mfma_f32_16x16x32_bf16 v[34:37], v[34:37], v[22:25], v[42:45]
	s_waitcnt lgkmcnt(0)
	v_mfma_f32_16x16x32_bf16 v[42:45], v[38:41], v[18:21], v[50:53]
	v_mfma_f32_16x16x32_bf16 v[38:41], v[38:41], v[22:25], v[46:49]
	s_nop 2
	ds_read_b64_tr_b16 v[46:47], v182 offset:46144
	ds_read_b64_tr_b16 v[48:49], v182 offset:50752
	s_waitcnt lgkmcnt(0)
; #define LAS __attribute__((address_space(3)))
; #define MFMA16(a, b, c) __builtin_amdgcn_mfma_f32_16x16x32_bf16((a), (b), (c), 0, 0, 0)
; __device__ __forceinline__ s16x4 trread(const LAS unsigned char* p) { return __builtin_bit_cast(s16x4, __builtin_amdgcn_ds_read_tr16_b64_v4i16((LAS s16x4*)p)); }
; __device__ __forceinline__ bf16x8 cat8(s16x4 lo, s16x4 hi) { return (bf16x8){lo[0], lo[1], lo[2], lo[3], hi[0], hi[1], hi[2], hi[3]}; }
; __device__ __forceinline__ void mem_attn(const Params& P, int l, LAS unsigned char* lds, int item, int tid) {
;     ...
;         for (int s = 0; s < 8; ++s) { const LAS unsigned char* vp = VS + (32 * s + quad * 4 + (i >> 2)) * 288 + (4 * (i & 3)) * 2;
; #pragma unroll
;             for (int et = 0; et < 8; ++et) { const bf16x8 va = cat8(trread(vp + et * 32), trread(vp + et * 32 + 16 * 288)); oa[et] = MFMA16(va, pa[s], oa[et]); ob[et] = MFMA16(va, pbb[s], ob[et]); }
;             __builtin_amdgcn_sched_barrier(0); }
	v_mfma_f32_16x16x32_bf16 v[50:53], v[46:49], v[18:21], v[58:61]
	v_mfma_f32_16x16x32_bf16 v[46:49], v[46:49], v[22:25], v[54:57]
	s_nop 2
	ds_read_b64_tr_b16 v[54:55], v182 offset:46176
	ds_read_b64_tr_b16 v[56:57], v182 offset:50784
	s_waitcnt lgkmcnt(0)
	v_mfma_f32_16x16x32_bf16 v[58:61], v[54:57], v[18:21], v[70:73]
	v_mfma_f32_16x16x32_bf16 v[54:57], v[54:57], v[22:25], v[62:65]
	s_nop 2
	ds_read_b64_tr_b16 v[62:63], v182 offset:46208
	ds_read_b64_tr_b16 v[64:65], v182 offset:50816
	s_waitcnt lgkmcnt(0)
	v_mfma_f32_16x16x32_bf16 v[70:73], v[62:65], v[18:21], v[78:81]
	v_mfma_f32_16x16x32_bf16 v[62:65], v[62:65], v[22:25], v[74:77]
	s_nop 2
	ds_read_b64_tr_b16 v[74:75], v182 offset:46240
	ds_read_b64_tr_b16 v[76:77], v182 offset:50848
	s_waitcnt lgkmcnt(0)
	v_mfma_f32_16x16x32_bf16 v[78:81], v[74:77], v[18:21], v[86:89]
	v_mfma_f32_16x16x32_bf16 v[74:77], v[74:77], v[22:25], v[82:85]
	s_nop 2
	ds_read_b64_tr_b16 v[82:83], v182 offset:46272
	ds_read_b64_tr_b16 v[84:85], v182 offset:50880
	s_waitcnt lgkmcnt(0)
	v_mfma_f32_16x16x32_bf16 v[86:89], v[82:85], v[18:21], v[94:97]
	v_mfma_f32_16x16x32_bf16 v[82:85], v[82:85], v[22:25], v[90:93]
	s_nop 2
	ds_read_b64_tr_b16 v[90:91], v182 offset:46304
	ds_read_b64_tr_b16 v[92:93], v182 offset:50912
	s_waitcnt lgkmcnt(0)
	v_mfma_f32_16x16x32_bf16 v[18:21], v[90:93], v[18:21], v[26:29]
	v_mfma_f32_16x16x32_bf16 v[22:25], v[90:93], v[22:25], v[30:33]
	s_nop 1
	ds_read_b64_tr_b16 v[28:29], v182 offset:59904
	ds_read_b64_tr_b16 v[26:27], v182 offset:55296
	ds_read_b64_tr_b16 v[30:31], v182 offset:55328
	ds_read_b64_tr_b16 v[32:33], v182 offset:59936
	s_waitcnt lgkmcnt(2)
	v_mfma_f32_16x16x32_bf16 v[66:69], v[26:29], v[10:13], v[66:69]
	v_mfma_f32_16x16x32_bf16 v[26:29], v[26:29], v[14:17], v[34:37]
	s_waitcnt lgkmcnt(0)
	v_mfma_f32_16x16x32_bf16 v[34:37], v[30:33], v[10:13], v[42:45]
	v_mfma_f32_16x16x32_bf16 v[30:33], v[30:33], v[14:17], v[38:41]
	s_nop 2
	ds_read_b64_tr_b16 v[38:39], v182 offset:55360
	ds_read_b64_tr_b16 v[40:41], v182 offset:59968
	s_waitcnt lgkmcnt(0)
	v_mfma_f32_16x16x32_bf16 v[42:45], v[38:41], v[10:13], v[50:53]
	v_mfma_f32_16x16x32_bf16 v[38:41], v[38:41], v[14:17], v[46:49]
	s_nop 2
	ds_read_b64_tr_b16 v[46:47], v182 offset:55392
	ds_read_b64_tr_b16 v[48:49], v182 offset:60000
	ds_read_b64_tr_b16 v[50:51], v182 offset:55424
	ds_read_b64_tr_b16 v[52:53], v182 offset:60032
	s_waitcnt lgkmcnt(0)
	v_mfma_f32_16x16x32_bf16 v[70:73], v[50:53], v[10:13], v[70:73]
	v_mfma_f32_16x16x32_bf16 v[90:93], v[50:53], v[14:17], v[62:65]
	ds_read_b64_tr_b16 v[50:51], v182 offset:55456
	ds_read_b64_tr_b16 v[52:53], v182 offset:60064
	s_waitcnt lgkmcnt(0)
	v_mfma_f32_16x16x32_bf16 v[78:81], v[50:53], v[10:13], v[78:81]
	v_mfma_f32_16x16x32_bf16 v[74:77], v[50:53], v[14:17], v[74:77]
	ds_read_b64_tr_b16 v[50:51], v182 offset:55488
	ds_read_b64_tr_b16 v[52:53], v182 offset:60096
	s_waitcnt lgkmcnt(0)
	v_mfma_f32_16x16x32_bf16 v[86:89], v[50:53], v[10:13], v[86:89]
	v_mfma_f32_16x16x32_bf16 v[82:85], v[50:53], v[14:17], v[82:85]
	ds_read_b64_tr_b16 v[50:51], v182 offset:55520
	ds_read_b64_tr_b16 v[52:53], v182 offset:60128
	v_mfma_f32_16x16x32_bf16 v[58:61], v[46:49], v[10:13], v[58:61]
	v_mfma_f32_16x16x32_bf16 v[46:49], v[46:49], v[14:17], v[54:57]
	s_waitcnt lgkmcnt(0)
	v_mfma_f32_16x16x32_bf16 v[94:97], v[50:53], v[10:13], v[18:21]
	v_mfma_f32_16x16x32_bf16 v[98:101], v[50:53], v[14:17], v[22:25]
	ds_read_b64_tr_b16 v[12:13], v183
	ds_read_b64_tr_b16 v[10:11], v182 offset:64512
	ds_read_b64_tr_b16 v[14:15], v182 offset:64544
	ds_read_b64_tr_b16 v[16:17], v184
	s_waitcnt lgkmcnt(2)
	v_mfma_f32_16x16x32_bf16 v[62:65], v[10:13], v[2:5], v[66:69]
	v_mfma_f32_16x16x32_bf16 v[50:53], v[10:13], v[6:9], v[26:29]
	ds_read_b64_tr_b16 v[10:11], v182 offset:64576
	ds_read_b64_tr_b16 v[12:13], v185
	s_waitcnt lgkmcnt(0)
	v_mfma_f32_16x16x32_bf16 v[42:45], v[10:13], v[2:5], v[42:45]
	v_mfma_f32_16x16x32_bf16 v[22:25], v[10:13], v[6:9], v[38:41]
	ds_read_b64_tr_b16 v[10:11], v182 offset:64608
	ds_read_b64_tr_b16 v[12:13], v186
	s_waitcnt lgkmcnt(0)
	v_mfma_f32_16x16x32_bf16 v[66:69], v[10:13], v[2:5], v[58:61]
	v_mfma_f32_16x16x32_bf16 v[54:57], v[10:13], v[6:9], v[46:49]
	ds_read_b64_tr_b16 v[10:11], v182 offset:64640
	ds_read_b64_tr_b16 v[12:13], v187
	v_mfma_f32_16x16x32_bf16 v[34:37], v[14:17], v[2:5], v[34:37]
	v_mfma_f32_16x16x32_bf16 v[14:17], v[14:17], v[6:9], v[30:33]
	s_waitcnt lgkmcnt(0)
	v_mfma_f32_16x16x32_bf16 v[46:49], v[10:13], v[2:5], v[70:73]
	v_mfma_f32_16x16x32_bf16 v[30:33], v[10:13], v[6:9], v[90:93]
	ds_read_b64_tr_b16 v[10:11], v182 offset:64672
	ds_read_b64_tr_b16 v[12:13], v188
	s_waitcnt lgkmcnt(0)
	v_mfma_f32_16x16x32_bf16 v[38:41], v[10:13], v[2:5], v[78:81]
	v_mfma_f32_16x16x32_bf16 v[18:21], v[10:13], v[6:9], v[74:77]
	ds_read_b64_tr_b16 v[10:11], v182 offset:64704
	ds_read_b64_tr_b16 v[12:13], v189
	ds_read_b64_tr_b16 v[70:71], v182 offset:64736
	ds_read_b64_tr_b16 v[72:73], v190
	s_waitcnt lgkmcnt(2)
	v_mfma_f32_16x16x32_bf16 v[26:29], v[10:13], v[2:5], v[86:89]
	v_mfma_f32_16x16x32_bf16 v[10:13], v[10:13], v[6:9], v[82:85]
	s_waitcnt lgkmcnt(0)
; __device__ __forceinline__ float bf_lo(unsigned u) { return __uint_as_float(u << 16); }
; __device__ __forceinline__ float bf_hi(unsigned u) { return __uint_as_float(u & 0xffff0000u); }
; __device__ __forceinline__ unsigned pk2(float lo, float hi) { const f32x2c_t v = {lo, hi}; return __builtin_bit_cast(unsigned, __builtin_convertvector(v, bf16x2c_t)); }
; #define MFMA16(a, b, c) __builtin_amdgcn_mfma_f32_16x16x32_bf16((a), (b), (c), 0, 0, 0)
; __device__ __forceinline__ s16x4 trread(const LAS unsigned char* p) { return __builtin_bit_cast(s16x4, __builtin_amdgcn_ds_read_tr16_b64_v4i16((LAS s16x4*)p)); }
; __device__ __forceinline__ bf16x8 cat8(s16x4 lo, s16x4 hi) { return (bf16x8){lo[0], lo[1], lo[2], lo[3], hi[0], hi[1], hi[2], hi[3]}; }
; __device__ __forceinline__ void mem_attn(const Params& P, int l, LAS unsigned char* lds, int item, int tid) {
;     ...
;             for (int et = 0; et < 8; ++et) { const bf16x8 va = cat8(trread(vp + et * 32), trread(vp + et * 32 + 16 * 288)); oa[et] = MFMA16(va, pa[s], oa[et]); ob[et] = MFMA16(va, pbb[s], ob[et]); }
;             __builtin_amdgcn_sched_barrier(0); }
;         const float rla = 1.0f / lsa, rlb = 1.0f / lsb;
; #pragma unroll
;         for (int et = 0; et < 8; ++et) { const int e = et * 16 + quad * 4;
;             const v2u g0 = *(const v2u*)(z + tt0 * ZP + ZC_MG + h * 128 + e), g1 = *(const v2u*)(z + tt1 * ZP + ZC_MG + h * 128 + e);
;             v2u o; o.x = pk2(oa[et][0] * rla * bf_lo(g0.x), oa[et][1] * rla * bf_hi(g0.x)); o.y = pk2(oa[et][2] * rla * bf_lo(g0.y), oa[et][3] * rla * bf_hi(g0.y));
;             *(v2u*)(mix + tt0 * 2048 + 1536 + h * 128 + e) = o;
;             v2u o2; o2.x = pk2(ob[et][0] * rlb * bf_lo(g1.x), ob[et][1] * rlb * bf_hi(g1.x)); o2.y = pk2(ob[et][2] * rlb * bf_lo(g1.y), ob[et][3] * rlb * bf_hi(g1.y));
;             *(v2u*)(mix + tt1 * 2048 + 1536 + h * 128 + e) = o2; }
	v_mfma_f32_16x16x32_bf16 v[58:61], v[70:73], v[2:5], v[94:97]
	v_mfma_f32_16x16x32_bf16 v[2:5], v[70:73], v[6:9], v[98:101]
	v_div_scale_f32 v6, s[8:9], v122, v122, 1.0
	v_rcp_f32_e32 v8, v6
	v_add_f32_e32 v7, v123, v124
	v_mov_b32_e32 v173, v1
	v_lshl_add_u64 v[74:75], v[176:177], 0, v[172:173]
	v_fma_f32 v9, -v6, v8, 1.0
	v_fmac_f32_e32 v8, v9, v8
	v_div_scale_f32 v9, vcc, 1.0, v122, 1.0
	v_mul_f32_e32 v70, v9, v8
	v_fma_f32 v71, -v6, v70, v9
	v_fmac_f32_e32 v70, v71, v8
	v_fma_f32 v6, -v6, v70, v9
	v_div_fmas_f32 v6, v6, v8, v70
	v_div_scale_f32 v8, s[8:9], v7, v7, 1.0
	v_rcp_f32_e32 v9, v8
	s_mov_b64 s[8:9], 0x2c00
	v_lshl_add_u64 v[76:77], v[74:75], 0, s[8:9]
	s_mov_b64 s[8:9], 0x62c00
	v_fma_f32 v70, -v8, v9, 1.0
	v_fmac_f32_e32 v9, v70, v9
	v_div_scale_f32 v70, vcc, 1.0, v7, 1.0
	v_mul_f32_e32 v71, v70, v9
	v_fma_f32 v72, -v8, v71, v70
	v_fmac_f32_e32 v71, v72, v9
	v_fma_f32 v8, -v8, v71, v70
	v_div_fmas_f32 v8, v8, v9, v71
	v_add_co_u32_e32 v78, vcc, s42, v74
	s_mov_b32 s7, 0x62000
	s_nop 0
	v_addc_co_u32_e32 v79, vcc, 0, v75, vcc
	global_load_dwordx2 v[192:193], v[78:79], off offset:3072
	v_lshl_add_u64 v[80:81], v[74:75], 0, s[8:9]
	v_add_co_u32_e32 v74, vcc, s7, v74
	v_div_fixup_f32 v6, v6, v122, 1.0
	s_nop 0
	v_addc_co_u32_e32 v75, vcc, 0, v75, vcc
	global_load_dwordx2 v[194:195], v[74:75], off offset:3072
	global_load_dwordx2 v[196:197], v[76:77], off offset:32
	global_load_dwordx2 v[198:199], v[80:81], off offset:32
	global_load_dwordx2 v[200:201], v[76:77], off offset:64
	global_load_dwordx2 v[202:203], v[80:81], off offset:64
	global_load_dwordx2 v[204:205], v[76:77], off offset:96
	global_load_dwordx2 v[206:207], v[80:81], off offset:96
	global_load_dwordx2 v[208:209], v[76:77], off offset:128
	global_load_dwordx2 v[210:211], v[80:81], off offset:128
	global_load_dwordx2 v[212:213], v[76:77], off offset:160
	global_load_dwordx2 v[214:215], v[80:81], off offset:160
	global_load_dwordx2 v[216:217], v[76:77], off offset:192
	global_load_dwordx2 v[218:219], v[80:81], off offset:192
	global_load_dwordx2 v[220:221], v[76:77], off offset:224
	global_load_dwordx2 v[222:223], v[80:81], off offset:224
	v_pk_mul_f32 v[62:63], v[6:7], v[62:63] op_sel_hi:[0,1]
	v_pk_mul_f32 v[64:65], v[6:7], v[64:65] op_sel_hi:[0,1]
	v_lshlrev_b64 v[70:71], 12, v[174:175]
	v_div_fixup_f32 v8, v8, v7, 1.0
	v_pk_mul_f32 v[50:51], v[8:9], v[50:51] op_sel_hi:[0,1]
	v_pk_mul_f32 v[52:53], v[8:9], v[52:53] op_sel_hi:[0,1]
	v_or_b32_e32 v72, 0x10000, v70
	v_mov_b32_e32 v73, v71
	v_pk_mul_f32 v[34:35], v[6:7], v[34:35] op_sel_hi:[0,1]
	v_pk_mul_f32 v[36:37], v[6:7], v[36:37] op_sel_hi:[0,1]
	v_pk_mul_f32 v[14:15], v[8:9], v[14:15] op_sel_hi:[0,1]
	v_pk_mul_f32 v[16:17], v[8:9], v[16:17] op_sel_hi:[0,1]
	v_pk_mul_f32 v[10:11], v[8:9], v[10:11] op_sel_hi:[0,1]
	v_pk_mul_f32 v[12:13], v[8:9], v[12:13] op_sel_hi:[0,1]
	v_pk_mul_f32 v[2:3], v[8:9], v[2:3] op_sel_hi:[0,1]
	v_pk_mul_f32 v[4:5], v[8:9], v[4:5] op_sel_hi:[0,1]
	s_movk_i32 s7, 0x100
	s_and_b64 vcc, exec, s[0:1]
	s_mov_b64 s[0:1], 0
	s_waitcnt vmcnt(0)
	v_lshlrev_b32_e32 v82, 16, v192
	v_and_b32_e32 v83, 0xffff0000, v192
	v_lshlrev_b32_e32 v78, 16, v193
	v_and_b32_e32 v79, 0xffff0000, v193
	v_pk_mul_f32 v[62:63], v[62:63], v[82:83]
	v_pk_mul_f32 v[64:65], v[64:65], v[78:79]
	v_cvt_pk_bf16_f32 v192, v62, v63
	v_cvt_pk_bf16_f32 v193, v64, v65
	v_lshl_add_u64 v[64:65], v[126:127], 0, v[70:71]
	v_and_b32_e32 v232, 16, v234
	v_lshrrev_b32_e32 v233, 1, v232
	v_add_u32_e32 v232, v232, v233
	v_mov_b32_e32 v233, 0
	v_lshl_add_u64 v[64:65], v[64:65], 0, v[232:233]
	v_lshlrev_b32_e32 v62, 16, v194
	v_and_b32_e32 v63, 0xffff0000, v194
	v_pk_mul_f32 v[50:51], v[50:51], v[62:63]
	v_lshlrev_b32_e32 v62, 16, v195
	v_and_b32_e32 v63, 0xffff0000, v195
	v_pk_mul_f32 v[52:53], v[52:53], v[62:63]
	v_cvt_pk_bf16_f32 v224, v50, v51
	v_cvt_pk_bf16_f32 v225, v52, v53
	v_lshl_add_u64 v[52:53], v[126:127], 0, v[72:73]
	v_lshl_add_u64 v[52:53], v[52:53], 0, v[232:233]
	s_nop 0
	v_lshlrev_b32_e32 v70, 16, v196
	v_and_b32_e32 v71, 0xffff0000, v196
	v_lshlrev_b32_e32 v50, 16, v197
	v_and_b32_e32 v51, 0xffff0000, v197
	v_pk_mul_f32 v[34:35], v[34:35], v[70:71]
	v_pk_mul_f32 v[36:37], v[36:37], v[50:51]
	v_cvt_pk_bf16_f32 v194, v34, v35
	v_cvt_pk_bf16_f32 v195, v36, v37
	s_nop 1
	v_permlane16_swap_b32_e32 v192, v194
	v_permlane16_swap_b32_e32 v193, v195
	global_store_dwordx4 v[64:65], v[192:195], off offset:3072
	v_lshlrev_b32_e32 v34, 16, v198
	v_and_b32_e32 v35, 0xffff0000, v198
	v_pk_mul_f32 v[14:15], v[14:15], v[34:35]
	v_lshlrev_b32_e32 v34, 16, v199
	v_and_b32_e32 v35, 0xffff0000, v199
	v_pk_mul_f32 v[16:17], v[16:17], v[34:35]
	v_cvt_pk_bf16_f32 v226, v14, v15
	v_cvt_pk_bf16_f32 v227, v16, v17
	s_nop 1
	v_permlane16_swap_b32_e32 v224, v226
	v_permlane16_swap_b32_e32 v225, v227
	global_store_dwordx4 v[52:53], v[224:227], off offset:3072
	s_nop 0
	v_pk_mul_f32 v[34:35], v[6:7], v[42:43] op_sel_hi:[0,1]
	v_lshlrev_b32_e32 v36, 16, v200
	v_and_b32_e32 v37, 0xffff0000, v200
	v_pk_mul_f32 v[34:35], v[34:35], v[36:37]
	v_lshlrev_b32_e32 v36, 16, v201
	v_cvt_pk_bf16_f32 v200, v34, v35
	v_pk_mul_f32 v[34:35], v[6:7], v[44:45] op_sel_hi:[0,1]
	v_and_b32_e32 v37, 0xffff0000, v201
	v_pk_mul_f32 v[34:35], v[34:35], v[36:37]
	s_nop 0
	v_cvt_pk_bf16_f32 v201, v34, v35
	v_pk_mul_f32 v[14:15], v[8:9], v[22:23] op_sel_hi:[0,1]
; __device__ __forceinline__ float bf_lo(unsigned u) { return __uint_as_float(u << 16); }
; __device__ __forceinline__ float bf_hi(unsigned u) { return __uint_as_float(u & 0xffff0000u); }
; __device__ __forceinline__ unsigned pk2(float lo, float hi) { const f32x2c_t v = {lo, hi}; return __builtin_bit_cast(unsigned, __builtin_convertvector(v, bf16x2c_t)); }
; __device__ __forceinline__ void mem_attn(const Params& P, int l, LAS unsigned char* lds, int item, int tid) {
;     ...
;         const float rla = 1.0f / lsa, rlb = 1.0f / lsb;
; #pragma unroll
;         for (int et = 0; et < 8; ++et) { const int e = et * 16 + quad * 4;
;             const v2u g0 = *(const v2u*)(z + tt0 * ZP + ZC_MG + h * 128 + e), g1 = *(const v2u*)(z + tt1 * ZP + ZC_MG + h * 128 + e);
;             v2u o; o.x = pk2(oa[et][0] * rla * bf_lo(g0.x), oa[et][1] * rla * bf_hi(g0.x)); o.y = pk2(oa[et][2] * rla * bf_lo(g0.y), oa[et][3] * rla * bf_hi(g0.y));
;             *(v2u*)(mix + tt0 * 2048 + 1536 + h * 128 + e) = o;
;             v2u o2; o2.x = pk2(ob[et][0] * rlb * bf_lo(g1.x), ob[et][1] * rlb * bf_hi(g1.x)); o2.y = pk2(ob[et][2] * rlb * bf_lo(g1.y), ob[et][3] * rlb * bf_hi(g1.y));
;             *(v2u*)(mix + tt1 * 2048 + 1536 + h * 128 + e) = o2; }
;     }
	v_lshlrev_b32_e32 v22, 16, v202
	v_and_b32_e32 v23, 0xffff0000, v202
	v_pk_mul_f32 v[14:15], v[14:15], v[22:23]
	v_pk_mul_f32 v[22:23], v[8:9], v[24:25] op_sel_hi:[0,1]
	v_lshlrev_b32_e32 v16, 16, v203
	v_and_b32_e32 v17, 0xffff0000, v203
	v_pk_mul_f32 v[16:17], v[22:23], v[16:17]
	v_cvt_pk_bf16_f32 v224, v14, v15
	v_cvt_pk_bf16_f32 v225, v16, v17
	s_nop 0
	v_pk_mul_f32 v[22:23], v[6:7], v[66:67] op_sel_hi:[0,1]
	v_lshlrev_b32_e32 v24, 16, v204
	v_and_b32_e32 v25, 0xffff0000, v204
	v_pk_mul_f32 v[22:23], v[22:23], v[24:25]
	v_lshlrev_b32_e32 v24, 16, v205
	v_cvt_pk_bf16_f32 v202, v22, v23
	v_pk_mul_f32 v[22:23], v[6:7], v[68:69] op_sel_hi:[0,1]
	v_and_b32_e32 v25, 0xffff0000, v205
	v_pk_mul_f32 v[22:23], v[22:23], v[24:25]
	s_nop 0
	v_cvt_pk_bf16_f32 v203, v22, v23
	s_nop 1
	v_permlane16_swap_b32_e32 v200, v202
	v_permlane16_swap_b32_e32 v201, v203
	global_store_dwordx4 v[64:65], v[200:203], off offset:3136
	v_pk_mul_f32 v[14:15], v[8:9], v[54:55] op_sel_hi:[0,1]
	v_lshlrev_b32_e32 v22, 16, v206
	v_and_b32_e32 v23, 0xffff0000, v206
	v_pk_mul_f32 v[14:15], v[14:15], v[22:23]
	v_pk_mul_f32 v[22:23], v[8:9], v[56:57] op_sel_hi:[0,1]
	v_lshlrev_b32_e32 v16, 16, v207
	v_and_b32_e32 v17, 0xffff0000, v207
	v_pk_mul_f32 v[16:17], v[22:23], v[16:17]
	v_cvt_pk_bf16_f32 v226, v14, v15
	v_cvt_pk_bf16_f32 v227, v16, v17
	s_nop 1
	v_permlane16_swap_b32_e32 v224, v226
	v_permlane16_swap_b32_e32 v225, v227
	global_store_dwordx4 v[52:53], v[224:227], off offset:3136
	s_nop 0
	v_pk_mul_f32 v[22:23], v[6:7], v[46:47] op_sel_hi:[0,1]
	v_lshlrev_b32_e32 v24, 16, v208
	v_and_b32_e32 v25, 0xffff0000, v208
	v_pk_mul_f32 v[22:23], v[22:23], v[24:25]
	v_lshlrev_b32_e32 v24, 16, v209
	v_cvt_pk_bf16_f32 v208, v22, v23
	v_pk_mul_f32 v[22:23], v[6:7], v[48:49] op_sel_hi:[0,1]
	v_and_b32_e32 v25, 0xffff0000, v209
	v_pk_mul_f32 v[22:23], v[22:23], v[24:25]
	s_nop 0
	v_cvt_pk_bf16_f32 v209, v22, v23
	v_pk_mul_f32 v[14:15], v[8:9], v[30:31] op_sel_hi:[0,1]
	v_lshlrev_b32_e32 v22, 16, v210
	v_and_b32_e32 v23, 0xffff0000, v210
	v_pk_mul_f32 v[14:15], v[14:15], v[22:23]
	v_pk_mul_f32 v[22:23], v[8:9], v[32:33] op_sel_hi:[0,1]
	v_lshlrev_b32_e32 v16, 16, v211
	v_and_b32_e32 v17, 0xffff0000, v211
	v_pk_mul_f32 v[16:17], v[22:23], v[16:17]
	v_cvt_pk_bf16_f32 v224, v14, v15
	v_cvt_pk_bf16_f32 v225, v16, v17
	s_nop 0
	v_pk_mul_f32 v[22:23], v[6:7], v[38:39] op_sel_hi:[0,1]
	v_lshlrev_b32_e32 v24, 16, v212
	v_and_b32_e32 v25, 0xffff0000, v212
	v_pk_mul_f32 v[22:23], v[22:23], v[24:25]
	v_lshlrev_b32_e32 v24, 16, v213
	v_cvt_pk_bf16_f32 v210, v22, v23
	v_pk_mul_f32 v[22:23], v[6:7], v[40:41] op_sel_hi:[0,1]
	v_and_b32_e32 v25, 0xffff0000, v213
	v_pk_mul_f32 v[22:23], v[22:23], v[24:25]
	s_nop 0
	v_cvt_pk_bf16_f32 v211, v22, v23
	s_nop 1
	v_permlane16_swap_b32_e32 v208, v210
	v_permlane16_swap_b32_e32 v209, v211
	global_store_dwordx4 v[64:65], v[208:211], off offset:3200
	v_pk_mul_f32 v[14:15], v[8:9], v[18:19] op_sel_hi:[0,1]
	v_lshlrev_b32_e32 v18, 16, v214
	v_and_b32_e32 v19, 0xffff0000, v214
	v_pk_mul_f32 v[14:15], v[14:15], v[18:19]
	v_pk_mul_f32 v[18:19], v[8:9], v[20:21] op_sel_hi:[0,1]
	v_lshlrev_b32_e32 v16, 16, v215
	v_and_b32_e32 v17, 0xffff0000, v215
	v_pk_mul_f32 v[16:17], v[18:19], v[16:17]
	v_cvt_pk_bf16_f32 v226, v14, v15
	v_cvt_pk_bf16_f32 v227, v16, v17
	s_nop 1
	v_permlane16_swap_b32_e32 v224, v226
	v_permlane16_swap_b32_e32 v225, v227
	global_store_dwordx4 v[52:53], v[224:227], off offset:3200
	s_nop 0
	v_pk_mul_f32 v[18:19], v[6:7], v[26:27] op_sel_hi:[0,1]
	v_lshlrev_b32_e32 v20, 16, v216
	v_and_b32_e32 v21, 0xffff0000, v216
	v_pk_mul_f32 v[18:19], v[18:19], v[20:21]
	v_lshlrev_b32_e32 v20, 16, v217
	v_cvt_pk_bf16_f32 v216, v18, v19
	v_pk_mul_f32 v[18:19], v[6:7], v[28:29] op_sel_hi:[0,1]
	v_and_b32_e32 v21, 0xffff0000, v217
	v_pk_mul_f32 v[18:19], v[18:19], v[20:21]
	s_nop 0
	v_cvt_pk_bf16_f32 v217, v18, v19
	v_lshlrev_b32_e32 v14, 16, v218
	v_and_b32_e32 v15, 0xffff0000, v218
	v_pk_mul_f32 v[10:11], v[10:11], v[14:15]
	v_lshlrev_b32_e32 v14, 16, v219
	v_and_b32_e32 v15, 0xffff0000, v219
	v_pk_mul_f32 v[12:13], v[12:13], v[14:15]
	v_cvt_pk_bf16_f32 v224, v10, v11
	v_cvt_pk_bf16_f32 v225, v12, v13
	s_nop 0
	v_pk_mul_f32 v[14:15], v[6:7], v[58:59] op_sel_hi:[0,1]
	v_pk_mul_f32 v[6:7], v[6:7], v[60:61] op_sel_hi:[0,1]
	v_lshlrev_b32_e32 v16, 16, v220
	v_and_b32_e32 v17, 0xffff0000, v220
	v_pk_mul_f32 v[14:15], v[14:15], v[16:17]
	s_nop 0
	v_cvt_pk_bf16_f32 v218, v14, v15
	v_lshlrev_b32_e32 v14, 16, v221
	v_and_b32_e32 v15, 0xffff0000, v221
	v_pk_mul_f32 v[6:7], v[6:7], v[14:15]
	s_nop 0
	v_cvt_pk_bf16_f32 v219, v6, v7
	v_lshlrev_b32_e32 v6, 16, v222
	v_and_b32_e32 v7, 0xffff0000, v222
	v_pk_mul_f32 v[2:3], v[2:3], v[6:7]
	v_lshlrev_b32_e32 v6, 16, v223
	v_and_b32_e32 v7, 0xffff0000, v223
	v_pk_mul_f32 v[4:5], v[4:5], v[6:7]
	v_cvt_pk_bf16_f32 v226, v2, v3
	v_cvt_pk_bf16_f32 v227, v4, v5
	s_nop 1
	v_permlane16_swap_b32_e32 v216, v218
	v_permlane16_swap_b32_e32 v217, v219
	global_store_dwordx4 v[64:65], v[216:219], off offset:3264
	s_nop 1
	v_permlane16_swap_b32_e32 v224, v226
	v_permlane16_swap_b32_e32 v225, v227
	global_store_dwordx4 v[52:53], v[224:227], off offset:3264
	s_cbranch_vccnz .LBB0_415
	v_readlane_b32 s0, v253, 63
	s_add_i32 s6, s0, s6
	s_cmpk_gt_i32 s6, 0x7f
	s_cbranch_scc0 .LBB0_414

; __device__ __forceinline__ float bf_lo(unsigned u) { return __uint_as_float(u << 16); }
; __device__ __forceinline__ float bf_hi(unsigned u) { return __uint_as_float(u & 0xffff0000u); }
; __device__ __forceinline__ unsigned pk2(float lo, float hi) { const f32x2c_t v = {lo, hi}; return __builtin_bit_cast(unsigned, __builtin_convertvector(v, bf16x2c_t)); }
; __device__ __forceinline__ void gla_scan(const Params& P, int tid, int cu, int ncu) {
;     ...
;     for (int wk = cu * NTHR + tid; wk < half; wk += ncu * NTHR) {
;         const int wa = wk, wb = wk + half;
;         const int bha = wa >> 13, pa = wa & 8191, bhb = wb >> 13, pb = wb & 8191; const int da = (pa & 31) * 4, db = (pb & 31) * 4;
;         float a0 = 0.f, a1 = 0.f, a2 = 0.f, a3 = 0.f, b0 = 0.f, b1 = 0.f, b2 = 0.f, b3 = 0.f;
;         const size_t basea = (size_t)bha * 64 * 32768 + (size_t)pa * 4, baseb = (size_t)bhb * 64 * 32768 + (size_t)pb * 4;
; #pragma unroll 8
;         for (int n = 0; n < 64; ++n) {
;             const v2u ua = *(const v2u*)(Ut + basea + (size_t)n * 32768), ub = *(const v2u*)(Ut + baseb + (size_t)n * 32768);
;             const f32x4 dda = *(const f32x4*)(dv + (size_t)(bha * 64 + n) * 128 + da), ddb = *(const f32x4*)(dv + (size_t)(bhb * 64 + n) * 128 + db);
;             v2u oa, ob; oa.x = pk2(a0, a1); oa.y = pk2(a2, a3); ob.x = pk2(b0, b1); ob.y = pk2(b2, b3);
;             *(v2u*)(St + basea + (size_t)n * 32768) = oa; *(v2u*)(St + baseb + (size_t)n * 32768) = ob;
;             a0 = a0 * dda[0] + bf_lo(ua.x); a1 = a1 * dda[1] + bf_hi(ua.x); a2 = a2 * dda[2] + bf_lo(ua.y); a3 = a3 * dda[3] + bf_hi(ua.y);
;             b0 = b0 * ddb[0] + bf_lo(ub.x); b1 = b1 * ddb[1] + bf_hi(ub.x); b2 = b2 * ddb[2] + bf_lo(ub.y); b3 = b3 * ddb[3] + bf_hi(ub.y);
;         }
;     }
.Lscan_loop:
	v_cvt_pk_bf16_f32 v34, v18, v19
	v_cvt_pk_bf16_f32 v35, v20, v21
	v_cvt_pk_bf16_f32 v36, v22, v23
	v_cvt_pk_bf16_f32 v37, v24, v25
	global_store_dwordx2 v[14:15], v[34:35], off
	global_store_dwordx2 v[16:17], v[36:37], off
	v_lshl_add_u64 v[14:15], v[14:15], 0, s[8:9]
	v_lshl_add_u64 v[16:17], v[16:17], 0, s[8:9]
	s_waitcnt vmcnt(28)
	v_lshlrev_b32_e32 v32, 16, v48
	v_and_b32_e32 v33, 0xffff0000, v48
	v_pk_fma_f32 v[18:19], v[18:19], v[52:53], v[32:33]
	v_lshlrev_b32_e32 v32, 16, v49
	v_and_b32_e32 v33, 0xffff0000, v49
	v_pk_fma_f32 v[20:21], v[20:21], v[54:55], v[32:33]
	v_lshlrev_b32_e32 v32, 16, v50
	v_and_b32_e32 v33, 0xffff0000, v50
	v_pk_fma_f32 v[22:23], v[22:23], v[56:57], v[32:33]
	v_lshlrev_b32_e32 v32, 16, v51
	v_and_b32_e32 v33, 0xffff0000, v51
	v_pk_fma_f32 v[24:25], v[24:25], v[58:59], v[32:33]
	global_load_dwordx2 v[48:49], v[10:11], off
	global_load_dwordx2 v[50:51], v[12:13], off
	global_load_dwordx4 v[52:55], v[26:27], off
	global_load_dwordx4 v[56:59], v[30:31], off
	v_lshl_add_u64 v[10:11], v[10:11], 0, s[8:9]
	v_lshl_add_u64 v[12:13], v[12:13], 0, s[8:9]
	v_cvt_pk_bf16_f32 v34, v18, v19
	v_cvt_pk_bf16_f32 v35, v20, v21
	v_cvt_pk_bf16_f32 v36, v22, v23
	v_cvt_pk_bf16_f32 v37, v24, v25
	global_store_dwordx2 v[14:15], v[34:35], off
	global_store_dwordx2 v[16:17], v[36:37], off
	v_lshl_add_u64 v[14:15], v[14:15], 0, s[8:9]
	v_lshl_add_u64 v[16:17], v[16:17], 0, s[8:9]
	s_waitcnt vmcnt(28)
	v_lshlrev_b32_e32 v32, 16, v60
	v_and_b32_e32 v33, 0xffff0000, v60
	v_pk_fma_f32 v[18:19], v[18:19], v[64:65], v[32:33]
	v_lshlrev_b32_e32 v32, 16, v61
	v_and_b32_e32 v33, 0xffff0000, v61
	v_pk_fma_f32 v[20:21], v[20:21], v[66:67], v[32:33]
	v_lshlrev_b32_e32 v32, 16, v62
	v_and_b32_e32 v33, 0xffff0000, v62
	v_pk_fma_f32 v[22:23], v[22:23], v[68:69], v[32:33]
	v_lshlrev_b32_e32 v32, 16, v63
	v_and_b32_e32 v33, 0xffff0000, v63
	v_pk_fma_f32 v[24:25], v[24:25], v[70:71], v[32:33]
	global_load_dwordx2 v[60:61], v[10:11], off
	global_load_dwordx2 v[62:63], v[12:13], off
	global_load_dwordx4 v[64:67], v[26:27], off offset:512
	global_load_dwordx4 v[68:71], v[30:31], off offset:512
	v_lshl_add_u64 v[10:11], v[10:11], 0, s[8:9]
	v_lshl_add_u64 v[12:13], v[12:13], 0, s[8:9]
	v_cvt_pk_bf16_f32 v34, v18, v19
	v_cvt_pk_bf16_f32 v35, v20, v21
	v_cvt_pk_bf16_f32 v36, v22, v23
	v_cvt_pk_bf16_f32 v37, v24, v25
	global_store_dwordx2 v[14:15], v[34:35], off
	global_store_dwordx2 v[16:17], v[36:37], off
	v_lshl_add_u64 v[14:15], v[14:15], 0, s[8:9]
	v_lshl_add_u64 v[16:17], v[16:17], 0, s[8:9]
	s_waitcnt vmcnt(28)
	v_lshlrev_b32_e32 v32, 16, v72
	v_and_b32_e32 v33, 0xffff0000, v72
	v_pk_fma_f32 v[18:19], v[18:19], v[76:77], v[32:33]
	v_lshlrev_b32_e32 v32, 16, v73
	v_and_b32_e32 v33, 0xffff0000, v73
	v_pk_fma_f32 v[20:21], v[20:21], v[78:79], v[32:33]
	v_lshlrev_b32_e32 v32, 16, v74
	v_and_b32_e32 v33, 0xffff0000, v74
	v_pk_fma_f32 v[22:23], v[22:23], v[80:81], v[32:33]
	v_lshlrev_b32_e32 v32, 16, v75
	v_and_b32_e32 v33, 0xffff0000, v75
	v_pk_fma_f32 v[24:25], v[24:25], v[82:83], v[32:33]
	global_load_dwordx2 v[72:73], v[10:11], off
	global_load_dwordx2 v[74:75], v[12:13], off
	global_load_dwordx4 v[76:79], v[26:27], off offset:1024
	global_load_dwordx4 v[80:83], v[30:31], off offset:1024
	v_lshl_add_u64 v[10:11], v[10:11], 0, s[8:9]
	v_lshl_add_u64 v[12:13], v[12:13], 0, s[8:9]
	v_cvt_pk_bf16_f32 v34, v18, v19
	v_cvt_pk_bf16_f32 v35, v20, v21
	v_cvt_pk_bf16_f32 v36, v22, v23
	v_cvt_pk_bf16_f32 v37, v24, v25
	global_store_dwordx2 v[14:15], v[34:35], off
	global_store_dwordx2 v[16:17], v[36:37], off
	v_lshl_add_u64 v[14:15], v[14:15], 0, s[8:9]
	v_lshl_add_u64 v[16:17], v[16:17], 0, s[8:9]
	s_waitcnt vmcnt(28)
	v_lshlrev_b32_e32 v32, 16, v84
	v_and_b32_e32 v33, 0xffff0000, v84
	v_pk_fma_f32 v[18:19], v[18:19], v[88:89], v[32:33]
	v_lshlrev_b32_e32 v32, 16, v85
	v_and_b32_e32 v33, 0xffff0000, v85
	v_pk_fma_f32 v[20:21], v[20:21], v[90:91], v[32:33]
	v_lshlrev_b32_e32 v32, 16, v86
	v_and_b32_e32 v33, 0xffff0000, v86
	v_pk_fma_f32 v[22:23], v[22:23], v[92:93], v[32:33]
	v_lshlrev_b32_e32 v32, 16, v87
	v_and_b32_e32 v33, 0xffff0000, v87
	v_pk_fma_f32 v[24:25], v[24:25], v[94:95], v[32:33]
	global_load_dwordx2 v[84:85], v[10:11], off
	global_load_dwordx2 v[86:87], v[12:13], off
	global_load_dwordx4 v[88:91], v[26:27], off offset:1536
	global_load_dwordx4 v[92:95], v[30:31], off offset:1536
	v_lshl_add_u64 v[10:11], v[10:11], 0, s[8:9]
	v_lshl_add_u64 v[12:13], v[12:13], 0, s[8:9]
	v_cvt_pk_bf16_f32 v34, v18, v19
	v_cvt_pk_bf16_f32 v35, v20, v21
	v_cvt_pk_bf16_f32 v36, v22, v23
	v_cvt_pk_bf16_f32 v37, v24, v25
	global_store_dwordx2 v[14:15], v[34:35], off
	global_store_dwordx2 v[16:17], v[36:37], off
	v_lshl_add_u64 v[14:15], v[14:15], 0, s[8:9]
	v_lshl_add_u64 v[16:17], v[16:17], 0, s[8:9]
	s_waitcnt vmcnt(28)
; __device__ __forceinline__ float bf_lo(unsigned u) { return __uint_as_float(u << 16); }
; __device__ __forceinline__ float bf_hi(unsigned u) { return __uint_as_float(u & 0xffff0000u); }
; __device__ __forceinline__ unsigned pk2(float lo, float hi) { const f32x2c_t v = {lo, hi}; return __builtin_bit_cast(unsigned, __builtin_convertvector(v, bf16x2c_t)); }
; __device__ __forceinline__ void gla_scan(const Params& P, int tid, int cu, int ncu) {
;     ...
;     for (int wk = cu * NTHR + tid; wk < half; wk += ncu * NTHR) {
;         const int wa = wk, wb = wk + half;
;         const int bha = wa >> 13, pa = wa & 8191, bhb = wb >> 13, pb = wb & 8191; const int da = (pa & 31) * 4, db = (pb & 31) * 4;
;         float a0 = 0.f, a1 = 0.f, a2 = 0.f, a3 = 0.f, b0 = 0.f, b1 = 0.f, b2 = 0.f, b3 = 0.f;
;         const size_t basea = (size_t)bha * 64 * 32768 + (size_t)pa * 4, baseb = (size_t)bhb * 64 * 32768 + (size_t)pb * 4;
; #pragma unroll 8
;         for (int n = 0; n < 64; ++n) {
;             const v2u ua = *(const v2u*)(Ut + basea + (size_t)n * 32768), ub = *(const v2u*)(Ut + baseb + (size_t)n * 32768);
;             const f32x4 dda = *(const f32x4*)(dv + (size_t)(bha * 64 + n) * 128 + da), ddb = *(const f32x4*)(dv + (size_t)(bhb * 64 + n) * 128 + db);
;             v2u oa, ob; oa.x = pk2(a0, a1); oa.y = pk2(a2, a3); ob.x = pk2(b0, b1); ob.y = pk2(b2, b3);
;             *(v2u*)(St + basea + (size_t)n * 32768) = oa; *(v2u*)(St + baseb + (size_t)n * 32768) = ob;
;             a0 = a0 * dda[0] + bf_lo(ua.x); a1 = a1 * dda[1] + bf_hi(ua.x); a2 = a2 * dda[2] + bf_lo(ua.y); a3 = a3 * dda[3] + bf_hi(ua.y);
;             b0 = b0 * ddb[0] + bf_lo(ub.x); b1 = b1 * ddb[1] + bf_hi(ub.x); b2 = b2 * ddb[2] + bf_lo(ub.y); b3 = b3 * ddb[3] + bf_hi(ub.y);
;         }
;     }
	v_lshlrev_b32_e32 v32, 16, v96
	v_and_b32_e32 v33, 0xffff0000, v96
	v_pk_fma_f32 v[18:19], v[18:19], v[100:101], v[32:33]
	v_lshlrev_b32_e32 v32, 16, v97
	v_and_b32_e32 v33, 0xffff0000, v97
	v_pk_fma_f32 v[20:21], v[20:21], v[102:103], v[32:33]
	v_lshlrev_b32_e32 v32, 16, v98
	v_and_b32_e32 v33, 0xffff0000, v98
	v_pk_fma_f32 v[22:23], v[22:23], v[104:105], v[32:33]
	v_lshlrev_b32_e32 v32, 16, v99
	v_and_b32_e32 v33, 0xffff0000, v99
	v_pk_fma_f32 v[24:25], v[24:25], v[106:107], v[32:33]
	global_load_dwordx2 v[96:97], v[10:11], off
	global_load_dwordx2 v[98:99], v[12:13], off
	global_load_dwordx4 v[100:103], v[26:27], off offset:2048
	global_load_dwordx4 v[104:107], v[30:31], off offset:2048
	v_lshl_add_u64 v[10:11], v[10:11], 0, s[8:9]
	v_lshl_add_u64 v[12:13], v[12:13], 0, s[8:9]
	v_cvt_pk_bf16_f32 v34, v18, v19
	v_cvt_pk_bf16_f32 v35, v20, v21
	v_cvt_pk_bf16_f32 v36, v22, v23
	v_cvt_pk_bf16_f32 v37, v24, v25
	global_store_dwordx2 v[14:15], v[34:35], off
	global_store_dwordx2 v[16:17], v[36:37], off
	v_lshl_add_u64 v[14:15], v[14:15], 0, s[8:9]
	v_lshl_add_u64 v[16:17], v[16:17], 0, s[8:9]
	s_waitcnt vmcnt(28)
	v_lshlrev_b32_e32 v32, 16, v108
	v_and_b32_e32 v33, 0xffff0000, v108
	v_pk_fma_f32 v[18:19], v[18:19], v[112:113], v[32:33]
	v_lshlrev_b32_e32 v32, 16, v109
	v_and_b32_e32 v33, 0xffff0000, v109
	v_pk_fma_f32 v[20:21], v[20:21], v[114:115], v[32:33]
	v_lshlrev_b32_e32 v32, 16, v110
	v_and_b32_e32 v33, 0xffff0000, v110
	v_pk_fma_f32 v[22:23], v[22:23], v[116:117], v[32:33]
	v_lshlrev_b32_e32 v32, 16, v111
	v_and_b32_e32 v33, 0xffff0000, v111
	v_pk_fma_f32 v[24:25], v[24:25], v[118:119], v[32:33]
	global_load_dwordx2 v[108:109], v[10:11], off
	global_load_dwordx2 v[110:111], v[12:13], off
	global_load_dwordx4 v[112:115], v[26:27], off offset:2560
	global_load_dwordx4 v[116:119], v[30:31], off offset:2560
	v_lshl_add_u64 v[10:11], v[10:11], 0, s[8:9]
	v_lshl_add_u64 v[12:13], v[12:13], 0, s[8:9]
	v_cvt_pk_bf16_f32 v34, v18, v19
	v_cvt_pk_bf16_f32 v35, v20, v21
	v_cvt_pk_bf16_f32 v36, v22, v23
	v_cvt_pk_bf16_f32 v37, v24, v25
	global_store_dwordx2 v[14:15], v[34:35], off
	global_store_dwordx2 v[16:17], v[36:37], off
	v_lshl_add_u64 v[14:15], v[14:15], 0, s[8:9]
	v_lshl_add_u64 v[16:17], v[16:17], 0, s[8:9]
	s_waitcnt vmcnt(28)
	v_lshlrev_b32_e32 v32, 16, v144
	v_and_b32_e32 v33, 0xffff0000, v144
	v_pk_fma_f32 v[18:19], v[18:19], v[148:149], v[32:33]
	v_lshlrev_b32_e32 v32, 16, v145
	v_and_b32_e32 v33, 0xffff0000, v145
	v_pk_fma_f32 v[20:21], v[20:21], v[150:151], v[32:33]
	v_lshlrev_b32_e32 v32, 16, v146
	v_and_b32_e32 v33, 0xffff0000, v146
	v_pk_fma_f32 v[22:23], v[22:23], v[152:153], v[32:33]
	v_lshlrev_b32_e32 v32, 16, v147
	v_and_b32_e32 v33, 0xffff0000, v147
	v_pk_fma_f32 v[24:25], v[24:25], v[154:155], v[32:33]
	global_load_dwordx2 v[144:145], v[10:11], off
	global_load_dwordx2 v[146:147], v[12:13], off
	global_load_dwordx4 v[148:151], v[26:27], off offset:3072
	global_load_dwordx4 v[152:155], v[30:31], off offset:3072
	v_lshl_add_u64 v[10:11], v[10:11], 0, s[8:9]
	v_lshl_add_u64 v[12:13], v[12:13], 0, s[8:9]
	v_cvt_pk_bf16_f32 v34, v18, v19
	v_cvt_pk_bf16_f32 v35, v20, v21
	v_cvt_pk_bf16_f32 v36, v22, v23
	v_cvt_pk_bf16_f32 v37, v24, v25
	global_store_dwordx2 v[14:15], v[34:35], off
	global_store_dwordx2 v[16:17], v[36:37], off
	v_lshl_add_u64 v[14:15], v[14:15], 0, s[8:9]
	v_lshl_add_u64 v[16:17], v[16:17], 0, s[8:9]
	s_waitcnt vmcnt(28)
	v_lshlrev_b32_e32 v32, 16, v156
	v_and_b32_e32 v33, 0xffff0000, v156
	v_pk_fma_f32 v[18:19], v[18:19], v[160:161], v[32:33]
	v_lshlrev_b32_e32 v32, 16, v157
	v_and_b32_e32 v33, 0xffff0000, v157
	v_pk_fma_f32 v[20:21], v[20:21], v[162:163], v[32:33]
	v_lshlrev_b32_e32 v32, 16, v158
	v_and_b32_e32 v33, 0xffff0000, v158
	v_pk_fma_f32 v[22:23], v[22:23], v[164:165], v[32:33]
	v_lshlrev_b32_e32 v32, 16, v159
	v_and_b32_e32 v33, 0xffff0000, v159
	v_pk_fma_f32 v[24:25], v[24:25], v[166:167], v[32:33]
	global_load_dwordx2 v[156:157], v[10:11], off
	global_load_dwordx2 v[158:159], v[12:13], off
	global_load_dwordx4 v[160:163], v[26:27], off offset:3584
	global_load_dwordx4 v[164:167], v[30:31], off offset:3584
	v_lshl_add_u64 v[10:11], v[10:11], 0, s[8:9]
	v_lshl_add_u64 v[12:13], v[12:13], 0, s[8:9]
	v_lshl_add_u64 v[26:27], v[26:27], 0, s[96:97]
	v_lshl_add_u64 v[30:31], v[30:31], 0, s[96:97]
	s_add_i32 s4, s4, -1
	s_cmp_eq_u32 s4, 0
	s_cbranch_scc0 .Lscan_loop
	s_waitcnt vmcnt(0)
	v_readlane_b32 s4, v254, 5
	s_nop 1
	v_add_u32_e32 v28, s4, v28
	s_mov_b32 s4, 0xffff
	v_cmp_lt_i32_e32 vcc, s4, v28
	v_readlane_b32 s4, v255, 7
	s_or_b64 s[6:7], vcc, s[6:7]
	s_nop 0
	v_add_u32_e32 v29, s4, v29
	s_andn2_b64 exec, exec, s[6:7]
	s_cbranch_execnz .LBB0_450

;     __device__ __forceinline__ void operator()(f32x4 (&acc)[2][2][4][2], const Unit& u, int wr, int wc, int fr, int fq) const {
;         const int row0 = u.pm * BM + wr * 64 + fr, col0 = u.pn * BM + wc * 32 + 4 * fq;
; #pragma unroll
;         for (int ai = 0; ai < 2; ++ai)
; #pragma unroll
;             for (int m = 0; m < 4; ++m) { const int row = row0 + ai * HALF + m * 16; const size_t off = (size_t)row * 2048 + col0; float ss = 0.f;
; #pragma unroll
;                 for (int bj = 0; bj < 2; ++bj)
; #pragma unroll
;                     for (int n = 0; n < 2; ++n) { const f32x4 xo = *(const f32x4*)(Xin + off + bj * HALF + n * 16) + acc[ai][bj][m][n]; acc[ai][bj][m][n] = xo;
;                         if (!FINAL) *(f32x4*)(X + off + bj * HALF + n * 16) = xo;
;                         ss += (xo[0] * xo[0] + xo[1] * xo[1]) + (xo[2] * xo[2] + xo[3] * xo[3]); }
;                 ss += __shfl_xor(ss, 16); ss += __shfl_xor(ss, 32);
;                 if (fq == 0) atomicAdd(ssq + row, ss); }
.LBB0_913:
	v_lshl_add_u32 v154, s13, 8, v178
	v_lshl_or_b32 v156, s34, 8, v180
	v_ashrrev_i32_e32 v155, 31, v154
	v_ashrrev_i32_e32 v157, 31, v156
	v_lshlrev_b64 v[152:153], 11, v[154:155]
	v_lshl_add_u64 v[152:153], v[152:153], 0, v[156:157]
	v_lshlrev_b64 v[152:153], 2, v[152:153]
	v_lshl_add_u64 v[162:163], s[14:15], 0, v[152:153]
	global_load_dwordx4 v[158:161], v[162:163], off
	global_load_dwordx4 v[196:199], v[162:163], off offset:64
	global_load_dwordx4 v[200:203], v[162:163], off offset:512
	global_load_dwordx4 v[204:207], v[162:163], off offset:576
	v_lshl_add_u64 v[152:153], s[58:59], 0, v[152:153]
	s_waitcnt vmcnt(0)
	v_pk_add_f32 v[76:77], v[76:77], v[160:161]
	v_pk_add_f32 v[74:75], v[74:75], v[158:159]
	global_store_dwordx4 v[152:153], v[74:77], off
	v_mul_f32_e32 v164, v77, v77
	v_fmac_f32_e32 v164, v76, v76
	v_pk_add_f32 v[80:81], v[80:81], v[198:199]
	v_pk_add_f32 v[78:79], v[78:79], v[196:197]
	global_store_dwordx4 v[152:153], v[78:81], off offset:64
	v_mul_f32_e32 v165, v81, v81
	v_fmac_f32_e32 v165, v80, v80
	v_pk_add_f32 v[84:85], v[84:85], v[202:203]
	v_pk_add_f32 v[82:83], v[82:83], v[200:201]
	global_store_dwordx4 v[152:153], v[82:85], off offset:512
	v_and_b32_e32 v163, 64, v241
	v_xor_b32_e32 v162, 16, v241
	v_add_u32_e32 v163, 64, v163
	v_cmp_lt_i32_e32 vcc, v162, v163
	v_pk_add_f32 v[96:97], v[96:97], v[206:207]
	v_cndmask_b32_e32 v162, v241, v162, vcc
	v_lshlrev_b32_e32 v182, 2, v162
	v_mul_f32_e32 v162, v75, v75
	v_fmac_f32_e32 v162, v74, v74
	v_add_f32_e32 v162, v162, v164
	v_mul_f32_e32 v164, v79, v79
	v_fmac_f32_e32 v164, v78, v78
	v_add_f32_e32 v164, v164, v165
	v_add_f32_e32 v162, v162, v164
	v_mul_f32_e32 v164, v83, v83
	v_mul_f32_e32 v165, v85, v85
	v_pk_add_f32 v[94:95], v[94:95], v[204:205]
	v_fmac_f32_e32 v164, v82, v82
	v_fmac_f32_e32 v165, v84, v84
	v_mul_f32_e32 v158, v95, v95
	v_mul_f32_e32 v159, v97, v97
	v_add_f32_e32 v164, v164, v165
	v_fmac_f32_e32 v158, v94, v94
	v_fmac_f32_e32 v159, v96, v96
	v_add_f32_e32 v162, v162, v164
	v_add_f32_e32 v158, v158, v159
	v_add_f32_e32 v158, v162, v158
	ds_bpermute_b32 v159, v182, v158
	v_xor_b32_e32 v160, 32, v241
	v_cmp_lt_i32_e32 vcc, v160, v163
	global_store_dwordx4 v[152:153], v[94:97], off offset:576
	v_lshl_add_u64 v[152:153], v[154:155], 2, s[16:17]
	v_cndmask_b32_e32 v160, v241, v160, vcc
	v_lshlrev_b32_e32 v183, 2, v160
	s_waitcnt lgkmcnt(0)
	v_add_f32_e32 v158, v158, v159
	ds_bpermute_b32 v159, v183, v158
	s_and_saveexec_b64 s[0:1], s[4:5]
	s_mov_b32 s81, 0x2d400000
	s_cbranch_execz .LBB0_915
	s_waitcnt lgkmcnt(0)
	v_add_f32_e32 v158, v158, v159
	global_atomic_add_f32 v[152:153], v158, off
.LBB0_915:
	s_or_b64 exec, exec, s[0:1]
	v_or_b32_e32 v158, 16, v154
	s_waitcnt lgkmcnt(0)
	v_ashrrev_i32_e32 v159, 31, v158
	v_lshlrev_b64 v[160:161], 11, v[158:159]
	v_lshl_add_u64 v[160:161], v[160:161], 0, v[156:157]
	v_lshlrev_b64 v[164:165], 2, v[160:161]
	v_lshl_add_u64 v[166:167], s[14:15], 0, v[164:165]
	global_load_dwordx4 v[160:163], v[166:167], off
	global_load_dwordx4 v[196:199], v[166:167], off offset:64
	global_load_dwordx4 v[200:203], v[166:167], off offset:512
	global_load_dwordx4 v[204:207], v[166:167], off offset:576
	v_lshl_add_u64 v[164:165], s[58:59], 0, v[164:165]
	s_waitcnt vmcnt(0)
	v_pk_add_f32 v[104:105], v[104:105], v[162:163]
	v_pk_add_f32 v[102:103], v[102:103], v[160:161]
	global_store_dwordx4 v[164:165], v[102:105], off
	v_pk_add_f32 v[108:109], v[108:109], v[198:199]
	v_pk_add_f32 v[106:107], v[106:107], v[196:197]
	global_store_dwordx4 v[164:165], v[106:109], off offset:64
	v_mul_f32_e32 v168, v109, v109
	v_fmac_f32_e32 v168, v108, v108
	v_pk_add_f32 v[112:113], v[112:113], v[202:203]
	v_pk_add_f32 v[110:111], v[110:111], v[200:201]
	global_store_dwordx4 v[164:165], v[110:113], off offset:512
	v_mul_f32_e32 v166, v103, v103
	v_mul_f32_e32 v167, v105, v105
	v_fmac_f32_e32 v166, v102, v102
	v_fmac_f32_e32 v167, v104, v104
	v_add_f32_e32 v166, v166, v167
	v_mul_f32_e32 v167, v107, v107
	v_fmac_f32_e32 v167, v106, v106
	v_add_f32_e32 v167, v167, v168
	v_add_f32_e32 v166, v166, v167
	v_mul_f32_e32 v167, v111, v111
	v_mul_f32_e32 v168, v113, v113
	v_fmac_f32_e32 v167, v110, v110
	v_fmac_f32_e32 v168, v112, v112
	v_add_f32_e32 v167, v167, v168
	v_add_f32_e32 v166, v166, v167
	v_pk_add_f32 v[120:121], v[120:121], v[206:207]
	v_pk_add_f32 v[118:119], v[118:119], v[204:205]
	v_mul_f32_e32 v161, v121, v121
	v_mul_f32_e32 v160, v119, v119
	v_fmac_f32_e32 v160, v118, v118
	v_fmac_f32_e32 v161, v120, v120
	v_add_f32_e32 v160, v160, v161
	v_add_f32_e32 v160, v166, v160
	ds_bpermute_b32 v161, v182, v160
	v_lshl_add_u64 v[162:163], v[158:159], 2, s[16:17]
	global_store_dwordx4 v[164:165], v[118:121], off offset:576
	s_waitcnt lgkmcnt(0)
	v_add_f32_e32 v160, v160, v161
	ds_bpermute_b32 v161, v183, v160
	s_and_saveexec_b64 s[0:1], s[4:5]
	s_cbranch_execz .LBB0_917
	s_waitcnt lgkmcnt(0)
	v_add_f32_e32 v160, v160, v161
	global_atomic_add_f32 v[162:163], v160, off
;     __device__ __forceinline__ void operator()(f32x4 (&acc)[2][2][4][2], const Unit& u, int wr, int wc, int fr, int fq) const {
;     ...
;             for (int m = 0; m < 4; ++m) { const int row = row0 + ai * HALF + m * 16; const size_t off = (size_t)row * 2048 + col0; float ss = 0.f;
; #pragma unroll
;                 for (int bj = 0; bj < 2; ++bj)
; #pragma unroll
;                     for (int n = 0; n < 2; ++n) { const f32x4 xo = *(const f32x4*)(Xin + off + bj * HALF + n * 16) + acc[ai][bj][m][n]; acc[ai][bj][m][n] = xo;
;                         if (!FINAL) *(f32x4*)(X + off + bj * HALF + n * 16) = xo;
;                         ss += (xo[0] * xo[0] + xo[1] * xo[1]) + (xo[2] * xo[2] + xo[3] * xo[3]); }
;                 ss += __shfl_xor(ss, 16); ss += __shfl_xor(ss, 32);
;                 if (fq == 0) atomicAdd(ssq + row, ss); }
.LBB0_917:
	s_or_b64 exec, exec, s[0:1]
	v_or_b32_e32 v160, 32, v154
	s_waitcnt lgkmcnt(0)
	v_ashrrev_i32_e32 v161, 31, v160
	v_lshlrev_b64 v[164:165], 11, v[160:161]
	v_lshl_add_u64 v[164:165], v[164:165], 0, v[156:157]
	v_lshlrev_b64 v[168:169], 2, v[164:165]
	v_lshl_add_u64 v[170:171], s[14:15], 0, v[168:169]
	global_load_dwordx4 v[164:167], v[170:171], off
	global_load_dwordx4 v[196:199], v[170:171], off offset:64
	global_load_dwordx4 v[200:203], v[170:171], off offset:512
	global_load_dwordx4 v[204:207], v[170:171], off offset:576
	v_lshl_add_u64 v[168:169], s[58:59], 0, v[168:169]
	s_waitcnt vmcnt(0)
	v_pk_add_f32 v[124:125], v[124:125], v[166:167]
	v_pk_add_f32 v[122:123], v[122:123], v[164:165]
	global_store_dwordx4 v[168:169], v[122:125], off
	v_pk_add_f32 v[146:147], v[146:147], v[198:199]
	v_pk_add_f32 v[144:145], v[144:145], v[196:197]
	global_store_dwordx4 v[168:169], v[144:147], off offset:64
	v_mul_f32_e32 v172, v147, v147
	v_fmac_f32_e32 v172, v146, v146
	v_pk_add_f32 v[116:117], v[116:117], v[202:203]
	v_pk_add_f32 v[114:115], v[114:115], v[200:201]
	global_store_dwordx4 v[168:169], v[114:117], off offset:512
	v_mul_f32_e32 v170, v123, v123
	v_mul_f32_e32 v171, v125, v125
	v_fmac_f32_e32 v170, v122, v122
	v_fmac_f32_e32 v171, v124, v124
	v_add_f32_e32 v170, v170, v171
	v_mul_f32_e32 v171, v145, v145
	v_fmac_f32_e32 v171, v144, v144
	v_add_f32_e32 v171, v171, v172
	v_add_f32_e32 v170, v170, v171
	v_mul_f32_e32 v171, v115, v115
	v_mul_f32_e32 v172, v117, v117
	v_fmac_f32_e32 v171, v114, v114
	v_fmac_f32_e32 v172, v116, v116
	v_add_f32_e32 v171, v171, v172
	v_add_f32_e32 v170, v170, v171
	v_pk_add_f32 v[100:101], v[100:101], v[206:207]
	v_pk_add_f32 v[98:99], v[98:99], v[204:205]
	v_mul_f32_e32 v165, v101, v101
	v_mul_f32_e32 v164, v99, v99
	v_fmac_f32_e32 v164, v98, v98
	v_fmac_f32_e32 v165, v100, v100
	v_add_f32_e32 v164, v164, v165
	v_add_f32_e32 v164, v170, v164
	ds_bpermute_b32 v165, v182, v164
	v_lshl_add_u64 v[166:167], v[160:161], 2, s[16:17]
	global_store_dwordx4 v[168:169], v[98:101], off offset:576
	s_waitcnt lgkmcnt(0)
	v_add_f32_e32 v164, v164, v165
	ds_bpermute_b32 v165, v183, v164
	s_and_saveexec_b64 s[0:1], s[4:5]
	s_mov_b32 s91, 0xca00000
	s_cbranch_execz .LBB0_919
	s_waitcnt lgkmcnt(0)
	v_add_f32_e32 v164, v164, v165
	global_atomic_add_f32 v[166:167], v164, off
.LBB0_919:
	s_or_b64 exec, exec, s[0:1]
	v_or_b32_e32 v164, 48, v154
	s_waitcnt lgkmcnt(0)
	v_ashrrev_i32_e32 v165, 31, v164
	v_lshlrev_b64 v[168:169], 11, v[164:165]
	v_lshl_add_u64 v[168:169], v[168:169], 0, v[156:157]
	v_lshlrev_b64 v[172:173], 2, v[168:169]
	v_lshl_add_u64 v[174:175], s[14:15], 0, v[172:173]
	global_load_dwordx4 v[168:171], v[174:175], off
	global_load_dwordx4 v[196:199], v[174:175], off offset:64
	global_load_dwordx4 v[200:203], v[174:175], off offset:512
	global_load_dwordx4 v[204:207], v[174:175], off offset:576
	v_lshl_add_u64 v[172:173], s[58:59], 0, v[172:173]
	s_waitcnt vmcnt(0)
	v_pk_add_f32 v[92:93], v[92:93], v[170:171]
	v_pk_add_f32 v[90:91], v[90:91], v[168:169]
	global_store_dwordx4 v[172:173], v[90:93], off
	v_pk_add_f32 v[88:89], v[88:89], v[198:199]
	v_pk_add_f32 v[86:87], v[86:87], v[196:197]
	global_store_dwordx4 v[172:173], v[86:89], off offset:64
	v_mul_f32_e32 v176, v89, v89
	v_fmac_f32_e32 v176, v88, v88
	v_pk_add_f32 v[72:73], v[72:73], v[202:203]
	v_pk_add_f32 v[70:71], v[70:71], v[200:201]
	global_store_dwordx4 v[172:173], v[70:73], off offset:512
	v_mul_f32_e32 v174, v91, v91
	v_mul_f32_e32 v175, v93, v93
	v_fmac_f32_e32 v174, v90, v90
	v_fmac_f32_e32 v175, v92, v92
	v_add_f32_e32 v174, v174, v175
	v_mul_f32_e32 v175, v87, v87
	v_fmac_f32_e32 v175, v86, v86
	v_add_f32_e32 v175, v175, v176
	v_add_f32_e32 v174, v174, v175
	v_mul_f32_e32 v175, v71, v71
	v_mul_f32_e32 v176, v73, v73
	v_fmac_f32_e32 v175, v70, v70
	v_fmac_f32_e32 v176, v72, v72
	v_add_f32_e32 v175, v175, v176
	v_add_f32_e32 v174, v174, v175
	v_pk_add_f32 v[68:69], v[68:69], v[206:207]
	v_pk_add_f32 v[66:67], v[66:67], v[204:205]
	v_mul_f32_e32 v169, v69, v69
	v_mul_f32_e32 v168, v67, v67
	v_fmac_f32_e32 v168, v66, v66
	v_fmac_f32_e32 v169, v68, v68
	v_add_f32_e32 v168, v168, v169
	v_add_f32_e32 v168, v174, v168
	ds_bpermute_b32 v169, v182, v168
	v_lshl_add_u64 v[170:171], v[164:165], 2, s[16:17]
	global_store_dwordx4 v[172:173], v[66:69], off offset:576
	s_waitcnt lgkmcnt(0)
	v_add_f32_e32 v168, v168, v169
	ds_bpermute_b32 v169, v183, v168
	s_and_saveexec_b64 s[0:1], s[4:5]
	s_cbranch_execz .LBB0_921
	s_waitcnt lgkmcnt(0)
	v_add_f32_e32 v168, v168, v169
	global_atomic_add_f32 v[170:171], v168, off
;     __device__ __forceinline__ void operator()(f32x4 (&acc)[2][2][4][2], const Unit& u, int wr, int wc, int fr, int fq) const {
;     ...
;             for (int m = 0; m < 4; ++m) { const int row = row0 + ai * HALF + m * 16; const size_t off = (size_t)row * 2048 + col0; float ss = 0.f;
; #pragma unroll
;                 for (int bj = 0; bj < 2; ++bj)
; #pragma unroll
;                     for (int n = 0; n < 2; ++n) { const f32x4 xo = *(const f32x4*)(Xin + off + bj * HALF + n * 16) + acc[ai][bj][m][n]; acc[ai][bj][m][n] = xo;
;                         if (!FINAL) *(f32x4*)(X + off + bj * HALF + n * 16) = xo;
;                         ss += (xo[0] * xo[0] + xo[1] * xo[1]) + (xo[2] * xo[2] + xo[3] * xo[3]); }
;                 ss += __shfl_xor(ss, 16); ss += __shfl_xor(ss, 32);
;                 if (fq == 0) atomicAdd(ssq + row, ss); }
.LBB0_921:
	s_or_b64 exec, exec, s[0:1]
	v_add_u32_e32 v168, 0x80, v154
	s_waitcnt lgkmcnt(0)
	v_ashrrev_i32_e32 v169, 31, v168
	v_lshlrev_b64 v[172:173], 11, v[168:169]
	v_lshl_add_u64 v[172:173], v[172:173], 0, v[156:157]
	v_lshlrev_b64 v[176:177], 2, v[172:173]
	v_lshl_add_u64 v[184:185], s[14:15], 0, v[176:177]
	global_load_dwordx4 v[172:175], v[184:185], off
	global_load_dwordx4 v[196:199], v[184:185], off offset:64
	global_load_dwordx4 v[200:203], v[184:185], off offset:512
	global_load_dwordx4 v[204:207], v[184:185], off offset:576
	v_lshl_add_u64 v[176:177], s[58:59], 0, v[176:177]
	s_waitcnt vmcnt(0)
	v_pk_add_f32 v[64:65], v[64:65], v[174:175]
	v_pk_add_f32 v[62:63], v[62:63], v[172:173]
	global_store_dwordx4 v[176:177], v[62:65], off
	v_pk_add_f32 v[60:61], v[60:61], v[198:199]
	v_pk_add_f32 v[58:59], v[58:59], v[196:197]
	global_store_dwordx4 v[176:177], v[58:61], off offset:64
	v_mul_f32_e32 v186, v61, v61
	v_fmac_f32_e32 v186, v60, v60
	v_pk_add_f32 v[56:57], v[56:57], v[202:203]
	v_pk_add_f32 v[54:55], v[54:55], v[200:201]
	global_store_dwordx4 v[176:177], v[54:57], off offset:512
	v_mul_f32_e32 v184, v63, v63
	v_mul_f32_e32 v185, v65, v65
	v_fmac_f32_e32 v184, v62, v62
	v_fmac_f32_e32 v185, v64, v64
	v_add_f32_e32 v184, v184, v185
	v_mul_f32_e32 v185, v59, v59
	v_fmac_f32_e32 v185, v58, v58
	v_add_f32_e32 v185, v185, v186
	v_add_f32_e32 v184, v184, v185
	v_mul_f32_e32 v185, v55, v55
	v_mul_f32_e32 v186, v57, v57
	v_fmac_f32_e32 v185, v54, v54
	v_fmac_f32_e32 v186, v56, v56
	v_add_f32_e32 v185, v185, v186
	v_add_f32_e32 v184, v184, v185
	v_pk_add_f32 v[52:53], v[52:53], v[206:207]
	v_pk_add_f32 v[50:51], v[50:51], v[204:205]
	v_mul_f32_e32 v173, v53, v53
	v_mul_f32_e32 v172, v51, v51
	v_fmac_f32_e32 v172, v50, v50
	v_fmac_f32_e32 v173, v52, v52
	v_add_f32_e32 v172, v172, v173
	v_add_f32_e32 v172, v184, v172
	ds_bpermute_b32 v173, v182, v172
	global_store_dwordx4 v[176:177], v[50:53], off offset:576
	s_waitcnt lgkmcnt(0)
	v_add_f32_e32 v172, v172, v173
	ds_bpermute_b32 v173, v183, v172
	s_and_saveexec_b64 s[0:1], s[4:5]
	s_cbranch_execz .LBB0_923
	v_lshl_add_u64 v[174:175], v[168:169], 2, s[16:17]
	s_waitcnt lgkmcnt(0)
	v_add_f32_e32 v172, v172, v173
	global_atomic_add_f32 v[174:175], v172, off
.LBB0_923:
	s_or_b64 exec, exec, s[0:1]
	v_add_u32_e32 v172, 0x90, v154
	s_waitcnt lgkmcnt(0)
	v_ashrrev_i32_e32 v173, 31, v172
	v_lshlrev_b64 v[174:175], 11, v[172:173]
	v_lshl_add_u64 v[174:175], v[174:175], 0, v[156:157]
	v_lshlrev_b64 v[184:185], 2, v[174:175]
	v_lshl_add_u64 v[186:187], s[14:15], 0, v[184:185]
	global_load_dwordx4 v[174:177], v[186:187], off
	global_load_dwordx4 v[196:199], v[186:187], off offset:64
	global_load_dwordx4 v[200:203], v[186:187], off offset:512
	global_load_dwordx4 v[204:207], v[186:187], off offset:576
	v_lshl_add_u64 v[184:185], s[58:59], 0, v[184:185]
	s_waitcnt vmcnt(0)
	v_pk_add_f32 v[48:49], v[48:49], v[176:177]
	v_pk_add_f32 v[46:47], v[46:47], v[174:175]
	global_store_dwordx4 v[184:185], v[46:49], off
	v_pk_add_f32 v[44:45], v[44:45], v[198:199]
	v_pk_add_f32 v[42:43], v[42:43], v[196:197]
	global_store_dwordx4 v[184:185], v[42:45], off offset:64
	v_mul_f32_e32 v188, v45, v45
	v_fmac_f32_e32 v188, v44, v44
	v_pk_add_f32 v[40:41], v[40:41], v[202:203]
	v_pk_add_f32 v[38:39], v[38:39], v[200:201]
	global_store_dwordx4 v[184:185], v[38:41], off offset:512
	v_mul_f32_e32 v186, v47, v47
	v_mul_f32_e32 v187, v49, v49
	v_fmac_f32_e32 v186, v46, v46
	v_fmac_f32_e32 v187, v48, v48
	v_add_f32_e32 v186, v186, v187
	v_mul_f32_e32 v187, v43, v43
	v_fmac_f32_e32 v187, v42, v42
	v_add_f32_e32 v187, v187, v188
	v_add_f32_e32 v186, v186, v187
	v_mul_f32_e32 v187, v39, v39
	v_mul_f32_e32 v188, v41, v41
	v_fmac_f32_e32 v187, v38, v38
	v_fmac_f32_e32 v188, v40, v40
	v_add_f32_e32 v187, v187, v188
	v_add_f32_e32 v186, v186, v187
	v_pk_add_f32 v[36:37], v[36:37], v[206:207]
	v_pk_add_f32 v[34:35], v[34:35], v[204:205]
	v_mul_f32_e32 v175, v37, v37
	v_mul_f32_e32 v174, v35, v35
	v_fmac_f32_e32 v174, v34, v34
	v_fmac_f32_e32 v175, v36, v36
	v_add_f32_e32 v174, v174, v175
	v_add_f32_e32 v174, v186, v174
	ds_bpermute_b32 v175, v182, v174
	global_store_dwordx4 v[184:185], v[34:37], off offset:576
	s_waitcnt lgkmcnt(0)
	v_add_f32_e32 v174, v174, v175
	ds_bpermute_b32 v175, v183, v174
	s_and_saveexec_b64 s[0:1], s[4:5]
	s_cbranch_execz .LBB0_925
	v_lshl_add_u64 v[176:177], v[172:173], 2, s[16:17]
	s_waitcnt lgkmcnt(0)
	v_add_f32_e32 v174, v174, v175
	global_atomic_add_f32 v[176:177], v174, off
;     __device__ __forceinline__ void operator()(f32x4 (&acc)[2][2][4][2], const Unit& u, int wr, int wc, int fr, int fq) const {
;     ...
;             for (int m = 0; m < 4; ++m) { const int row = row0 + ai * HALF + m * 16; const size_t off = (size_t)row * 2048 + col0; float ss = 0.f;
; #pragma unroll
;                 for (int bj = 0; bj < 2; ++bj)
; #pragma unroll
;                     for (int n = 0; n < 2; ++n) { const f32x4 xo = *(const f32x4*)(Xin + off + bj * HALF + n * 16) + acc[ai][bj][m][n]; acc[ai][bj][m][n] = xo;
;                         if (!FINAL) *(f32x4*)(X + off + bj * HALF + n * 16) = xo;
;                         ss += (xo[0] * xo[0] + xo[1] * xo[1]) + (xo[2] * xo[2] + xo[3] * xo[3]); }
;                 ss += __shfl_xor(ss, 16); ss += __shfl_xor(ss, 32);
;                 if (fq == 0) atomicAdd(ssq + row, ss); }
.LBB0_925:
	s_or_b64 exec, exec, s[0:1]
	v_add_u32_e32 v174, 0xa0, v154
	s_waitcnt lgkmcnt(0)
	v_ashrrev_i32_e32 v175, 31, v174
	v_lshlrev_b64 v[176:177], 11, v[174:175]
	v_lshl_add_u64 v[176:177], v[176:177], 0, v[156:157]
	v_lshlrev_b64 v[176:177], 2, v[176:177]
	v_lshl_add_u64 v[188:189], s[14:15], 0, v[176:177]
	global_load_dwordx4 v[184:187], v[188:189], off
	global_load_dwordx4 v[196:199], v[188:189], off offset:64
	global_load_dwordx4 v[200:203], v[188:189], off offset:512
	global_load_dwordx4 v[204:207], v[188:189], off offset:576
	v_lshl_add_u64 v[190:191], s[58:59], 0, v[176:177]
	s_waitcnt vmcnt(0)
	v_pk_add_f32 v[32:33], v[32:33], v[186:187]
	v_pk_add_f32 v[30:31], v[30:31], v[184:185]
	global_store_dwordx4 v[190:191], v[30:33], off
	v_mul_f32_e32 v176, v31, v31
	v_mul_f32_e32 v177, v33, v33
	v_fmac_f32_e32 v176, v30, v30
	v_fmac_f32_e32 v177, v32, v32
	v_add_f32_e32 v176, v176, v177
	v_pk_add_f32 v[28:29], v[28:29], v[198:199]
	v_pk_add_f32 v[26:27], v[26:27], v[196:197]
	global_store_dwordx4 v[190:191], v[26:29], off offset:64
	v_mul_f32_e32 v177, v27, v27
	v_fmac_f32_e32 v177, v26, v26
	v_pk_add_f32 v[24:25], v[24:25], v[202:203]
	v_pk_add_f32 v[22:23], v[22:23], v[200:201]
	global_store_dwordx4 v[190:191], v[22:25], off offset:512
	v_mul_f32_e32 v188, v29, v29
	v_fmac_f32_e32 v188, v28, v28
	v_add_f32_e32 v177, v177, v188
	v_add_f32_e32 v176, v176, v177
	v_mul_f32_e32 v177, v23, v23
	v_mul_f32_e32 v188, v25, v25
	v_fmac_f32_e32 v177, v22, v22
	v_fmac_f32_e32 v188, v24, v24
	v_add_f32_e32 v177, v177, v188
	v_add_f32_e32 v176, v176, v177
	v_pk_add_f32 v[20:21], v[20:21], v[206:207]
	v_pk_add_f32 v[18:19], v[18:19], v[204:205]
	v_mul_f32_e32 v184, v21, v21
	v_mul_f32_e32 v177, v19, v19
	v_fmac_f32_e32 v177, v18, v18
	v_fmac_f32_e32 v184, v20, v20
	v_add_f32_e32 v177, v177, v184
	v_add_f32_e32 v176, v176, v177
	ds_bpermute_b32 v177, v182, v176
	global_store_dwordx4 v[190:191], v[18:21], off offset:576
	s_waitcnt lgkmcnt(0)
	v_add_f32_e32 v176, v176, v177
	ds_bpermute_b32 v177, v183, v176
	s_and_saveexec_b64 s[0:1], s[4:5]
	s_cbranch_execz .LBB0_927
	v_lshl_add_u64 v[184:185], v[174:175], 2, s[16:17]
	s_waitcnt lgkmcnt(0)
	v_add_f32_e32 v176, v176, v177
	global_atomic_add_f32 v[184:185], v176, off
.LBB0_927:
	s_or_b64 exec, exec, s[0:1]
	v_add_u32_e32 v176, 0xb0, v154
	s_waitcnt lgkmcnt(0)
	v_ashrrev_i32_e32 v177, 31, v176
	v_lshlrev_b64 v[184:185], 11, v[176:177]
	v_lshl_add_u64 v[184:185], v[184:185], 0, v[156:157]
	v_lshlrev_b64 v[188:189], 2, v[184:185]
	v_lshl_add_u64 v[190:191], s[14:15], 0, v[188:189]
	global_load_dwordx4 v[184:187], v[190:191], off
	global_load_dwordx4 v[196:199], v[190:191], off offset:64
	global_load_dwordx4 v[200:203], v[190:191], off offset:512
	global_load_dwordx4 v[204:207], v[190:191], off offset:576
	v_lshl_add_u64 v[188:189], s[58:59], 0, v[188:189]
	s_waitcnt vmcnt(0)
	v_pk_add_f32 v[16:17], v[16:17], v[186:187]
	v_pk_add_f32 v[14:15], v[14:15], v[184:185]
	global_store_dwordx4 v[188:189], v[14:17], off
	v_pk_add_f32 v[12:13], v[12:13], v[198:199]
	v_pk_add_f32 v[10:11], v[10:11], v[196:197]
	global_store_dwordx4 v[188:189], v[10:13], off offset:64
	v_mul_f32_e32 v192, v13, v13
	v_fmac_f32_e32 v192, v12, v12
	v_pk_add_f32 v[8:9], v[8:9], v[202:203]
	v_pk_add_f32 v[6:7], v[6:7], v[200:201]
	global_store_dwordx4 v[188:189], v[6:9], off offset:512
	v_mul_f32_e32 v190, v15, v15
	v_mul_f32_e32 v191, v17, v17
	v_fmac_f32_e32 v190, v14, v14
	v_fmac_f32_e32 v191, v16, v16
	v_add_f32_e32 v190, v190, v191
	v_mul_f32_e32 v191, v11, v11
	v_fmac_f32_e32 v191, v10, v10
	v_add_f32_e32 v191, v191, v192
	v_add_f32_e32 v190, v190, v191
	v_mul_f32_e32 v191, v7, v7
	v_mul_f32_e32 v192, v9, v9
	v_fmac_f32_e32 v191, v6, v6
	v_fmac_f32_e32 v192, v8, v8
	v_add_f32_e32 v191, v191, v192
	v_add_f32_e32 v190, v190, v191
	v_pk_add_f32 v[4:5], v[4:5], v[206:207]
	v_pk_add_f32 v[2:3], v[2:3], v[204:205]
	v_mul_f32_e32 v185, v5, v5
	v_mul_f32_e32 v184, v3, v3
	v_fmac_f32_e32 v184, v2, v2
	v_fmac_f32_e32 v185, v4, v4
	v_add_f32_e32 v184, v184, v185
	v_add_f32_e32 v184, v190, v184
	ds_bpermute_b32 v182, v182, v184
	global_store_dwordx4 v[188:189], v[2:5], off offset:576
	s_waitcnt lgkmcnt(0)
	v_add_f32_e32 v182, v184, v182
	ds_bpermute_b32 v183, v183, v182
	s_and_saveexec_b64 s[0:1], s[4:5]
	s_cbranch_execz .LBB0_929
	v_lshl_add_u64 v[184:185], v[176:177], 2, s[16:17]
	s_waitcnt lgkmcnt(0)
	v_add_f32_e32 v182, v182, v183
	global_atomic_add_f32 v[184:185], v182, off

; __device__ __forceinline__ unsigned cvt_pk_bf16(float lo, float hi) { const f32x2e_t v = {lo, hi}; return __builtin_bit_cast(unsigned, __builtin_convertvector(v, bf16x2e_t)); }
;     __device__ __forceinline__ void operator()(f32x4 (&acc)[2][2][4][2], const Unit& u, int wr, int wc, int fr, int fq) const {
;     ...
;         asm volatile("s_waitcnt vmcnt(0)" ::: "memory");
;         __builtin_amdgcn_s_barrier();
;         if (threadIdx.x == 0) { unsigned* c = cnt + 64 * u.pm; __hip_atomic_fetch_add(c, 1u, __ATOMIC_RELAXED, __HIP_MEMORY_SCOPE_AGENT);
;             unsigned sp = 0; while (__hip_atomic_load(c, __ATOMIC_RELAXED, __HIP_MEMORY_SCOPE_AGENT) < 8u && ++sp < (1u << 22)) __builtin_amdgcn_s_sleep(2);
;             __builtin_amdgcn_fence(__ATOMIC_ACQUIRE, "agent"); }
;         asm volatile("s_waitcnt vmcnt(0) lgkmcnt(0)" ::: "memory");
;         __builtin_amdgcn_s_barrier();
;         asm volatile("" ::: "memory");
;         f32x4 gv[2][2];
;         if (FINAL) {
; #pragma unroll
;             for (int bj = 0; bj < 2; ++bj)
; #pragma unroll
;                 for (int n = 0; n < 2; ++n) gv[bj][n] = *(const f32x4*)(fgain + col0 + bj * HALF + n * 16); }
; #pragma unroll
;         for (int ai = 0; ai < 2; ++ai)
; #pragma unroll
;             for (int m = 0; m < 4; ++m) { const int row = row0 + ai * HALF + m * 16; const size_t off = (size_t)row * 2048 + col0;
;                 const float r = rsqrtf(__hip_atomic_load(ssq + row, __ATOMIC_RELAXED, __HIP_MEMORY_SCOPE_AGENT) * (1.0f / 2048.0f) + 1e-6f);
; #pragma unroll
;                 for (int bj = 0; bj < 2; ++bj)
; #pragma unroll
;                     for (int n = 0; n < 2; ++n) { const f32x4 xo = acc[ai][bj][m][n] * r;
;                         if (FINAL) *(f32x4*)(X + off + bj * HALF + n * 16) = xo * gv[bj][n];
;                         else { unsigned long long w = (unsigned long long)cvt_pk_bf16(xo[0], xo[1]) | ((unsigned long long)cvt_pk_bf16(xo[2], xo[3]) << 32); *(unsigned long long*)(XB + off + bj * HALF + n * 16) = w; } } }
.LBB0_944:
	s_or_b64 exec, exec, s[0:1]
	s_waitcnt vmcnt(0) lgkmcnt(0)
	s_barrier
	global_load_dword v208, v[152:153], off sc1
	global_load_dword v209, v[162:163], off sc1
	global_load_dword v210, v[166:167], off sc1
	global_load_dword v211, v[170:171], off sc1
	global_load_dword v212, v[152:153], off offset:512 sc1
	global_load_dword v213, v[152:153], off offset:576 sc1
	global_load_dword v214, v[152:153], off offset:640 sc1
	global_load_dword v215, v[152:153], off offset:704 sc1
	v_lshl_add_u64 v[156:157], v[156:157], 1, s[44:45]
	v_and_b32_e32 v216, 16, v234
	v_lshrrev_b32_e32 v217, 1, v216
	v_add_u32_e32 v216, v216, v217
	v_mov_b32_e32 v217, 0
	v_lshl_add_u64 v[156:157], v[156:157], 0, v[216:217]
	v_lshlrev_b64 v[154:155], 12, v[154:155]
	v_lshl_add_u64 v[154:155], v[156:157], 0, v[154:155]
	s_waitcnt vmcnt(0)
	v_fmamk_f32 v182, v208, 0x3a000000, v239
	s_waitcnt lgkmcnt(0)
	v_mul_f32_e32 v183, 0x4b800000, v182
	v_cmp_gt_f32_e32 vcc, s74, v182
	s_nop 1
	v_cndmask_b32_e32 v182, v182, v183, vcc
	v_rsq_f32_e32 v182, v182
	s_nop 0
	v_mul_f32_e32 v183, 0x45800000, v182
	v_cndmask_b32_e32 v182, v182, v183, vcc
	v_pk_mul_f32 v[76:77], v[76:77], v[182:183] op_sel_hi:[1,0]
	v_pk_mul_f32 v[74:75], v[74:75], v[182:183] op_sel_hi:[1,0]
	v_pk_mul_f32 v[80:81], v[80:81], v[182:183] op_sel_hi:[1,0]
	v_pk_mul_f32 v[78:79], v[78:79], v[182:183] op_sel_hi:[1,0]
	v_pk_mul_f32 v[84:85], v[84:85], v[182:183] op_sel_hi:[1,0]
	v_pk_mul_f32 v[82:83], v[82:83], v[182:183] op_sel_hi:[1,0]
	v_pk_mul_f32 v[96:97], v[96:97], v[182:183] op_sel_hi:[1,0]
	v_pk_mul_f32 v[94:95], v[94:95], v[182:183] op_sel_hi:[1,0]
	v_cvt_pk_bf16_f32 v196, v74, v75
	v_cvt_pk_bf16_f32 v197, v76, v77
	v_cvt_pk_bf16_f32 v198, v78, v79
	v_cvt_pk_bf16_f32 v199, v80, v81
	v_cvt_pk_bf16_f32 v200, v82, v83
	v_cvt_pk_bf16_f32 v201, v84, v85
	v_cvt_pk_bf16_f32 v202, v94, v95
	v_cvt_pk_bf16_f32 v203, v96, v97
	s_nop 1
	v_permlane16_swap_b32_e32 v196, v198
	v_permlane16_swap_b32_e32 v197, v199
	v_permlane16_swap_b32_e32 v200, v202
	v_permlane16_swap_b32_e32 v201, v203
	global_store_dwordx4 v[154:155], v[196:199], off
	global_store_dwordx4 v[154:155], v[200:203], off offset:256
	v_fmamk_f32 v74, v209, 0x3a000000, v239
	v_mul_f32_e32 v75, 0x4b800000, v74
	v_cmp_gt_f32_e32 vcc, s74, v74
	s_nop 1
	v_cndmask_b32_e32 v74, v74, v75, vcc
	v_rsq_f32_e32 v76, v74
	v_lshlrev_b64 v[74:75], 12, v[158:159]
	v_lshl_add_u64 v[74:75], v[156:157], 0, v[74:75]
	v_mul_f32_e32 v77, 0x45800000, v76
	v_cndmask_b32_e32 v76, v76, v77, vcc
	v_pk_mul_f32 v[78:79], v[104:105], v[76:77] op_sel_hi:[1,0]
	v_pk_mul_f32 v[80:81], v[102:103], v[76:77] op_sel_hi:[1,0]
	v_pk_mul_f32 v[82:83], v[108:109], v[76:77] op_sel_hi:[1,0]
	v_pk_mul_f32 v[84:85], v[106:107], v[76:77] op_sel_hi:[1,0]
	v_pk_mul_f32 v[94:95], v[112:113], v[76:77] op_sel_hi:[1,0]
	v_pk_mul_f32 v[96:97], v[110:111], v[76:77] op_sel_hi:[1,0]
	v_pk_mul_f32 v[102:103], v[120:121], v[76:77] op_sel_hi:[1,0]
	v_pk_mul_f32 v[76:77], v[118:119], v[76:77] op_sel_hi:[1,0]
	v_cvt_pk_bf16_f32 v204, v80, v81
	v_cvt_pk_bf16_f32 v205, v78, v79
	v_cvt_pk_bf16_f32 v206, v84, v85
	v_cvt_pk_bf16_f32 v207, v82, v83
	v_cvt_pk_bf16_f32 v196, v96, v97
	v_cvt_pk_bf16_f32 v197, v94, v95
	v_cvt_pk_bf16_f32 v198, v76, v77
	v_cvt_pk_bf16_f32 v199, v102, v103
	s_nop 1
	v_permlane16_swap_b32_e32 v204, v206
	v_permlane16_swap_b32_e32 v205, v207
	v_permlane16_swap_b32_e32 v196, v198
	v_permlane16_swap_b32_e32 v197, v199
	global_store_dwordx4 v[74:75], v[204:207], off
	global_store_dwordx4 v[74:75], v[196:199], off offset:256
	v_fmamk_f32 v74, v210, 0x3a000000, v239
	v_mul_f32_e32 v75, 0x4b800000, v74
	v_cmp_gt_f32_e32 vcc, s74, v74
	s_nop 1
	v_cndmask_b32_e32 v74, v74, v75, vcc
	v_rsq_f32_e32 v76, v74
	v_lshlrev_b64 v[74:75], 12, v[160:161]
	v_lshl_add_u64 v[74:75], v[156:157], 0, v[74:75]
	v_mul_f32_e32 v77, 0x45800000, v76
	v_cndmask_b32_e32 v76, v76, v77, vcc
	v_pk_mul_f32 v[78:79], v[124:125], v[76:77] op_sel_hi:[1,0]
	v_pk_mul_f32 v[80:81], v[122:123], v[76:77] op_sel_hi:[1,0]
	v_pk_mul_f32 v[82:83], v[146:147], v[76:77] op_sel_hi:[1,0]
	v_pk_mul_f32 v[84:85], v[144:145], v[76:77] op_sel_hi:[1,0]
	v_pk_mul_f32 v[94:95], v[116:117], v[76:77] op_sel_hi:[1,0]
	v_pk_mul_f32 v[96:97], v[114:115], v[76:77] op_sel_hi:[1,0]
	v_pk_mul_f32 v[100:101], v[100:101], v[76:77] op_sel_hi:[1,0]
	v_pk_mul_f32 v[76:77], v[98:99], v[76:77] op_sel_hi:[1,0]
	v_cvt_pk_bf16_f32 v200, v80, v81
	v_cvt_pk_bf16_f32 v201, v78, v79
	v_cvt_pk_bf16_f32 v202, v84, v85
	v_cvt_pk_bf16_f32 v203, v82, v83
	v_cvt_pk_bf16_f32 v204, v96, v97
	v_cvt_pk_bf16_f32 v205, v94, v95
	v_cvt_pk_bf16_f32 v206, v76, v77
	v_cvt_pk_bf16_f32 v207, v100, v101
	s_nop 1
	v_permlane16_swap_b32_e32 v200, v202
	v_permlane16_swap_b32_e32 v201, v203
	v_permlane16_swap_b32_e32 v204, v206
	v_permlane16_swap_b32_e32 v205, v207
	global_store_dwordx4 v[74:75], v[200:203], off
	global_store_dwordx4 v[74:75], v[204:207], off offset:256
	v_fmamk_f32 v74, v211, 0x3a000000, v239
	v_mul_f32_e32 v75, 0x4b800000, v74
	v_cmp_gt_f32_e32 vcc, s74, v74
	s_nop 1
	v_cndmask_b32_e32 v74, v74, v75, vcc
	v_rsq_f32_e32 v76, v74
	v_lshlrev_b64 v[74:75], 12, v[164:165]
	v_lshl_add_u64 v[74:75], v[156:157], 0, v[74:75]
	v_mul_f32_e32 v77, 0x45800000, v76
	v_cndmask_b32_e32 v76, v76, v77, vcc
	v_pk_mul_f32 v[78:79], v[92:93], v[76:77] op_sel_hi:[1,0]
	v_pk_mul_f32 v[80:81], v[90:91], v[76:77] op_sel_hi:[1,0]
	v_pk_mul_f32 v[82:83], v[88:89], v[76:77] op_sel_hi:[1,0]
	v_pk_mul_f32 v[84:85], v[86:87], v[76:77] op_sel_hi:[1,0]
	v_pk_mul_f32 v[72:73], v[72:73], v[76:77] op_sel_hi:[1,0]
	v_pk_mul_f32 v[70:71], v[70:71], v[76:77] op_sel_hi:[1,0]
	v_pk_mul_f32 v[68:69], v[68:69], v[76:77] op_sel_hi:[1,0]
; __device__ __forceinline__ unsigned cvt_pk_bf16(float lo, float hi) { const f32x2e_t v = {lo, hi}; return __builtin_bit_cast(unsigned, __builtin_convertvector(v, bf16x2e_t)); }
;     __device__ __forceinline__ void operator()(f32x4 (&acc)[2][2][4][2], const Unit& u, int wr, int wc, int fr, int fq) const {
;     ...
;         for (int ai = 0; ai < 2; ++ai)
; #pragma unroll
;             for (int m = 0; m < 4; ++m) { const int row = row0 + ai * HALF + m * 16; const size_t off = (size_t)row * 2048 + col0;
;                 const float r = rsqrtf(__hip_atomic_load(ssq + row, __ATOMIC_RELAXED, __HIP_MEMORY_SCOPE_AGENT) * (1.0f / 2048.0f) + 1e-6f);
; #pragma unroll
;                 for (int bj = 0; bj < 2; ++bj)
; #pragma unroll
;                     for (int n = 0; n < 2; ++n) { const f32x4 xo = acc[ai][bj][m][n] * r;
;                         if (FINAL) *(f32x4*)(X + off + bj * HALF + n * 16) = xo * gv[bj][n];
;                         else { unsigned long long w = (unsigned long long)cvt_pk_bf16(xo[0], xo[1]) | ((unsigned long long)cvt_pk_bf16(xo[2], xo[3]) << 32); *(unsigned long long*)(XB + off + bj * HALF + n * 16) = w; } } }
	v_pk_mul_f32 v[66:67], v[66:67], v[76:77] op_sel_hi:[1,0]
	v_cvt_pk_bf16_f32 v196, v80, v81
	v_cvt_pk_bf16_f32 v197, v78, v79
	v_cvt_pk_bf16_f32 v198, v84, v85
	v_cvt_pk_bf16_f32 v199, v82, v83
	v_cvt_pk_bf16_f32 v200, v70, v71
	v_cvt_pk_bf16_f32 v201, v72, v73
	v_cvt_pk_bf16_f32 v202, v66, v67
	v_cvt_pk_bf16_f32 v203, v68, v69
	s_nop 1
	v_permlane16_swap_b32_e32 v196, v198
	v_permlane16_swap_b32_e32 v197, v199
	v_permlane16_swap_b32_e32 v200, v202
	v_permlane16_swap_b32_e32 v201, v203
	global_store_dwordx4 v[74:75], v[196:199], off
	global_store_dwordx4 v[74:75], v[200:203], off offset:256
	v_fmamk_f32 v66, v212, 0x3a000000, v239
	v_mul_f32_e32 v67, 0x4b800000, v66
	v_cmp_gt_f32_e32 vcc, s74, v66
	s_nop 1
	v_cndmask_b32_e32 v66, v66, v67, vcc
	v_rsq_f32_e32 v68, v66
	v_lshlrev_b64 v[66:67], 12, v[168:169]
	v_lshl_add_u64 v[66:67], v[156:157], 0, v[66:67]
	v_mul_f32_e32 v69, 0x45800000, v68
	v_cndmask_b32_e32 v68, v68, v69, vcc
	v_pk_mul_f32 v[64:65], v[64:65], v[68:69] op_sel_hi:[1,0]
	v_pk_mul_f32 v[62:63], v[62:63], v[68:69] op_sel_hi:[1,0]
	v_pk_mul_f32 v[60:61], v[60:61], v[68:69] op_sel_hi:[1,0]
	v_pk_mul_f32 v[58:59], v[58:59], v[68:69] op_sel_hi:[1,0]
	v_pk_mul_f32 v[56:57], v[56:57], v[68:69] op_sel_hi:[1,0]
	v_pk_mul_f32 v[54:55], v[54:55], v[68:69] op_sel_hi:[1,0]
	v_pk_mul_f32 v[52:53], v[52:53], v[68:69] op_sel_hi:[1,0]
	v_pk_mul_f32 v[50:51], v[50:51], v[68:69] op_sel_hi:[1,0]
	v_cvt_pk_bf16_f32 v204, v62, v63
	v_cvt_pk_bf16_f32 v205, v64, v65
	v_cvt_pk_bf16_f32 v206, v58, v59
	v_cvt_pk_bf16_f32 v207, v60, v61
	v_cvt_pk_bf16_f32 v196, v54, v55
	v_cvt_pk_bf16_f32 v197, v56, v57
	v_cvt_pk_bf16_f32 v198, v50, v51
	v_cvt_pk_bf16_f32 v199, v52, v53
	s_nop 1
	v_permlane16_swap_b32_e32 v204, v206
	v_permlane16_swap_b32_e32 v205, v207
	v_permlane16_swap_b32_e32 v196, v198
	v_permlane16_swap_b32_e32 v197, v199
	global_store_dwordx4 v[66:67], v[204:207], off
	global_store_dwordx4 v[66:67], v[196:199], off offset:256
	v_fmamk_f32 v50, v213, 0x3a000000, v239
	v_mul_f32_e32 v51, 0x4b800000, v50
	v_cmp_gt_f32_e32 vcc, s74, v50
	s_nop 1
	v_cndmask_b32_e32 v50, v50, v51, vcc
	v_rsq_f32_e32 v52, v50
	v_lshlrev_b64 v[50:51], 12, v[172:173]
	v_lshl_add_u64 v[50:51], v[156:157], 0, v[50:51]
	v_mul_f32_e32 v53, 0x45800000, v52
	v_cndmask_b32_e32 v52, v52, v53, vcc
	v_pk_mul_f32 v[48:49], v[48:49], v[52:53] op_sel_hi:[1,0]
	v_pk_mul_f32 v[46:47], v[46:47], v[52:53] op_sel_hi:[1,0]
	v_pk_mul_f32 v[44:45], v[44:45], v[52:53] op_sel_hi:[1,0]
	v_pk_mul_f32 v[42:43], v[42:43], v[52:53] op_sel_hi:[1,0]
	v_pk_mul_f32 v[40:41], v[40:41], v[52:53] op_sel_hi:[1,0]
	v_pk_mul_f32 v[38:39], v[38:39], v[52:53] op_sel_hi:[1,0]
	v_pk_mul_f32 v[36:37], v[36:37], v[52:53] op_sel_hi:[1,0]
	v_pk_mul_f32 v[34:35], v[34:35], v[52:53] op_sel_hi:[1,0]
	v_cvt_pk_bf16_f32 v200, v46, v47
	v_cvt_pk_bf16_f32 v201, v48, v49
	v_cvt_pk_bf16_f32 v202, v42, v43
	v_cvt_pk_bf16_f32 v203, v44, v45
	v_cvt_pk_bf16_f32 v204, v38, v39
	v_cvt_pk_bf16_f32 v205, v40, v41
	v_cvt_pk_bf16_f32 v206, v34, v35
	v_cvt_pk_bf16_f32 v207, v36, v37
	s_nop 1
	v_permlane16_swap_b32_e32 v200, v202
	v_permlane16_swap_b32_e32 v201, v203
	v_permlane16_swap_b32_e32 v204, v206
	v_permlane16_swap_b32_e32 v205, v207
	global_store_dwordx4 v[50:51], v[200:203], off
	global_store_dwordx4 v[50:51], v[204:207], off offset:256
	v_fmamk_f32 v34, v214, 0x3a000000, v239
	v_mul_f32_e32 v35, 0x4b800000, v34
	v_cmp_gt_f32_e32 vcc, s74, v34
	s_nop 1
	v_cndmask_b32_e32 v34, v34, v35, vcc
	v_rsq_f32_e32 v36, v34
	v_lshlrev_b64 v[34:35], 12, v[174:175]
	v_lshl_add_u64 v[34:35], v[156:157], 0, v[34:35]
	v_mul_f32_e32 v37, 0x45800000, v36
	v_cndmask_b32_e32 v36, v36, v37, vcc
	v_pk_mul_f32 v[32:33], v[32:33], v[36:37] op_sel_hi:[1,0]
	v_pk_mul_f32 v[30:31], v[30:31], v[36:37] op_sel_hi:[1,0]
	v_pk_mul_f32 v[28:29], v[28:29], v[36:37] op_sel_hi:[1,0]
	v_pk_mul_f32 v[26:27], v[26:27], v[36:37] op_sel_hi:[1,0]
	v_pk_mul_f32 v[24:25], v[24:25], v[36:37] op_sel_hi:[1,0]
	v_pk_mul_f32 v[22:23], v[22:23], v[36:37] op_sel_hi:[1,0]
	v_pk_mul_f32 v[20:21], v[20:21], v[36:37] op_sel_hi:[1,0]
	v_pk_mul_f32 v[18:19], v[18:19], v[36:37] op_sel_hi:[1,0]
	v_cvt_pk_bf16_f32 v196, v30, v31
	v_cvt_pk_bf16_f32 v197, v32, v33
	v_cvt_pk_bf16_f32 v198, v26, v27
	v_cvt_pk_bf16_f32 v199, v28, v29
	v_cvt_pk_bf16_f32 v200, v22, v23
	v_cvt_pk_bf16_f32 v201, v24, v25
	v_cvt_pk_bf16_f32 v202, v18, v19
	v_cvt_pk_bf16_f32 v203, v20, v21
	s_nop 1
	v_permlane16_swap_b32_e32 v196, v198
	v_permlane16_swap_b32_e32 v197, v199
	v_permlane16_swap_b32_e32 v200, v202
	v_permlane16_swap_b32_e32 v201, v203
	global_store_dwordx4 v[34:35], v[196:199], off
	global_store_dwordx4 v[34:35], v[200:203], off offset:256
	v_lshlrev_b64 v[18:19], 12, v[176:177]
	v_lshl_add_u64 v[18:19], v[156:157], 0, v[18:19]
	s_andn2_b64 vcc, exec, s[6:7]
	v_fmamk_f32 v20, v215, 0x3a000000, v239
	v_mul_f32_e32 v21, 0x4b800000, v20
	v_cmp_gt_f32_e64 s[0:1], s74, v20
	s_nop 1
	v_cndmask_b32_e64 v20, v20, v21, s[0:1]
	v_rsq_f32_e32 v20, v20
	s_nop 0
	v_mul_f32_e32 v21, 0x45800000, v20
	v_cndmask_b32_e64 v20, v20, v21, s[0:1]
	v_pk_mul_f32 v[16:17], v[16:17], v[20:21] op_sel_hi:[1,0]
	v_pk_mul_f32 v[14:15], v[14:15], v[20:21] op_sel_hi:[1,0]
	v_pk_mul_f32 v[12:13], v[12:13], v[20:21] op_sel_hi:[1,0]
	v_pk_mul_f32 v[10:11], v[10:11], v[20:21] op_sel_hi:[1,0]
	v_pk_mul_f32 v[8:9], v[8:9], v[20:21] op_sel_hi:[1,0]
	v_pk_mul_f32 v[6:7], v[6:7], v[20:21] op_sel_hi:[1,0]
	v_pk_mul_f32 v[4:5], v[4:5], v[20:21] op_sel_hi:[1,0]
	v_pk_mul_f32 v[2:3], v[2:3], v[20:21] op_sel_hi:[1,0]
	v_cvt_pk_bf16_f32 v204, v14, v15
	v_cvt_pk_bf16_f32 v205, v16, v17
	s_mov_b64 s[0:1], -1
	v_cvt_pk_bf16_f32 v206, v10, v11
	v_cvt_pk_bf16_f32 v207, v12, v13
	v_cvt_pk_bf16_f32 v196, v6, v7
	v_cvt_pk_bf16_f32 v197, v8, v9
	v_cvt_pk_bf16_f32 v198, v2, v3
	v_cvt_pk_bf16_f32 v199, v4, v5
	s_nop 1
	v_permlane16_swap_b32_e32 v204, v206
	v_permlane16_swap_b32_e32 v205, v207
	v_permlane16_swap_b32_e32 v196, v198
	v_permlane16_swap_b32_e32 v197, v199
	global_store_dwordx4 v[18:19], v[204:207], off
	global_store_dwordx4 v[18:19], v[196:199], off offset:256
	s_cbranch_vccnz .LBB0_902
	s_andn2_b64 vcc, exec, s[8:9]
	s_cbranch_vccnz .LBB0_901
	s_barrier
	s_branch .LBB0_901
